# LDS-DMA tile loads with sc1 (bypass the CU vector L1) on top of v14
# speedup vs baseline: 1.0185x; 1.0185x over previous
; template <class Epi, class Sched, bool ALIGN_EPI = false, bool SP2 = false, bool ABLK = false>
; __device__ __forceinline__ void gemm_phase(PG8_LAS unsigned char* lds, const Gemm g, const Sched& S, const Epi& E) {
;     const int tid = threadIdx.x, wid = __builtin_amdgcn_readfirstlane(tid >> 6), lane = tid & 63, wr = wid >> 2, wc = wid & 3, fr = lane & 15, fq = lane >> 4;
;     const int K = g.K;
;     unsigned voffA[2], voffB[2];
; #pragma unroll
;     for (int i = 0; i < 2; ++i) { int R, C; stage_rc(tid * 16 + i * 8192, R, C); const int Rb = Epi::PERM ? ((R & ~31) + perm32(R & 31)) : R;
;         voffA[i] = (unsigned)(R * K + C) * 2u; (void)Rb;
;         if constexpr (ABLK) { const int st = (tid >> 6) + 8 * i; voffA[i] = (unsigned)(((st >> 1) * (K / 32) + (st & 1)) * 1024 + (tid & 63) * 16); }
;         { static_assert(Epi::PERM, "blocked weight copies are written in permuted row-slot order"); const int st = (tid >> 6) + 8 * i; voffB[i] = (unsigned)(((st >> 1) * (K / 32) + (st & 1)) * 1024 + (tid & 63) * 16); } }
;     const size_t kstep = ABLK ? (size_t)(BK / 32) * 1024 : (size_t)(BK * 2);
;     constexpr int KOA = ABLK ? 32 : 2;
;     const size_t pstep = (size_t)K * 128;
;     const size_t kstepB = (size_t)(BK / 32) * 1024;
;     const size_t hstep = (size_t)HALF * K * 2;
;     const size_t tstep = 2 * hstep;
;     const unsigned ldsw = (unsigned)wid * 1024u;
;     const int aoff = lds_byte(wr * 64 + fr, fq * 8), boff = lds_byte(wc * 32 + fr, fq * 8);
;     ...
;     Unit cur, nxt; int ui = 0;
;     if (!S.next(0, cur)) return;
;     f32x4 acc[2][2][4][2];
; #pragma unroll
;     for (int a = 0; a < 2; ++a)
; #pragma unroll
;         for (int b = 0; b < 2; ++b)
; #pragma unroll
;             for (int m = 0; m < 4; ++m)
; #pragma unroll
;                 for (int n = 0; n < 2; ++n) acc[a][b][m][n] = (f32x4){0.f, 0.f, 0.f, 0.f};
;     bf16x8 At[4][2], B0[2][2], B1[2][2];
;     const char* cA = (const char*)g.A + (size_t)cur.pm * tstep + (size_t)cur.ko * KOA; const char* cB = (const char*)g.Bt + (size_t)cur.pn * tstep + (size_t)cur.ko * 32; int nt = cur.nt;
;     S.a_ready(cur);
;     if constexpr (SP2) {
;         PG8_STAGE(PG8_SB(0, 0), cB, voffB); PG8_STAGE(PG8_SB(0, 1), cB + hstep, voffB); PG8_STAGE(PG8_SA(0, 0), cA, voffA); PG8_STAGE(PG8_SA(0, 1), cA + hstep, voffA);
;         if (wr == 1) PG8_BAR;
;         PG8_WAIT_V(2); PG8_BAR;
.LBB0_105:
	s_andn2_b64 vcc, exec, s[0:1]
	v_lshlrev_b32_e32 v1, 2, v0
	s_cbranch_vccnz .LBB0_149
	s_add_u32 s13, s86, 0x16e00000
	s_addc_u32 s25, s87, 0
	s_add_u32 s27, s86, 0x100000
	s_addc_u32 s33, s87, 0
	v_lshlrev_b32_e32 v2, 5, v7
	s_movk_i32 s0, 0xc1
	s_ashr_i32 s7, s6, 31
	s_ashr_i32 s23, s22, 31
	v_bitop3_b32 v2, v2, s0, v7 bitop3:0xc8
	s_ashr_i32 s3, s2, 2
	s_lshl_b32 s52, s2, 10
	s_lshl_b64 s[4:5], s[6:7], 20
	s_lshl_b64 s[0:1], s[22:23], 20
	v_lshlrev_b32_e32 v6, 4, v182
	s_add_u32 s16, s27, s0
	v_mov_b32_e32 v132, 0
	v_lshl_or_b32 v130, v2, 10, v6
	s_addc_u32 s17, s33, s1
	v_mov_b32_e32 v131, v132
	s_add_i32 s53, s52, 0
	v_lshl_add_u64 v[2:3], s[16:17], 0, v[130:131]
	s_add_i32 m0, s53, 0x10000
	s_mov_b64 s[0:1], 0x40000
	global_load_lds_dwordx4 v130, s[16:17]
	v_lshl_add_u64 v[4:5], v[2:3], 0, s[0:1]
	s_add_i32 m0, s53, 0x12000
	s_mov_b64 s[14:15], 0x80000
	global_load_lds_dwordx4 v[4:5], off sc1
	v_lshl_add_u64 v[4:5], v[2:3], 0, s[14:15]
	s_add_i32 m0, s53, 0x14000
	s_mov_b64 s[18:19], 0xc0000
	global_load_lds_dwordx4 v[4:5], off sc1
	s_add_i32 m0, s53, 0x16000
	s_add_u32 s70, s13, s4
	v_lshl_add_u64 v[4:5], v[2:3], 0, s[18:19]
	s_addc_u32 s71, s25, s5
	global_load_lds_dwordx4 v[4:5], off sc1
	v_lshl_add_u64 v[4:5], s[70:71], 0, v[130:131]
	s_mov_b32 m0, s53
	s_add_i32 s54, s53, 0x2000
	global_load_lds_dwordx4 v130, s[70:71]
	v_lshl_add_u64 v[8:9], v[4:5], 0, s[0:1]
	s_mov_b32 m0, s54
	s_add_i32 s55, s53, 0x4000
	global_load_lds_dwordx4 v[8:9], off sc1
	v_lshl_add_u64 v[8:9], v[4:5], 0, s[14:15]
	s_mov_b32 m0, s55
	s_add_i32 s56, s53, 0x6000
	global_load_lds_dwordx4 v[8:9], off sc1
	v_lshl_add_u64 v[8:9], v[4:5], 0, s[18:19]
	s_mov_b32 m0, s56
	v_writelane_b32 v251, s88, 44
	global_load_lds_dwordx4 v[8:9], off sc1
	s_cmp_eq_u32 s3, 1
	v_writelane_b32 v251, s89, 45
	s_cselect_b64 s[4:5], -1, 0
	s_mov_b32 s83, s96
	v_and_b32_e32 v7, 1, v7
	v_writelane_b32 v251, s4, 46
	s_cmp_lg_u32 s3, 1
	s_mov_b32 s23, 0
	v_writelane_b32 v251, s5, 47
	s_cbranch_scc1 .LBB0_108
	s_barrier
.LBB0_108:
	s_add_u32 s57, s86, 0x1b400000
	s_addc_u32 s58, s87, 0
	s_add_u32 s4, s86, 0x34000000
	v_and_b32_e32 v9, 15, v0
	s_addc_u32 s5, s87, 0
	v_lshl_or_b32 v148, s3, 6, v9
	v_writelane_b32 v251, s4, 48
	s_add_u32 s78, s86, 0x40000
	v_and_b32_e32 v8, 48, v0
	v_lshlrev_b32_e32 v12, 2, v148
	v_writelane_b32 v251, s5, 49
	s_addc_u32 s79, s87, 0
	v_lshl_or_b32 v10, v9, 6, v8
	s_lshl_b32 s4, s3, 13
	v_and_b32_e32 v11, 32, v12
	s_and_b32 s7, s2, 3
	v_bitop3_b32 v13, v10, s4, v11 bitop3:0xde
	v_lshlrev_b32_e32 v10, 6, v0
	s_movk_i32 s4, 0x3c0
	v_and_or_b32 v10, v10, s4, v8
	s_lshl_b32 s4, s7, 12
	v_and_b32_e32 v11, 32, v1
	s_mov_b64 s[28:29], 0x800
	v_bitop3_b32 v149, s4, v10, v11 bitop3:0xf6
	v_lshl_add_u64 v[10:11], v[2:3], 0, s[28:29]
	s_add_i32 m0, s53, 0x18000
	s_mov_b64 s[30:31], 0x40800
	s_waitcnt vmcnt(2)
	s_barrier
	global_load_lds_dwordx4 v[10:11], off sc1
	v_lshl_add_u64 v[10:11], v[2:3], 0, s[30:31]
	s_add_i32 m0, s53, 0x1a000
	s_add_i32 s59, s53, 0x8000
	global_load_lds_dwordx4 v[10:11], off sc1
	v_lshl_add_u64 v[10:11], v[4:5], 0, s[28:29]
	s_mov_b32 m0, s59
	s_add_i32 s60, s53, 0xa000
	global_load_lds_dwordx4 v[10:11], off sc1
	v_lshl_add_u64 v[4:5], v[4:5], 0, s[30:31]
	s_mov_b32 m0, s60
	s_mov_b64 s[34:35], 0x80800
	global_load_lds_dwordx4 v[4:5], off sc1
	v_lshl_add_u64 v[4:5], v[2:3], 0, s[34:35]
	s_add_i32 m0, s53, 0x1c000
	s_mov_b64 s[36:37], 0xc0800
	global_load_lds_dwordx4 v[4:5], off sc1
	v_lshl_add_u64 v[2:3], v[2:3], 0, s[36:37]
	s_add_i32 m0, s53, 0x1e000
	s_cmp_lt_u32 s2, 4
	global_load_lds_dwordx4 v[2:3], off sc1
	s_cselect_b64 s[38:39], -1, 0
	s_and_b32 s61, s2, -4
	s_lshl_b32 s2, s2, 6
	v_or3_b32 v150, s2, v8, v9
	s_movk_i32 s2, 0x100
	v_cmp_gt_i32_e64 s[4:5], s2, v150
	s_lshl_b32 s2, s3, 8
	s_add_i32 s10, 0, 0x22800
	s_add_i32 s2, s10, s2
	s_lshl_b32 s80, s7, 1
	s_ashr_i32 s62, s97, 31
	s_ashr_i32 s63, s82, 31
	v_lshl_add_u32 v159, v9, 2, s2
	s_lshl_b32 s2, s7, 6
	s_add_u32 s2, s86, s2
	s_addc_u32 s3, s87, 0
	v_mov_b32_e32 v9, v132
	v_lshlrev_b32_e32 v2, 3, v0
	v_lshl_add_u64 v[4:5], s[2:3], 0, v[8:9]
	s_mov_b64 s[2:3], 0x23800000
	v_and_b32_e32 v2, 0x1f8, v2
	v_lshlrev_b32_e32 v19, 5, v150
	v_lshl_add_u64 v[134:135], v[4:5], 0, s[2:3]
	s_lshl_b32 s2, s7, 3
	s_waitcnt vmcnt(6)
	v_cmp_eq_u32_e64 s[8:9], 0, v150
	v_or_b32_e32 v151, 16, v148
	v_or_b32_e32 v152, 32, v148
	v_or_b32_e32 v153, 48, v148
	v_add_u32_e32 v154, 0x80, v148
	v_add_u32_e32 v155, 0x90, v148
	v_add_u32_e32 v156, 0xa0, v148
	v_add_u32_e32 v157, 0xb0, v148
	s_add_i32 s2, s2, 0
	v_lshlrev_b32_e32 v4, 9, v0
	v_lshlrev_b32_e32 v142, 1, v2
	v_add_u32_e32 v2, 0, v19
	v_writelane_b32 v251, s8, 50
	v_lshlrev_b32_e32 v3, 5, v148
	v_lshlrev_b32_e32 v10, 5, v151
	v_lshlrev_b32_e32 v11, 5, v152
	v_lshlrev_b32_e32 v14, 5, v153
	v_lshlrev_b32_e32 v15, 5, v154
	v_lshlrev_b32_e32 v16, 5, v155
	v_lshlrev_b32_e32 v17, 5, v156
	v_lshlrev_b32_e32 v18, 5, v157
	s_add_i32 s2, s2, 0x20800
	v_and_b32_e32 v4, 0x30000, v4
	v_lshlrev_b32_e32 v5, 10, v7
	s_add_i32 s64, 0, 0x10000
	s_add_i32 s65, 0, 0x14000
	v_add_u32_e32 v180, 0x20800, v2
	v_mbcnt_lo_u32_b32 v2, -1, 0
	v_writelane_b32 v251, s9, 51
	s_mov_b32 s81, s23
	v_cmp_gt_u32_e64 s[8:9], 16, v182
	v_lshl_add_u32 v158, v150, 2, s10
	v_add_u32_e32 v160, s10, v12
	v_lshl_add_u32 v161, v151, 2, s10
	v_lshl_add_u32 v162, v152, 2, s10
	v_lshl_add_u32 v163, v153, 2, s10
	v_lshl_add_u32 v164, v154, 2, s10
	v_lshl_add_u32 v165, v155, 2, s10
	v_lshl_add_u32 v166, v156, 2, s10
	v_lshl_add_u32 v167, v157, 2, s10
	v_or3_b32 v136, v4, v5, v6
	v_mov_b32_e32 v137, v132
	v_mov_b64_e32 v[138:139], 0xc60
	v_mov_b64_e32 v[140:141], 0xc5f
	v_add_u32_e32 v168, s64, v149
	v_add_u32_e32 v169, s65, v149
	v_add_u32_e32 v170, 0, v13
	s_add_i32 s66, 0, 0x22c00
	v_mov_b32_e32 v171, 0x358637bd
	s_mov_b32 s90, 0x3e6d3388
	s_mov_b32 s92, 0x3f07dc22
	s_mov_b32 s94, 0xbf3a00e3
	s_mov_b32 s96, 0x3f35f0e3
	s_mov_b32 s12, 0xbe11a98e
	s_mov_b32 s24, 0x3e027906
	s_mov_b32 s26, 0xbf38aa3b
	v_add_u32_e32 v172, s2, v3
	v_add_u32_e32 v173, s2, v10
	v_add_u32_e32 v174, s2, v11
	v_add_u32_e32 v175, s2, v14
	v_add_u32_e32 v176, s2, v15
	v_add_u32_e32 v177, s2, v16
	v_add_u32_e32 v178, s2, v17
	v_add_u32_e32 v179, s2, v18
	v_mbcnt_hi_u32_b32 v181, -1, v2
	s_mov_b32 s67, 0
	s_barrier
	s_branch .LBB0_111

; #define PG8_STAGE(bufoff, gbase, voff) do { if constexpr (!pg8_noload<Epi>::value) { _Pragma("unroll") for (int _i = 0; _i < 2; ++_i) \
;         __builtin_amdgcn_global_load_lds((const unsigned*)((const char*)(gbase) + (size_t)_i * pstep + (voff)[0]), (PG8_LAS unsigned*)(lds + (bufoff) + ldsw + _i * 8192), 16, 0, 0); } } while (0)
; #define PG8_LDA(dst, b, h) do { _Pragma("unroll") for (int m = 0; m < 4; ++m) _Pragma("unroll") for (int k = 0; k < 2; ++k) dst[m][k] = *(const PG8_LAS bf16x8*)(lds + PG8_SA(b, h) + aoff + m * 2048 + k * 1024); } while (0)
; #define PG8_LDB(dst, b, h) do { _Pragma("unroll") for (int n = 0; n < 2; ++n) _Pragma("unroll") for (int k = 0; k < 2; ++k) dst[n][k] = *(const PG8_LAS bf16x8*)(lds + PG8_SB(b, h) + boff + n * 2048 + k * 1024); } while (0)
; #define PG8_MMA(ai, bj, At, Bt) do { __builtin_amdgcn_s_setprio(1); _Pragma("unroll") for (int m = 0; m < 4; ++m) _Pragma("unroll") for (int n = 0; n < 2; ++n) _Pragma("unroll") for (int k = 0; k < 2; ++k) \
;         acc[ai][bj][m][n] = __builtin_amdgcn_mfma_f32_16x16x32_bf16(Bt[n][k], At[m][k], acc[ai][bj][m][n], 0, 0, 0); __builtin_amdgcn_s_setprio(0); } while (0)
; #define PG8_BAR __builtin_amdgcn_s_barrier()
; template <class Epi, class Sched, bool ALIGN_EPI = false, bool SP2 = false, bool ABLK = false>
; __device__ __forceinline__ void gemm_phase(PG8_LAS unsigned char* lds, const Gemm g, const Sched& S, const Epi& E) {
;     ...
;         for (int t = 0; t < nt; t += 2) {
;             const bool last = (t == nt - 2);
;             const char* a1 = cA + (size_t)(t + 1) * kstep;
;             const char* a2 = last ? nA : cA + (size_t)(t + 2) * kstep; const char* b2 = last ? nB : cB + (size_t)(t + 2) * kstepB;
;             const char* a3 = a2 + kstep; const char* b3 = b2 + kstepB;
;             if (last && has_next) S.a_ready(nxt);
;             if constexpr (SP2) {
;             PG8_LDB(B0, 0, 0); PG8_LDB(B1, 0, 1); PG8_SCHED; PG8_LDA(At, 0, 0); PG8_STAGE(PG8_SA(1, 1), a1 + hstep, voffA);
;             PG8_WAIT_V(8); PG8_WAIT_L(0); PG8_BAR; PG8_MMA(0, 0, At, B0); PG8_MMA(0, 1, At, B1); PG8_BAR; PG8_SCHED;
;             PG8_LDA(At, 0, 1); PG8_STAGE(PG8_SB(0, 0), b2, voffB); PG8_STAGE(PG8_SB(0, 1), b2 + hstep, voffB); PG8_STAGE(PG8_SA(0, 0), a2, voffA);
;             PG8_WAIT_V(8); PG8_WAIT_L(0); PG8_BAR; PG8_MMA(1, 0, At, B0); PG8_MMA(1, 1, At, B1); PG8_BAR; PG8_SCHED;
.LBB0_114:
	ds_read_b128 v[144:147], v168
	ds_read_b128 v[184:187], v168 offset:1024
	ds_read_b128 v[188:191], v168 offset:2048
	ds_read_b128 v[192:195], v168 offset:3072
	ds_read_b128 v[196:199], v169
	ds_read_b128 v[200:203], v169 offset:1024
	ds_read_b128 v[204:207], v169 offset:2048
	ds_read_b128 v[208:211], v169 offset:3072
	s_add_u32 s71, vcc_lo, 0xfff80800
	s_addc_u32 s73, vcc_hi, -1
	s_cmp_eq_u32 s70, 28
	s_cselect_b32 s75, s3, s73
	s_cselect_b32 s74, s7, s71
	s_cselect_b32 s77, s21, s17
	s_cselect_b32 s76, s72, s16
	v_lshl_add_u64 v[244:245], vcc, 0, v[136:137]
	s_add_i32 m0, s53, 0xc000
	ds_read_b128 v[212:215], v170
	ds_read_b128 v[216:219], v170 offset:1024
	ds_read_b128 v[220:223], v170 offset:2048
	ds_read_b128 v[224:227], v170 offset:3072
	ds_read_b128 v[228:231], v170 offset:4096
	ds_read_b128 v[232:235], v170 offset:5120
	ds_read_b128 v[236:239], v170 offset:6144
	ds_read_b128 v[240:243], v170 offset:7168
	global_load_lds_dwordx4 v[244:245], off sc1
	v_lshl_add_u64 v[244:245], v[244:245], 0, s[0:1]
	s_add_i32 m0, s53, 0xe000
	s_nop 0
	global_load_lds_dwordx4 v[244:245], off sc1
	s_waitcnt vmcnt(8)
	s_waitcnt lgkmcnt(0)
	s_barrier
	s_setprio 1
	s_waitcnt lgkmcnt(0)
	v_mfma_f32_16x16x32_bf16 v[126:129], v[144:147], v[212:215], v[126:129]
	v_mfma_f32_16x16x32_bf16 v[126:129], v[184:187], v[216:219], v[126:129]
	v_mfma_f32_16x16x32_bf16 v[110:113], v[184:187], v[224:227], v[110:113]
	v_mfma_f32_16x16x32_bf16 v[110:113], v[144:147], v[220:223], v[110:113]
	v_mfma_f32_16x16x32_bf16 v[94:97], v[144:147], v[228:231], v[94:97]
	v_mfma_f32_16x16x32_bf16 v[94:97], v[184:187], v[232:235], v[94:97]
	v_mfma_f32_16x16x32_bf16 v[78:81], v[184:187], v[240:243], v[78:81]
	v_mfma_f32_16x16x32_bf16 v[78:81], v[144:147], v[236:239], v[78:81]
	v_mfma_f32_16x16x32_bf16 v[74:77], v[188:191], v[236:239], v[74:77]
	v_mfma_f32_16x16x32_bf16 v[74:77], v[192:195], v[240:243], v[74:77]
	v_mfma_f32_16x16x32_bf16 v[90:93], v[192:195], v[232:235], v[90:93]
	v_mfma_f32_16x16x32_bf16 v[90:93], v[188:191], v[228:231], v[90:93]
	v_mfma_f32_16x16x32_bf16 v[106:109], v[188:191], v[220:223], v[106:109]
	v_mfma_f32_16x16x32_bf16 v[106:109], v[192:195], v[224:227], v[106:109]
	v_mfma_f32_16x16x32_bf16 v[122:125], v[192:195], v[216:219], v[122:125]
	v_mfma_f32_16x16x32_bf16 v[122:125], v[188:191], v[212:215], v[122:125]
	v_mfma_f32_16x16x32_bf16 v[118:121], v[196:199], v[212:215], v[118:121]
	v_mfma_f32_16x16x32_bf16 v[118:121], v[200:203], v[216:219], v[118:121]
	v_mfma_f32_16x16x32_bf16 v[102:105], v[200:203], v[224:227], v[102:105]
	v_mfma_f32_16x16x32_bf16 v[102:105], v[196:199], v[220:223], v[102:105]
	v_mfma_f32_16x16x32_bf16 v[86:89], v[196:199], v[228:231], v[86:89]
	v_mfma_f32_16x16x32_bf16 v[86:89], v[200:203], v[232:235], v[86:89]
	v_mfma_f32_16x16x32_bf16 v[70:73], v[200:203], v[240:243], v[70:73]
	v_mfma_f32_16x16x32_bf16 v[70:73], v[196:199], v[236:239], v[70:73]
	v_mfma_f32_16x16x32_bf16 v[66:69], v[204:207], v[236:239], v[66:69]
	v_mfma_f32_16x16x32_bf16 v[66:69], v[208:211], v[240:243], v[66:69]
	v_mfma_f32_16x16x32_bf16 v[82:85], v[208:211], v[232:235], v[82:85]
	v_mfma_f32_16x16x32_bf16 v[82:85], v[204:207], v[228:231], v[82:85]
	s_barrier
	s_setprio 2
	v_mfma_f32_16x16x32_bf16 v[98:101], v[204:207], v[220:223], v[98:101]
	v_mfma_f32_16x16x32_bf16 v[98:101], v[208:211], v[224:227], v[98:101]
	v_mfma_f32_16x16x32_bf16 v[114:117], v[208:211], v[216:219], v[114:117]
	v_mfma_f32_16x16x32_bf16 v[114:117], v[204:207], v[212:215], v[114:117]
	s_setprio 0
	s_add_i32 s71, s64, s52
	v_lshl_add_u64 v[244:245], s[76:77], 0, v[130:131]
	s_mov_b32 m0, s71
	ds_read_b128 v[212:215], v170 offset:16384
	ds_read_b128 v[216:219], v170 offset:17408
	ds_read_b128 v[220:223], v170 offset:18432
	ds_read_b128 v[224:227], v170 offset:19456
	ds_read_b128 v[228:231], v170 offset:20480
	ds_read_b128 v[232:235], v170 offset:21504
	ds_read_b128 v[236:239], v170 offset:22528
	ds_read_b128 v[240:243], v170 offset:23552
	global_load_lds_dwordx4 v[244:245], off sc1
	v_lshl_add_u64 v[246:247], v[244:245], 0, s[0:1]
	s_add_i32 m0, s71, 0x2000
	s_add_i32 s71, s65, s52
	global_load_lds_dwordx4 v[246:247], off sc1
	v_lshl_add_u64 v[246:247], v[244:245], 0, s[14:15]
	s_mov_b32 m0, s71
	s_nop 0
	global_load_lds_dwordx4 v[246:247], off sc1
	v_lshl_add_u64 v[246:247], v[244:245], 0, s[18:19]
	s_add_i32 m0, s71, 0x2000
	s_nop 0
	global_load_lds_dwordx4 v[246:247], off sc1
	v_lshl_add_u64 v[246:247], s[74:75], 0, v[130:131]
	s_mov_b32 m0, s53
	v_lshl_add_u64 v[248:249], v[246:247], 0, s[0:1]
	global_load_lds_dwordx4 v[246:247], off sc1
	s_mov_b32 m0, s54
	s_nop 0
	global_load_lds_dwordx4 v[248:249], off sc1
	s_waitcnt vmcnt(8)
	s_waitcnt lgkmcnt(0)
	s_barrier
; #define PG8_STAGE(bufoff, gbase, voff) do { if constexpr (!pg8_noload<Epi>::value) { _Pragma("unroll") for (int _i = 0; _i < 2; ++_i) \
;         __builtin_amdgcn_global_load_lds((const unsigned*)((const char*)(gbase) + (size_t)_i * pstep + (voff)[0]), (PG8_LAS unsigned*)(lds + (bufoff) + ldsw + _i * 8192), 16, 0, 0); } } while (0)
; #define PG8_LDA(dst, b, h) do { _Pragma("unroll") for (int m = 0; m < 4; ++m) _Pragma("unroll") for (int k = 0; k < 2; ++k) dst[m][k] = *(const PG8_LAS bf16x8*)(lds + PG8_SA(b, h) + aoff + m * 2048 + k * 1024); } while (0)
; #define PG8_LDB(dst, b, h) do { _Pragma("unroll") for (int n = 0; n < 2; ++n) _Pragma("unroll") for (int k = 0; k < 2; ++k) dst[n][k] = *(const PG8_LAS bf16x8*)(lds + PG8_SB(b, h) + boff + n * 2048 + k * 1024); } while (0)
; #define PG8_MMA(ai, bj, At, Bt) do { __builtin_amdgcn_s_setprio(1); _Pragma("unroll") for (int m = 0; m < 4; ++m) _Pragma("unroll") for (int n = 0; n < 2; ++n) _Pragma("unroll") for (int k = 0; k < 2; ++k) \
;         acc[ai][bj][m][n] = __builtin_amdgcn_mfma_f32_16x16x32_bf16(Bt[n][k], At[m][k], acc[ai][bj][m][n], 0, 0, 0); __builtin_amdgcn_s_setprio(0); } while (0)
; #define PG8_WAIT_V(n) asm volatile("s_waitcnt vmcnt(" #n ")" ::: "memory")
; #define PG8_WAIT_L(n) asm volatile("s_waitcnt lgkmcnt(" #n ")" ::: "memory")
; #define PG8_BAR __builtin_amdgcn_s_barrier()
; #define PG8_SCHED __builtin_amdgcn_sched_barrier(0)
; template <class Epi, class Sched, bool ALIGN_EPI = false, bool SP2 = false, bool ABLK = false>
; __device__ __forceinline__ void gemm_phase(PG8_LAS unsigned char* lds, const Gemm g, const Sched& S, const Epi& E) {
;     ...
;             PG8_WAIT_V(8); PG8_WAIT_L(0); PG8_BAR; PG8_MMA(0, 0, At, B0); PG8_MMA(0, 1, At, B1); PG8_BAR; PG8_SCHED;
;             PG8_LDA(At, 0, 1); PG8_STAGE(PG8_SB(0, 0), b2, voffB); PG8_STAGE(PG8_SB(0, 1), b2 + hstep, voffB); PG8_STAGE(PG8_SA(0, 0), a2, voffA);
;             PG8_WAIT_V(8); PG8_WAIT_L(0); PG8_BAR; PG8_MMA(1, 0, At, B0); PG8_MMA(1, 1, At, B1); PG8_BAR; PG8_SCHED;
;             PG8_LDB(B0, 1, 0); PG8_LDB(B1, 1, 1); PG8_SCHED; PG8_LDA(At, 1, 0); PG8_STAGE(PG8_SA(0, 1), a2 + hstep, voffA);
;             PG8_WAIT_V(8); PG8_WAIT_L(0); PG8_BAR; PG8_MMA(0, 0, At, B0); PG8_MMA(0, 1, At, B1); PG8_BAR; PG8_SCHED;
	s_setprio 1
	s_waitcnt lgkmcnt(0)
	v_mfma_f32_16x16x32_bf16 v[62:65], v[144:147], v[212:215], v[62:65]
	v_mfma_f32_16x16x32_bf16 v[62:65], v[184:187], v[216:219], v[62:65]
	v_mfma_f32_16x16x32_bf16 v[46:49], v[184:187], v[224:227], v[46:49]
	v_mfma_f32_16x16x32_bf16 v[46:49], v[144:147], v[220:223], v[46:49]
	v_mfma_f32_16x16x32_bf16 v[30:33], v[144:147], v[228:231], v[30:33]
	v_mfma_f32_16x16x32_bf16 v[30:33], v[184:187], v[232:235], v[30:33]
	v_mfma_f32_16x16x32_bf16 v[14:17], v[184:187], v[240:243], v[14:17]
	v_mfma_f32_16x16x32_bf16 v[14:17], v[144:147], v[236:239], v[14:17]
	v_mfma_f32_16x16x32_bf16 v[10:13], v[188:191], v[236:239], v[10:13]
	v_mfma_f32_16x16x32_bf16 v[10:13], v[192:195], v[240:243], v[10:13]
	v_mfma_f32_16x16x32_bf16 v[26:29], v[192:195], v[232:235], v[26:29]
	v_mfma_f32_16x16x32_bf16 v[26:29], v[188:191], v[228:231], v[26:29]
	v_mfma_f32_16x16x32_bf16 v[42:45], v[188:191], v[220:223], v[42:45]
	v_mfma_f32_16x16x32_bf16 v[42:45], v[192:195], v[224:227], v[42:45]
	v_mfma_f32_16x16x32_bf16 v[58:61], v[192:195], v[216:219], v[58:61]
	v_mfma_f32_16x16x32_bf16 v[58:61], v[188:191], v[212:215], v[58:61]
	v_mfma_f32_16x16x32_bf16 v[54:57], v[196:199], v[212:215], v[54:57]
	v_mfma_f32_16x16x32_bf16 v[54:57], v[200:203], v[216:219], v[54:57]
	v_mfma_f32_16x16x32_bf16 v[38:41], v[200:203], v[224:227], v[38:41]
	v_mfma_f32_16x16x32_bf16 v[38:41], v[196:199], v[220:223], v[38:41]
	v_mfma_f32_16x16x32_bf16 v[22:25], v[196:199], v[228:231], v[22:25]
	v_mfma_f32_16x16x32_bf16 v[22:25], v[200:203], v[232:235], v[22:25]
	v_mfma_f32_16x16x32_bf16 v[6:9], v[200:203], v[240:243], v[6:9]
	v_mfma_f32_16x16x32_bf16 v[6:9], v[196:199], v[236:239], v[6:9]
	v_mfma_f32_16x16x32_bf16 v[2:5], v[204:207], v[236:239], v[2:5]
	v_mfma_f32_16x16x32_bf16 v[2:5], v[208:211], v[240:243], v[2:5]
	v_mfma_f32_16x16x32_bf16 v[18:21], v[208:211], v[232:235], v[18:21]
	v_mfma_f32_16x16x32_bf16 v[18:21], v[204:207], v[228:231], v[18:21]
	s_barrier
	s_setprio 2
	v_mfma_f32_16x16x32_bf16 v[34:37], v[204:207], v[220:223], v[34:37]
	v_mfma_f32_16x16x32_bf16 v[34:37], v[208:211], v[224:227], v[34:37]
	v_mfma_f32_16x16x32_bf16 v[50:53], v[208:211], v[216:219], v[50:53]
	v_mfma_f32_16x16x32_bf16 v[50:53], v[204:207], v[212:215], v[50:53]
	s_setprio 0
	s_add_i32 s71, 0, 0x18000
	v_add_u32_e32 v133, s71, v149
	s_add_i32 s73, 0, 0x1c000
	ds_read_b128 v[144:147], v133
	ds_read_b128 v[184:187], v133 offset:1024
	ds_read_b128 v[188:191], v133 offset:2048
	ds_read_b128 v[192:195], v133 offset:3072
	v_add_u32_e32 v133, s73, v149
	ds_read_b128 v[196:199], v133
	ds_read_b128 v[200:203], v133 offset:1024
	ds_read_b128 v[204:207], v133 offset:2048
	ds_read_b128 v[208:211], v133 offset:3072
	s_mov_b32 m0, s55
	v_lshl_add_u64 v[248:249], v[246:247], 0, s[14:15]
	ds_read_b128 v[212:215], v170 offset:32768
	ds_read_b128 v[216:219], v170 offset:33792
	ds_read_b128 v[220:223], v170 offset:34816
	ds_read_b128 v[224:227], v170 offset:35840
	ds_read_b128 v[228:231], v170 offset:36864
	ds_read_b128 v[232:235], v170 offset:37888
	ds_read_b128 v[236:239], v170 offset:38912
	ds_read_b128 v[240:243], v170 offset:39936
	global_load_lds_dwordx4 v[248:249], off sc1
	v_lshl_add_u64 v[248:249], v[246:247], 0, s[18:19]
	s_mov_b32 m0, s56
	s_nop 0
	global_load_lds_dwordx4 v[248:249], off sc1
	s_waitcnt vmcnt(8)
	s_waitcnt lgkmcnt(0)
	s_barrier
	s_setprio 1
	s_waitcnt lgkmcnt(0)
	v_mfma_f32_16x16x32_bf16 v[126:129], v[144:147], v[212:215], v[126:129]
	v_mfma_f32_16x16x32_bf16 v[126:129], v[184:187], v[216:219], v[126:129]
	v_mfma_f32_16x16x32_bf16 v[110:113], v[184:187], v[224:227], v[110:113]
	v_mfma_f32_16x16x32_bf16 v[110:113], v[144:147], v[220:223], v[110:113]
	v_mfma_f32_16x16x32_bf16 v[94:97], v[144:147], v[228:231], v[94:97]
	v_mfma_f32_16x16x32_bf16 v[94:97], v[184:187], v[232:235], v[94:97]
	v_mfma_f32_16x16x32_bf16 v[78:81], v[184:187], v[240:243], v[78:81]
	v_mfma_f32_16x16x32_bf16 v[78:81], v[144:147], v[236:239], v[78:81]
	v_mfma_f32_16x16x32_bf16 v[74:77], v[188:191], v[236:239], v[74:77]
	v_mfma_f32_16x16x32_bf16 v[74:77], v[192:195], v[240:243], v[74:77]
	v_mfma_f32_16x16x32_bf16 v[90:93], v[192:195], v[232:235], v[90:93]
	v_mfma_f32_16x16x32_bf16 v[90:93], v[188:191], v[228:231], v[90:93]
	v_mfma_f32_16x16x32_bf16 v[106:109], v[188:191], v[220:223], v[106:109]
	v_mfma_f32_16x16x32_bf16 v[106:109], v[192:195], v[224:227], v[106:109]
	v_mfma_f32_16x16x32_bf16 v[122:125], v[192:195], v[216:219], v[122:125]
	v_mfma_f32_16x16x32_bf16 v[122:125], v[188:191], v[212:215], v[122:125]
	v_mfma_f32_16x16x32_bf16 v[118:121], v[196:199], v[212:215], v[118:121]
	v_mfma_f32_16x16x32_bf16 v[118:121], v[200:203], v[216:219], v[118:121]
	v_mfma_f32_16x16x32_bf16 v[102:105], v[200:203], v[224:227], v[102:105]
	v_mfma_f32_16x16x32_bf16 v[102:105], v[196:199], v[220:223], v[102:105]
	v_mfma_f32_16x16x32_bf16 v[86:89], v[196:199], v[228:231], v[86:89]
	v_mfma_f32_16x16x32_bf16 v[86:89], v[200:203], v[232:235], v[86:89]
	v_mfma_f32_16x16x32_bf16 v[70:73], v[200:203], v[240:243], v[70:73]
	v_mfma_f32_16x16x32_bf16 v[70:73], v[196:199], v[236:239], v[70:73]
	v_mfma_f32_16x16x32_bf16 v[66:69], v[204:207], v[236:239], v[66:69]
	v_mfma_f32_16x16x32_bf16 v[66:69], v[208:211], v[240:243], v[66:69]
	v_mfma_f32_16x16x32_bf16 v[82:85], v[208:211], v[232:235], v[82:85]
	v_mfma_f32_16x16x32_bf16 v[82:85], v[204:207], v[228:231], v[82:85]
	s_barrier
; #define PG8_STAGE(bufoff, gbase, voff) do { if constexpr (!pg8_noload<Epi>::value) { _Pragma("unroll") for (int _i = 0; _i < 2; ++_i) \
;         __builtin_amdgcn_global_load_lds((const unsigned*)((const char*)(gbase) + (size_t)_i * pstep + (voff)[0]), (PG8_LAS unsigned*)(lds + (bufoff) + ldsw + _i * 8192), 16, 0, 0); } } while (0)
; #define PG8_LDA(dst, b, h) do { _Pragma("unroll") for (int m = 0; m < 4; ++m) _Pragma("unroll") for (int k = 0; k < 2; ++k) dst[m][k] = *(const PG8_LAS bf16x8*)(lds + PG8_SA(b, h) + aoff + m * 2048 + k * 1024); } while (0)
; #define PG8_LDB(dst, b, h) do { _Pragma("unroll") for (int n = 0; n < 2; ++n) _Pragma("unroll") for (int k = 0; k < 2; ++k) dst[n][k] = *(const PG8_LAS bf16x8*)(lds + PG8_SB(b, h) + boff + n * 2048 + k * 1024); } while (0)
; #define PG8_WAIT_V(n) asm volatile("s_waitcnt vmcnt(" #n ")" ::: "memory")
; #define PG8_WAIT_L(n) asm volatile("s_waitcnt lgkmcnt(" #n ")" ::: "memory")
; #define PG8_BAR __builtin_amdgcn_s_barrier()
; #define PG8_SCHED __builtin_amdgcn_sched_barrier(0)
; template <class Epi, class Sched, bool ALIGN_EPI = false, bool SP2 = false, bool ABLK = false>
; __device__ __forceinline__ void gemm_phase(PG8_LAS unsigned char* lds, const Gemm g, const Sched& S, const Epi& E) {
;     ...
;         for (int t = 0; t < nt; t += 2) {
;             const bool last = (t == nt - 2);
;             const char* a1 = cA + (size_t)(t + 1) * kstep;
;             const char* a2 = last ? nA : cA + (size_t)(t + 2) * kstep; const char* b2 = last ? nB : cB + (size_t)(t + 2) * kstepB;
;             const char* a3 = a2 + kstep; const char* b3 = b2 + kstepB;
;             if (last && has_next) S.a_ready(nxt);
;     ...
;             PG8_WAIT_V(8); PG8_WAIT_L(0); PG8_BAR; PG8_MMA(1, 0, At, B0); PG8_MMA(1, 1, At, B1); PG8_BAR; PG8_SCHED;
;             PG8_LDB(B0, 1, 0); PG8_LDB(B1, 1, 1); PG8_SCHED; PG8_LDA(At, 1, 0); PG8_STAGE(PG8_SA(0, 1), a2 + hstep, voffA);
;             PG8_WAIT_V(8); PG8_WAIT_L(0); PG8_BAR; PG8_MMA(0, 0, At, B0); PG8_MMA(0, 1, At, B1); PG8_BAR; PG8_SCHED;
;             PG8_LDA(At, 1, 1); PG8_STAGE(PG8_SB(1, 0), b3, voffB); PG8_STAGE(PG8_SB(1, 1), b3 + hstep, voffB); PG8_STAGE(PG8_SA(1, 0), a3, voffA);
;             PG8_WAIT_V(8); PG8_WAIT_L(0); PG8_BAR; PG8_MMA(1, 0, At, B0); PG8_MMA(1, 1, At, B1); PG8_BAR; PG8_SCHED;
	s_setprio 2
	v_mfma_f32_16x16x32_bf16 v[98:101], v[204:207], v[220:223], v[98:101]
	v_mfma_f32_16x16x32_bf16 v[98:101], v[208:211], v[224:227], v[98:101]
	v_mfma_f32_16x16x32_bf16 v[114:117], v[208:211], v[216:219], v[114:117]
	v_mfma_f32_16x16x32_bf16 v[114:117], v[204:207], v[212:215], v[114:117]
	s_setprio 0
	s_add_i32 s71, s71, s52
	v_lshl_add_u64 v[248:249], v[244:245], 0, s[28:29]
	s_mov_b32 m0, s71
	ds_read_b128 v[212:215], v170 offset:49152
	ds_read_b128 v[216:219], v170 offset:50176
	ds_read_b128 v[220:223], v170 offset:51200
	ds_read_b128 v[224:227], v170 offset:52224
	ds_read_b128 v[228:231], v170 offset:53248
	ds_read_b128 v[232:235], v170 offset:54272
	ds_read_b128 v[236:239], v170 offset:55296
	ds_read_b128 v[240:243], v170 offset:56320
	global_load_lds_dwordx4 v[248:249], off sc1
	v_lshl_add_u64 v[248:249], v[244:245], 0, s[30:31]
	s_add_i32 m0, s71, 0x2000
	s_add_i32 s71, s73, s52
	global_load_lds_dwordx4 v[248:249], off sc1
	v_lshl_add_u64 v[248:249], v[244:245], 0, s[34:35]
	s_mov_b32 m0, s71
	v_lshl_add_u64 v[244:245], v[244:245], 0, s[36:37]
	global_load_lds_dwordx4 v[248:249], off sc1
	s_add_i32 m0, s71, 0x2000
	s_nop 0
	global_load_lds_dwordx4 v[244:245], off sc1
	v_lshl_add_u64 v[244:245], v[246:247], 0, s[28:29]
	s_mov_b32 m0, s59
	s_nop 0
	global_load_lds_dwordx4 v[244:245], off sc1
	v_lshl_add_u64 v[244:245], v[246:247], 0, s[30:31]
	s_mov_b32 m0, s60
	s_nop 0
	global_load_lds_dwordx4 v[244:245], off sc1
	s_waitcnt vmcnt(8)
	s_waitcnt lgkmcnt(0)
	s_barrier
	s_setprio 1
	s_waitcnt lgkmcnt(0)
	v_mfma_f32_16x16x32_bf16 v[62:65], v[144:147], v[212:215], v[62:65]
	v_mfma_f32_16x16x32_bf16 v[62:65], v[184:187], v[216:219], v[62:65]
	v_mfma_f32_16x16x32_bf16 v[46:49], v[184:187], v[224:227], v[46:49]
	v_mfma_f32_16x16x32_bf16 v[46:49], v[144:147], v[220:223], v[46:49]
	v_mfma_f32_16x16x32_bf16 v[30:33], v[144:147], v[228:231], v[30:33]
	v_mfma_f32_16x16x32_bf16 v[30:33], v[184:187], v[232:235], v[30:33]
	v_mfma_f32_16x16x32_bf16 v[14:17], v[184:187], v[240:243], v[14:17]
	v_mfma_f32_16x16x32_bf16 v[14:17], v[144:147], v[236:239], v[14:17]
	v_mfma_f32_16x16x32_bf16 v[10:13], v[188:191], v[236:239], v[10:13]
	v_mfma_f32_16x16x32_bf16 v[10:13], v[192:195], v[240:243], v[10:13]
	v_mfma_f32_16x16x32_bf16 v[26:29], v[192:195], v[232:235], v[26:29]
	v_mfma_f32_16x16x32_bf16 v[26:29], v[188:191], v[228:231], v[26:29]
	v_mfma_f32_16x16x32_bf16 v[42:45], v[188:191], v[220:223], v[42:45]
	v_mfma_f32_16x16x32_bf16 v[42:45], v[192:195], v[224:227], v[42:45]
	v_mfma_f32_16x16x32_bf16 v[58:61], v[192:195], v[216:219], v[58:61]
	v_mfma_f32_16x16x32_bf16 v[58:61], v[188:191], v[212:215], v[58:61]
	v_mfma_f32_16x16x32_bf16 v[54:57], v[196:199], v[212:215], v[54:57]
	v_mfma_f32_16x16x32_bf16 v[54:57], v[200:203], v[216:219], v[54:57]
	v_mfma_f32_16x16x32_bf16 v[38:41], v[200:203], v[224:227], v[38:41]
	v_mfma_f32_16x16x32_bf16 v[38:41], v[196:199], v[220:223], v[38:41]
	v_mfma_f32_16x16x32_bf16 v[22:25], v[196:199], v[228:231], v[22:25]
	v_mfma_f32_16x16x32_bf16 v[22:25], v[200:203], v[232:235], v[22:25]
	v_mfma_f32_16x16x32_bf16 v[6:9], v[200:203], v[240:243], v[6:9]
	v_mfma_f32_16x16x32_bf16 v[6:9], v[196:199], v[236:239], v[6:9]
	v_mfma_f32_16x16x32_bf16 v[2:5], v[204:207], v[236:239], v[2:5]
	v_mfma_f32_16x16x32_bf16 v[2:5], v[208:211], v[240:243], v[2:5]
	v_mfma_f32_16x16x32_bf16 v[18:21], v[208:211], v[232:235], v[18:21]
	v_mfma_f32_16x16x32_bf16 v[18:21], v[204:207], v[228:231], v[18:21]
	s_barrier
	s_setprio 2
	v_mfma_f32_16x16x32_bf16 v[34:37], v[204:207], v[220:223], v[34:37]
	v_mfma_f32_16x16x32_bf16 v[34:37], v[208:211], v[224:227], v[34:37]
	v_mfma_f32_16x16x32_bf16 v[50:53], v[208:211], v[216:219], v[50:53]
	v_mfma_f32_16x16x32_bf16 v[50:53], v[204:207], v[212:215], v[50:53]
	s_setprio 0
	s_add_i32 s70, s70, 2
	s_add_u32 vcc_lo, vcc_lo, 0x1000
	s_addc_u32 vcc_hi, vcc_hi, 0
	s_add_u32 s16, s16, 0x1000
	s_addc_u32 s17, s17, 0
	s_cmp_gt_u32 s70, 29
	s_cbranch_scc0 .LBB0_114
	s_and_b64 vcc, exec, s[38:39]
	s_cbranch_vccz .LBB0_117
	s_barrier

; template <class Epi, class Sched, bool ALIGN_EPI = false, bool SP2 = false, bool ABLK = false>
; __device__ __forceinline__ void gemm_phase(PG8_LAS unsigned char* lds, const Gemm g, const Sched& S, const Epi& E) {
;     const int tid = threadIdx.x, wid = __builtin_amdgcn_readfirstlane(tid >> 6), lane = tid & 63, wr = wid >> 2, wc = wid & 3, fr = lane & 15, fq = lane >> 4;
;     const int K = g.K;
;     unsigned voffA[2], voffB[2];
; #pragma unroll
;     for (int i = 0; i < 2; ++i) { int R, C; stage_rc(tid * 16 + i * 8192, R, C); const int Rb = Epi::PERM ? ((R & ~31) + perm32(R & 31)) : R;
;         voffA[i] = (unsigned)(R * K + C) * 2u; (void)Rb;
;         if constexpr (ABLK) { const int st = (tid >> 6) + 8 * i; voffA[i] = (unsigned)(((st >> 1) * (K / 32) + (st & 1)) * 1024 + (tid & 63) * 16); }
;         { static_assert(Epi::PERM, "blocked weight copies are written in permuted row-slot order"); const int st = (tid >> 6) + 8 * i; voffB[i] = (unsigned)(((st >> 1) * (K / 32) + (st & 1)) * 1024 + (tid & 63) * 16); } }
;     const size_t kstep = ABLK ? (size_t)(BK / 32) * 1024 : (size_t)(BK * 2);
;     constexpr int KOA = ABLK ? 32 : 2;
;     const size_t pstep = (size_t)K * 128;
;     const size_t kstepB = (size_t)(BK / 32) * 1024;
;     const size_t hstep = (size_t)HALF * K * 2;
;     const size_t tstep = 2 * hstep;
;     const unsigned ldsw = (unsigned)wid * 1024u;
;     const int aoff = lds_byte(wr * 64 + fr, fq * 8), boff = lds_byte(wc * 32 + fr, fq * 8);
;     ...
;     Unit cur, nxt; int ui = 0;
;     if (!S.next(0, cur)) return;
;     f32x4 acc[2][2][4][2];
; #pragma unroll
;     for (int a = 0; a < 2; ++a)
; #pragma unroll
;         for (int b = 0; b < 2; ++b)
; #pragma unroll
;             for (int m = 0; m < 4; ++m)
; #pragma unroll
;                 for (int n = 0; n < 2; ++n) acc[a][b][m][n] = (f32x4){0.f, 0.f, 0.f, 0.f};
;     bf16x8 At[4][2], B0[2][2], B1[2][2];
;     const char* cA = (const char*)g.A + (size_t)cur.pm * tstep + (size_t)cur.ko * KOA; const char* cB = (const char*)g.Bt + (size_t)cur.pn * tstep + (size_t)cur.ko * 32; int nt = cur.nt;
;     S.a_ready(cur);
;     if constexpr (SP2) {
;         PG8_STAGE(PG8_SB(0, 0), cB, voffB); PG8_STAGE(PG8_SB(0, 1), cB + hstep, voffB); PG8_STAGE(PG8_SA(0, 0), cA, voffA); PG8_STAGE(PG8_SA(0, 1), cA + hstep, voffA);
;         if (wr == 1) PG8_BAR;
;         PG8_WAIT_V(2); PG8_BAR;
.LBB0_467:
	s_andn2_b64 vcc, exec, s[4:5]
	s_cbranch_vccnz .LBB0_516
	s_add_u32 s33, s86, 0x38a00000
	s_addc_u32 s52, s87, 0
	s_add_u32 s53, s86, 0x6500000
	v_and_b32_e32 v6, 1, v183
	s_movk_i32 s3, 0x180
	s_addc_u32 s54, s87, 0
	v_and_or_b32 v1, v0, s3, v6
	s_ashr_i32 s3, s2, 31
	s_ashr_i32 s91, s90, 31
	s_ashr_i32 s11, s10, 31
	s_ashr_i32 s6, s8, 2
	s_lshl_b32 s55, s8, 10
	s_lshl_b64 s[4:5], s[2:3], 21
	s_lshl_b64 s[18:19], s[90:91], 5
	s_lshl_b64 s[12:13], s[10:11], 21
	s_add_u32 s3, s53, s12
	s_addc_u32 s7, s54, s13
	s_add_u32 s94, s3, s18
	v_lshlrev_b32_e32 v7, 4, v182
	s_addc_u32 s95, s7, s19
	s_add_i32 s56, s55, 0
	v_lshl_or_b32 v154, v1, 10, v7
	v_mov_b32_e32 v155, 0
	s_add_i32 m0, s56, 0x10000
	v_lshl_add_u64 v[2:3], s[94:95], 0, v[154:155]
	global_load_lds_dwordx4 v154, s[94:95]
	s_mov_b64 s[12:13], 0x80000
	s_add_i32 m0, s56, 0x12000
	s_waitcnt lgkmcnt(0)
	v_lshl_add_u64 v[4:5], v[2:3], 0, s[12:13]
	s_add_u32 s3, s33, s4
	s_mov_b64 s[14:15], 0x100000
	global_load_lds_dwordx4 v[4:5], off sc1
	s_addc_u32 s4, s52, s5
	v_lshl_add_u64 v[4:5], v[2:3], 0, s[14:15]
	s_add_i32 m0, s56, 0x14000
	s_mov_b64 s[16:17], 0x180000
	global_load_lds_dwordx4 v[4:5], off sc1
	s_add_i32 m0, s56, 0x16000
	s_add_u32 s92, s3, s18
	v_lshl_add_u64 v[4:5], v[2:3], 0, s[16:17]
	s_addc_u32 s93, s4, s19
	global_load_lds_dwordx4 v[4:5], off sc1
	v_lshl_add_u64 v[4:5], s[92:93], 0, v[154:155]
	s_mov_b32 m0, s56
	s_add_i32 s57, s56, 0x2000
	global_load_lds_dwordx4 v154, s[92:93]
	v_lshl_add_u64 v[8:9], v[4:5], 0, s[12:13]
	s_mov_b32 m0, s57
	s_add_i32 s58, s56, 0x4000
	global_load_lds_dwordx4 v[8:9], off sc1
	v_lshl_add_u64 v[8:9], v[4:5], 0, s[14:15]
	s_mov_b32 m0, s58
	s_add_i32 s59, s56, 0x6000
	global_load_lds_dwordx4 v[8:9], off sc1
	v_lshl_add_u64 v[8:9], v[4:5], 0, s[16:17]
	s_mov_b32 m0, s59
	s_cmp_eq_u32 s6, 1
	global_load_lds_dwordx4 v[8:9], off sc1
	s_cselect_b64 s[18:19], -1, 0
	s_cmp_lg_u32 s6, 1
	s_mov_b32 s21, 0
	s_cbranch_scc1 .LBB0_470
	s_barrier
.LBB0_470:
	s_add_u32 s22, s86, 0x40000
	s_addc_u32 s23, s87, 0
	s_add_u32 s60, s86, 0x1b400000
	s_mov_b64 s[24:25], 0x800
	s_addc_u32 s61, s87, 0
	v_lshl_add_u64 v[8:9], v[2:3], 0, s[24:25]
	s_add_i32 m0, s56, 0x18000
	s_mov_b64 s[26:27], 0x80800
	s_waitcnt vmcnt(2)
	s_barrier
	global_load_lds_dwordx4 v[8:9], off sc1
	v_lshl_add_u64 v[8:9], v[2:3], 0, s[26:27]
	s_add_i32 m0, s56, 0x1a000
	s_add_i32 s62, s56, 0x8000
	global_load_lds_dwordx4 v[8:9], off sc1
	v_lshl_add_u64 v[8:9], v[4:5], 0, s[24:25]
	s_mov_b32 m0, s62
	s_add_i32 s63, s56, 0xa000
	global_load_lds_dwordx4 v[8:9], off sc1
	v_lshl_add_u64 v[4:5], v[4:5], 0, s[26:27]
	s_mov_b32 m0, s63
	s_mov_b64 s[28:29], 0x100800
	global_load_lds_dwordx4 v[4:5], off sc1
	v_lshl_add_u64 v[4:5], v[2:3], 0, s[28:29]
	s_add_i32 m0, s56, 0x1c000
	s_mov_b64 s[30:31], 0x180800
	global_load_lds_dwordx4 v[4:5], off sc1
	v_lshl_add_u64 v[2:3], v[2:3], 0, s[30:31]
	s_add_i32 m0, s56, 0x1e000
	v_lshrrev_b32_e32 v1, 1, v0
	global_load_lds_dwordx4 v[2:3], off sc1
	v_and_b32_e32 v3, 15, v0
	v_and_b32_e32 v9, 48, v0
	v_lshlrev_b32_e32 v2, 6, v3
	v_lshlrev_b32_e32 v5, 2, v0
	v_and_b32_e32 v4, 24, v1
	v_or_b32_e32 v1, v2, v9
	s_lshl_b32 s4, s6, 13
	v_and_b32_e32 v10, 32, v5
	s_and_b32 s3, s8, 3
	v_bitop3_b32 v11, v1, s4, v10 bitop3:0xde
	v_lshlrev_b32_e32 v1, 6, v0
	s_movk_i32 s4, 0x3c0
	v_and_or_b32 v1, v1, s4, v9
	s_lshl_b32 s4, s3, 12
	s_cmp_lt_u32 s8, 4
	v_lshl_or_b32 v8, s6, 6, v3
	s_cselect_b64 s[34:35], -1, 0
	s_lshl_b32 s11, s6, 10
	s_lshl_b32 s6, s8, 6
	v_bitop3_b32 v1, s4, v1, v10 bitop3:0xf6
	v_lshlrev_b32_e32 v10, 4, v3
	v_or3_b32 v165, s6, v9, v3
	v_mov_b32_e32 v3, v155
	v_lshl_or_b32 v164, s3, 5, v4
	v_bitop3_b32 v4, v5, v9, 32 bitop3:0x6c
	v_mov_b32_e32 v5, v155
	v_lshl_add_u64 v[2:3], s[86:87], 0, v[2:3]
	s_and_b32 s66, s8, -4
	v_lshl_add_u64 v[2:3], v[2:3], 0, v[4:5]
	s_mov_b64 s[8:9], 0x16e00000
	s_lshl_b32 s20, s3, 1
	v_lshl_add_u64 v[156:157], v[2:3], 0, s[8:9]
	s_lshl_b32 s3, s3, 2
	v_lshlrev_b32_e32 v2, 10, v0
	v_lshlrev_b32_e32 v9, 4, v165
	s_add_i32 s3, s3, 0
	v_and_b32_e32 v2, 0x60000, v2
	v_lshlrev_b32_e32 v3, 10, v6
	s_waitcnt vmcnt(6)
	s_add_i32 s3, s3, s11
	v_or3_b32 v158, v2, v3, v7
	v_add_u32_e32 v2, 0, v9
	s_movk_i32 s6, 0x100
	s_add_i32 s3, s3, 0x20800
	s_add_i32 s73, 0, 0x10000
	s_add_i32 s74, 0, 0x14000
	v_add_u32_e32 v170, 0x20800, v2
	v_mbcnt_lo_u32_b32 v2, -1, 0
	v_cmp_gt_u32_e64 s[4:5], 16, v182
	v_cmp_gt_i32_e64 s[6:7], s6, v165
	s_ashr_i32 s67, s97, 31
	s_ashr_i32 s72, s82, 31
	v_add_u32_e32 v166, 0xffffc000, v8
	v_mov_b32_e32 v159, v155
	v_mov_b64_e32 v[160:161], 0x1ff
	v_add_u32_e32 v167, s73, v1
	v_add_u32_e32 v168, s74, v1
	v_add_u32_e32 v169, 0, v11
	s_mov_b32 s75, 0x20000
	v_mbcnt_hi_u32_b32 v171, -1, v2
	v_add_u32_e32 v172, s3, v10
	s_mov_b32 s76, s21
	s_barrier
	s_branch .LBB0_473

; #define PG8_STAGE(bufoff, gbase, voff) do { if constexpr (!pg8_noload<Epi>::value) { _Pragma("unroll") for (int _i = 0; _i < 2; ++_i) \
;         __builtin_amdgcn_global_load_lds((const unsigned*)((const char*)(gbase) + (size_t)_i * pstep + (voff)[0]), (PG8_LAS unsigned*)(lds + (bufoff) + ldsw + _i * 8192), 16, 0, 0); } } while (0)
; #define PG8_LDA(dst, b, h) do { _Pragma("unroll") for (int m = 0; m < 4; ++m) _Pragma("unroll") for (int k = 0; k < 2; ++k) dst[m][k] = *(const PG8_LAS bf16x8*)(lds + PG8_SA(b, h) + aoff + m * 2048 + k * 1024); } while (0)
; #define PG8_LDB(dst, b, h) do { _Pragma("unroll") for (int n = 0; n < 2; ++n) _Pragma("unroll") for (int k = 0; k < 2; ++k) dst[n][k] = *(const PG8_LAS bf16x8*)(lds + PG8_SB(b, h) + boff + n * 2048 + k * 1024); } while (0)
; #define PG8_WAIT_V(n) asm volatile("s_waitcnt vmcnt(" #n ")" ::: "memory")
; #define PG8_WAIT_L(n) asm volatile("s_waitcnt lgkmcnt(" #n ")" ::: "memory")
; #define PG8_BAR __builtin_amdgcn_s_barrier()
; template <class Epi, class Sched, bool ALIGN_EPI = false, bool SP2 = false, bool ABLK = false>
; __device__ __forceinline__ void gemm_phase(PG8_LAS unsigned char* lds, const Gemm g, const Sched& S, const Epi& E) {
;     ...
;         const char* nA = has_next ? (const char*)g.A + (size_t)nxt.pm * tstep + (size_t)nxt.ko * KOA : cA; const char* nB = has_next ? (const char*)g.Bt + (size_t)nxt.pn * tstep + (size_t)nxt.ko * 32 : cB;
;         for (int t = 0; t < nt; t += 2) {
;             const bool last = (t == nt - 2);
;             const char* a1 = cA + (size_t)(t + 1) * kstep;
;             const char* a2 = last ? nA : cA + (size_t)(t + 2) * kstep; const char* b2 = last ? nB : cB + (size_t)(t + 2) * kstepB;
;             const char* a3 = a2 + kstep; const char* b3 = b2 + kstepB;
;             if (last && has_next) S.a_ready(nxt);
;             if constexpr (SP2) {
;             PG8_LDB(B0, 0, 0); PG8_LDB(B1, 0, 1); PG8_SCHED; PG8_LDA(At, 0, 0); PG8_STAGE(PG8_SA(1, 1), a1 + hstep, voffA);
;             PG8_WAIT_V(8); PG8_WAIT_L(0); PG8_BAR; PG8_MMA(0, 0, At, B0); PG8_MMA(0, 1, At, B1); PG8_BAR; PG8_SCHED;
;             PG8_LDA(At, 0, 1); PG8_STAGE(PG8_SB(0, 0), b2, voffB); PG8_STAGE(PG8_SB(0, 1), b2 + hstep, voffB); PG8_STAGE(PG8_SA(0, 0), a2, voffA);
;             PG8_WAIT_V(8); PG8_WAIT_L(0); PG8_BAR; PG8_MMA(1, 0, At, B0); PG8_MMA(1, 1, At, B1); PG8_BAR; PG8_SCHED;
.LBB0_487:
	ds_read_b128 v[114:117], v167
	ds_read_b128 v[126:129], v167 offset:1024
	ds_read_b128 v[130:133], v167 offset:2048
	ds_read_b128 v[142:145], v167 offset:3072
	ds_read_b128 v[146:149], v168
	ds_read_b128 v[150:153], v168 offset:1024
	ds_read_b128 v[174:177], v168 offset:2048
	ds_read_b128 v[178:181], v168 offset:3072
	s_add_i32 s65, s39, 2
	s_add_u32 s68, s92, 0xfff00800
	s_addc_u32 s69, s93, -1
	s_cmp_eq_u32 s3, s39
	s_cselect_b32 s69, s79, s69
	s_cselect_b32 s68, s78, s68
	s_cselect_b32 s71, s89, s37
	s_cselect_b32 s70, s88, s11
	v_lshl_add_u64 v[162:163], s[92:93], 0, v[158:159]
	s_add_i32 m0, s56, 0xc000
	ds_read_b128 v[184:187], v169
	ds_read_b128 v[188:191], v169 offset:1024
	ds_read_b128 v[192:195], v169 offset:2048
	ds_read_b128 v[196:199], v169 offset:3072
	ds_read_b128 v[200:203], v169 offset:4096
	ds_read_b128 v[204:207], v169 offset:5120
	ds_read_b128 v[208:211], v169 offset:6144
	ds_read_b128 v[212:215], v169 offset:7168
	global_load_lds_dwordx4 v[162:163], off sc1
	v_lshl_add_u64 v[162:163], v[162:163], 0, s[12:13]
	s_add_i32 m0, s56, 0xe000
	s_nop 0
	global_load_lds_dwordx4 v[162:163], off sc1
	s_waitcnt vmcnt(8)
	s_waitcnt lgkmcnt(0)
	s_barrier
	s_setprio 1
	s_waitcnt lgkmcnt(0)
	v_mfma_f32_16x16x32_bf16 v[138:141], v[114:117], v[184:187], v[138:141]
	v_mfma_f32_16x16x32_bf16 v[138:141], v[126:129], v[188:191], v[138:141]
	v_mfma_f32_16x16x32_bf16 v[110:113], v[126:129], v[196:199], v[110:113]
	v_mfma_f32_16x16x32_bf16 v[110:113], v[114:117], v[192:195], v[110:113]
	v_mfma_f32_16x16x32_bf16 v[94:97], v[114:117], v[200:203], v[94:97]
	v_mfma_f32_16x16x32_bf16 v[94:97], v[126:129], v[204:207], v[94:97]
	v_mfma_f32_16x16x32_bf16 v[78:81], v[126:129], v[212:215], v[78:81]
	v_mfma_f32_16x16x32_bf16 v[78:81], v[114:117], v[208:211], v[78:81]
	v_mfma_f32_16x16x32_bf16 v[74:77], v[130:133], v[208:211], v[74:77]
	v_mfma_f32_16x16x32_bf16 v[74:77], v[142:145], v[212:215], v[74:77]
	v_mfma_f32_16x16x32_bf16 v[90:93], v[142:145], v[204:207], v[90:93]
	v_mfma_f32_16x16x32_bf16 v[90:93], v[130:133], v[200:203], v[90:93]
	v_mfma_f32_16x16x32_bf16 v[106:109], v[130:133], v[192:195], v[106:109]
	v_mfma_f32_16x16x32_bf16 v[106:109], v[142:145], v[196:199], v[106:109]
	v_mfma_f32_16x16x32_bf16 v[134:137], v[142:145], v[188:191], v[134:137]
	v_mfma_f32_16x16x32_bf16 v[134:137], v[130:133], v[184:187], v[134:137]
	v_mfma_f32_16x16x32_bf16 v[122:125], v[146:149], v[184:187], v[122:125]
	v_mfma_f32_16x16x32_bf16 v[122:125], v[150:153], v[188:191], v[122:125]
	v_mfma_f32_16x16x32_bf16 v[102:105], v[150:153], v[196:199], v[102:105]
	v_mfma_f32_16x16x32_bf16 v[102:105], v[146:149], v[192:195], v[102:105]
	v_mfma_f32_16x16x32_bf16 v[86:89], v[146:149], v[200:203], v[86:89]
	v_mfma_f32_16x16x32_bf16 v[86:89], v[150:153], v[204:207], v[86:89]
	v_mfma_f32_16x16x32_bf16 v[70:73], v[150:153], v[212:215], v[70:73]
	v_mfma_f32_16x16x32_bf16 v[70:73], v[146:149], v[208:211], v[70:73]
	v_mfma_f32_16x16x32_bf16 v[66:69], v[174:177], v[208:211], v[66:69]
	v_mfma_f32_16x16x32_bf16 v[66:69], v[178:181], v[212:215], v[66:69]
	v_mfma_f32_16x16x32_bf16 v[82:85], v[178:181], v[204:207], v[82:85]
	v_mfma_f32_16x16x32_bf16 v[82:85], v[174:177], v[200:203], v[82:85]
	s_barrier
	s_setprio 2
	v_mfma_f32_16x16x32_bf16 v[98:101], v[174:177], v[192:195], v[98:101]
	v_mfma_f32_16x16x32_bf16 v[98:101], v[178:181], v[196:199], v[98:101]
	v_mfma_f32_16x16x32_bf16 v[118:121], v[178:181], v[188:191], v[118:121]
	v_mfma_f32_16x16x32_bf16 v[118:121], v[174:177], v[184:187], v[118:121]
	s_setprio 0
	s_add_i32 s39, s73, s55
	v_lshl_add_u64 v[162:163], s[70:71], 0, v[154:155]
	s_mov_b32 m0, s39
	ds_read_b128 v[184:187], v169 offset:16384
	ds_read_b128 v[188:191], v169 offset:17408
	ds_read_b128 v[192:195], v169 offset:18432
	ds_read_b128 v[196:199], v169 offset:19456
	ds_read_b128 v[200:203], v169 offset:20480
	ds_read_b128 v[204:207], v169 offset:21504
	ds_read_b128 v[208:211], v169 offset:22528
	ds_read_b128 v[212:215], v169 offset:23552
	global_load_lds_dwordx4 v[162:163], off sc1
	v_lshl_add_u64 v[216:217], v[162:163], 0, s[12:13]
	s_add_i32 m0, s39, 0x2000
	s_add_i32 s39, s74, s55
	global_load_lds_dwordx4 v[216:217], off sc1
	v_lshl_add_u64 v[216:217], v[162:163], 0, s[14:15]
	s_mov_b32 m0, s39
	s_nop 0
	global_load_lds_dwordx4 v[216:217], off sc1
	v_lshl_add_u64 v[216:217], v[162:163], 0, s[16:17]
	s_add_i32 m0, s39, 0x2000
	s_nop 0
	global_load_lds_dwordx4 v[216:217], off sc1
	v_lshl_add_u64 v[216:217], s[68:69], 0, v[154:155]
	s_mov_b32 m0, s56
	v_lshl_add_u64 v[218:219], v[216:217], 0, s[12:13]
	global_load_lds_dwordx4 v[216:217], off sc1
	s_mov_b32 m0, s57
	s_nop 0
	global_load_lds_dwordx4 v[218:219], off sc1
	s_waitcnt vmcnt(8)
	s_waitcnt lgkmcnt(0)
	s_barrier
; #define PG8_STAGE(bufoff, gbase, voff) do { if constexpr (!pg8_noload<Epi>::value) { _Pragma("unroll") for (int _i = 0; _i < 2; ++_i) \
;         __builtin_amdgcn_global_load_lds((const unsigned*)((const char*)(gbase) + (size_t)_i * pstep + (voff)[0]), (PG8_LAS unsigned*)(lds + (bufoff) + ldsw + _i * 8192), 16, 0, 0); } } while (0)
; #define PG8_LDA(dst, b, h) do { _Pragma("unroll") for (int m = 0; m < 4; ++m) _Pragma("unroll") for (int k = 0; k < 2; ++k) dst[m][k] = *(const PG8_LAS bf16x8*)(lds + PG8_SA(b, h) + aoff + m * 2048 + k * 1024); } while (0)
; #define PG8_LDB(dst, b, h) do { _Pragma("unroll") for (int n = 0; n < 2; ++n) _Pragma("unroll") for (int k = 0; k < 2; ++k) dst[n][k] = *(const PG8_LAS bf16x8*)(lds + PG8_SB(b, h) + boff + n * 2048 + k * 1024); } while (0)
; #define PG8_MMA(ai, bj, At, Bt) do { __builtin_amdgcn_s_setprio(1); _Pragma("unroll") for (int m = 0; m < 4; ++m) _Pragma("unroll") for (int n = 0; n < 2; ++n) _Pragma("unroll") for (int k = 0; k < 2; ++k) \
;         acc[ai][bj][m][n] = __builtin_amdgcn_mfma_f32_16x16x32_bf16(Bt[n][k], At[m][k], acc[ai][bj][m][n], 0, 0, 0); __builtin_amdgcn_s_setprio(0); } while (0)
; #define PG8_WAIT_V(n) asm volatile("s_waitcnt vmcnt(" #n ")" ::: "memory")
; #define PG8_WAIT_L(n) asm volatile("s_waitcnt lgkmcnt(" #n ")" ::: "memory")
; #define PG8_BAR __builtin_amdgcn_s_barrier()
; #define PG8_SCHED __builtin_amdgcn_sched_barrier(0)
; template <class Epi, class Sched, bool ALIGN_EPI = false, bool SP2 = false, bool ABLK = false>
; __device__ __forceinline__ void gemm_phase(PG8_LAS unsigned char* lds, const Gemm g, const Sched& S, const Epi& E) {
;     ...
;             PG8_WAIT_V(8); PG8_WAIT_L(0); PG8_BAR; PG8_MMA(1, 0, At, B0); PG8_MMA(1, 1, At, B1); PG8_BAR; PG8_SCHED;
;             PG8_LDB(B0, 1, 0); PG8_LDB(B1, 1, 1); PG8_SCHED; PG8_LDA(At, 1, 0); PG8_STAGE(PG8_SA(0, 1), a2 + hstep, voffA);
;             PG8_WAIT_V(8); PG8_WAIT_L(0); PG8_BAR; PG8_MMA(0, 0, At, B0); PG8_MMA(0, 1, At, B1); PG8_BAR; PG8_SCHED;
	s_setprio 1
	s_waitcnt lgkmcnt(0)
	v_mfma_f32_16x16x32_bf16 v[62:65], v[114:117], v[184:187], v[62:65]
	v_mfma_f32_16x16x32_bf16 v[62:65], v[126:129], v[188:191], v[62:65]
	v_mfma_f32_16x16x32_bf16 v[46:49], v[126:129], v[196:199], v[46:49]
	v_mfma_f32_16x16x32_bf16 v[46:49], v[114:117], v[192:195], v[46:49]
	v_mfma_f32_16x16x32_bf16 v[30:33], v[114:117], v[200:203], v[30:33]
	v_mfma_f32_16x16x32_bf16 v[30:33], v[126:129], v[204:207], v[30:33]
	v_mfma_f32_16x16x32_bf16 v[14:17], v[126:129], v[212:215], v[14:17]
	v_mfma_f32_16x16x32_bf16 v[14:17], v[114:117], v[208:211], v[14:17]
	v_mfma_f32_16x16x32_bf16 v[10:13], v[130:133], v[208:211], v[10:13]
	v_mfma_f32_16x16x32_bf16 v[10:13], v[142:145], v[212:215], v[10:13]
	v_mfma_f32_16x16x32_bf16 v[26:29], v[142:145], v[204:207], v[26:29]
	v_mfma_f32_16x16x32_bf16 v[26:29], v[130:133], v[200:203], v[26:29]
	v_mfma_f32_16x16x32_bf16 v[42:45], v[130:133], v[192:195], v[42:45]
	v_mfma_f32_16x16x32_bf16 v[42:45], v[142:145], v[196:199], v[42:45]
	v_mfma_f32_16x16x32_bf16 v[58:61], v[142:145], v[188:191], v[58:61]
	v_mfma_f32_16x16x32_bf16 v[58:61], v[130:133], v[184:187], v[58:61]
	v_mfma_f32_16x16x32_bf16 v[54:57], v[146:149], v[184:187], v[54:57]
	v_mfma_f32_16x16x32_bf16 v[54:57], v[150:153], v[188:191], v[54:57]
	v_mfma_f32_16x16x32_bf16 v[38:41], v[150:153], v[196:199], v[38:41]
	v_mfma_f32_16x16x32_bf16 v[38:41], v[146:149], v[192:195], v[38:41]
	v_mfma_f32_16x16x32_bf16 v[22:25], v[146:149], v[200:203], v[22:25]
	v_mfma_f32_16x16x32_bf16 v[22:25], v[150:153], v[204:207], v[22:25]
	v_mfma_f32_16x16x32_bf16 v[6:9], v[150:153], v[212:215], v[6:9]
	v_mfma_f32_16x16x32_bf16 v[6:9], v[146:149], v[208:211], v[6:9]
	v_mfma_f32_16x16x32_bf16 v[2:5], v[174:177], v[208:211], v[2:5]
	v_mfma_f32_16x16x32_bf16 v[2:5], v[178:181], v[212:215], v[2:5]
	v_mfma_f32_16x16x32_bf16 v[18:21], v[178:181], v[204:207], v[18:21]
	v_mfma_f32_16x16x32_bf16 v[18:21], v[174:177], v[200:203], v[18:21]
	s_barrier
	s_setprio 2
	v_mfma_f32_16x16x32_bf16 v[34:37], v[174:177], v[192:195], v[34:37]
	v_mfma_f32_16x16x32_bf16 v[34:37], v[178:181], v[196:199], v[34:37]
	v_mfma_f32_16x16x32_bf16 v[50:53], v[178:181], v[188:191], v[50:53]
	v_mfma_f32_16x16x32_bf16 v[50:53], v[174:177], v[184:187], v[50:53]
	s_setprio 0
	s_add_i32 s39, 0, 0x18000
	s_add_i32 s68, 0, 0x1c000
	v_add_u32_e32 v142, s39, v1
	v_add_u32_e32 v173, s68, v1
	ds_read_b128 v[114:117], v142
	ds_read_b128 v[126:129], v142 offset:1024
	ds_read_b128 v[130:133], v142 offset:2048
	ds_read_b128 v[142:145], v142 offset:3072
	ds_read_b128 v[146:149], v173
	ds_read_b128 v[150:153], v173 offset:1024
	ds_read_b128 v[174:177], v173 offset:2048
	ds_read_b128 v[178:181], v173 offset:3072
	s_mov_b32 m0, s58
	v_lshl_add_u64 v[218:219], v[216:217], 0, s[14:15]
	ds_read_b128 v[184:187], v169 offset:32768
	ds_read_b128 v[188:191], v169 offset:33792
	ds_read_b128 v[192:195], v169 offset:34816
	ds_read_b128 v[196:199], v169 offset:35840
	ds_read_b128 v[200:203], v169 offset:36864
	ds_read_b128 v[204:207], v169 offset:37888
	ds_read_b128 v[208:211], v169 offset:38912
	ds_read_b128 v[212:215], v169 offset:39936
	global_load_lds_dwordx4 v[218:219], off sc1
	v_lshl_add_u64 v[218:219], v[216:217], 0, s[16:17]
	s_mov_b32 m0, s59
	s_nop 0
	global_load_lds_dwordx4 v[218:219], off sc1
	s_waitcnt vmcnt(8)
	s_waitcnt lgkmcnt(0)
	s_barrier
	s_setprio 1
	s_waitcnt lgkmcnt(0)
	v_mfma_f32_16x16x32_bf16 v[138:141], v[114:117], v[184:187], v[138:141]
	v_mfma_f32_16x16x32_bf16 v[138:141], v[126:129], v[188:191], v[138:141]
	v_mfma_f32_16x16x32_bf16 v[110:113], v[126:129], v[196:199], v[110:113]
	v_mfma_f32_16x16x32_bf16 v[110:113], v[114:117], v[192:195], v[110:113]
	v_mfma_f32_16x16x32_bf16 v[94:97], v[114:117], v[200:203], v[94:97]
	v_mfma_f32_16x16x32_bf16 v[94:97], v[126:129], v[204:207], v[94:97]
	v_mfma_f32_16x16x32_bf16 v[78:81], v[126:129], v[212:215], v[78:81]
	v_mfma_f32_16x16x32_bf16 v[78:81], v[114:117], v[208:211], v[78:81]
	v_mfma_f32_16x16x32_bf16 v[74:77], v[130:133], v[208:211], v[74:77]
	v_mfma_f32_16x16x32_bf16 v[74:77], v[142:145], v[212:215], v[74:77]
	v_mfma_f32_16x16x32_bf16 v[90:93], v[142:145], v[204:207], v[90:93]
	v_mfma_f32_16x16x32_bf16 v[90:93], v[130:133], v[200:203], v[90:93]
	v_mfma_f32_16x16x32_bf16 v[106:109], v[130:133], v[192:195], v[106:109]
	v_mfma_f32_16x16x32_bf16 v[106:109], v[142:145], v[196:199], v[106:109]
	v_mfma_f32_16x16x32_bf16 v[134:137], v[142:145], v[188:191], v[134:137]
	v_mfma_f32_16x16x32_bf16 v[134:137], v[130:133], v[184:187], v[134:137]
	v_mfma_f32_16x16x32_bf16 v[122:125], v[146:149], v[184:187], v[122:125]
	v_mfma_f32_16x16x32_bf16 v[122:125], v[150:153], v[188:191], v[122:125]
	v_mfma_f32_16x16x32_bf16 v[102:105], v[150:153], v[196:199], v[102:105]
	v_mfma_f32_16x16x32_bf16 v[102:105], v[146:149], v[192:195], v[102:105]
	v_mfma_f32_16x16x32_bf16 v[86:89], v[146:149], v[200:203], v[86:89]
	v_mfma_f32_16x16x32_bf16 v[86:89], v[150:153], v[204:207], v[86:89]
	v_mfma_f32_16x16x32_bf16 v[70:73], v[150:153], v[212:215], v[70:73]
	v_mfma_f32_16x16x32_bf16 v[70:73], v[146:149], v[208:211], v[70:73]
	v_mfma_f32_16x16x32_bf16 v[66:69], v[174:177], v[208:211], v[66:69]
	v_mfma_f32_16x16x32_bf16 v[66:69], v[178:181], v[212:215], v[66:69]
	v_mfma_f32_16x16x32_bf16 v[82:85], v[178:181], v[204:207], v[82:85]
	v_mfma_f32_16x16x32_bf16 v[82:85], v[174:177], v[200:203], v[82:85]
	s_barrier
; #define PG8_STAGE(bufoff, gbase, voff) do { if constexpr (!pg8_noload<Epi>::value) { _Pragma("unroll") for (int _i = 0; _i < 2; ++_i) \
;         __builtin_amdgcn_global_load_lds((const unsigned*)((const char*)(gbase) + (size_t)_i * pstep + (voff)[0]), (PG8_LAS unsigned*)(lds + (bufoff) + ldsw + _i * 8192), 16, 0, 0); } } while (0)
; #define PG8_LDA(dst, b, h) do { _Pragma("unroll") for (int m = 0; m < 4; ++m) _Pragma("unroll") for (int k = 0; k < 2; ++k) dst[m][k] = *(const PG8_LAS bf16x8*)(lds + PG8_SA(b, h) + aoff + m * 2048 + k * 1024); } while (0)
; #define PG8_MMA(ai, bj, At, Bt) do { __builtin_amdgcn_s_setprio(1); _Pragma("unroll") for (int m = 0; m < 4; ++m) _Pragma("unroll") for (int n = 0; n < 2; ++n) _Pragma("unroll") for (int k = 0; k < 2; ++k) \
;         acc[ai][bj][m][n] = __builtin_amdgcn_mfma_f32_16x16x32_bf16(Bt[n][k], At[m][k], acc[ai][bj][m][n], 0, 0, 0); __builtin_amdgcn_s_setprio(0); } while (0)
; #define PG8_WAIT_V(n) asm volatile("s_waitcnt vmcnt(" #n ")" ::: "memory")
; #define PG8_WAIT_L(n) asm volatile("s_waitcnt lgkmcnt(" #n ")" ::: "memory")
; #define PG8_BAR __builtin_amdgcn_s_barrier()
; #define PG8_SCHED __builtin_amdgcn_sched_barrier(0)
;     __device__ __forceinline__ void operator()(const f32x4 (&acc)[2][2][4][2], const Unit& u, int wr, int wc, int fr, int fq) const {
;         const int c0 = u.pn * BM + wc * 32 + 8 * fq;
;         if (u.pm * BM < seq) {
; template <class Epi, class Sched, bool ALIGN_EPI = false, bool SP2 = false, bool ABLK = false>
; __device__ __forceinline__ void gemm_phase(PG8_LAS unsigned char* lds, const Gemm g, const Sched& S, const Epi& E) {
;     ...
;             PG8_WAIT_V(8); PG8_WAIT_L(0); PG8_BAR; PG8_MMA(0, 0, At, B0); PG8_MMA(0, 1, At, B1); PG8_BAR; PG8_SCHED;
;             PG8_LDA(At, 1, 1); PG8_STAGE(PG8_SB(1, 0), b3, voffB); PG8_STAGE(PG8_SB(1, 1), b3 + hstep, voffB); PG8_STAGE(PG8_SA(1, 0), a3, voffA);
;             PG8_WAIT_V(8); PG8_WAIT_L(0); PG8_BAR; PG8_MMA(1, 0, At, B0); PG8_MMA(1, 1, At, B1); PG8_BAR; PG8_SCHED;
	s_setprio 2
	v_mfma_f32_16x16x32_bf16 v[98:101], v[174:177], v[192:195], v[98:101]
	v_mfma_f32_16x16x32_bf16 v[98:101], v[178:181], v[196:199], v[98:101]
	v_mfma_f32_16x16x32_bf16 v[118:121], v[178:181], v[188:191], v[118:121]
	v_mfma_f32_16x16x32_bf16 v[118:121], v[174:177], v[184:187], v[118:121]
	s_setprio 0
	s_add_i32 s39, s39, s55
	v_lshl_add_u64 v[218:219], v[162:163], 0, s[24:25]
	s_mov_b32 m0, s39
	ds_read_b128 v[184:187], v169 offset:49152
	ds_read_b128 v[188:191], v169 offset:50176
	ds_read_b128 v[192:195], v169 offset:51200
	ds_read_b128 v[196:199], v169 offset:52224
	ds_read_b128 v[200:203], v169 offset:53248
	ds_read_b128 v[204:207], v169 offset:54272
	ds_read_b128 v[208:211], v169 offset:55296
	ds_read_b128 v[212:215], v169 offset:56320
	global_load_lds_dwordx4 v[218:219], off sc1
	v_lshl_add_u64 v[218:219], v[162:163], 0, s[26:27]
	s_add_i32 m0, s39, 0x2000
	s_add_i32 s39, s68, s55
	global_load_lds_dwordx4 v[218:219], off sc1
	v_lshl_add_u64 v[218:219], v[162:163], 0, s[28:29]
	s_mov_b32 m0, s39
	v_lshl_add_u64 v[162:163], v[162:163], 0, s[30:31]
	global_load_lds_dwordx4 v[218:219], off sc1
	s_add_i32 m0, s39, 0x2000
	s_nop 0
	global_load_lds_dwordx4 v[162:163], off sc1
	v_lshl_add_u64 v[162:163], v[216:217], 0, s[24:25]
	s_mov_b32 m0, s62
	s_nop 0
	global_load_lds_dwordx4 v[162:163], off sc1
	v_lshl_add_u64 v[162:163], v[216:217], 0, s[26:27]
	s_mov_b32 m0, s63
	s_nop 0
	global_load_lds_dwordx4 v[162:163], off sc1
	s_waitcnt vmcnt(8)
	s_waitcnt lgkmcnt(0)
	s_barrier
	s_setprio 1
	s_waitcnt lgkmcnt(0)
	v_mfma_f32_16x16x32_bf16 v[62:65], v[114:117], v[184:187], v[62:65]
	v_mfma_f32_16x16x32_bf16 v[62:65], v[126:129], v[188:191], v[62:65]
	v_mfma_f32_16x16x32_bf16 v[46:49], v[126:129], v[196:199], v[46:49]
	v_mfma_f32_16x16x32_bf16 v[46:49], v[114:117], v[192:195], v[46:49]
	v_mfma_f32_16x16x32_bf16 v[30:33], v[114:117], v[200:203], v[30:33]
	v_mfma_f32_16x16x32_bf16 v[30:33], v[126:129], v[204:207], v[30:33]
	v_mfma_f32_16x16x32_bf16 v[14:17], v[126:129], v[212:215], v[14:17]
	v_mfma_f32_16x16x32_bf16 v[14:17], v[114:117], v[208:211], v[14:17]
	v_mfma_f32_16x16x32_bf16 v[10:13], v[130:133], v[208:211], v[10:13]
	v_mfma_f32_16x16x32_bf16 v[10:13], v[142:145], v[212:215], v[10:13]
	v_mfma_f32_16x16x32_bf16 v[26:29], v[142:145], v[204:207], v[26:29]
	v_mfma_f32_16x16x32_bf16 v[26:29], v[130:133], v[200:203], v[26:29]
	v_mfma_f32_16x16x32_bf16 v[42:45], v[130:133], v[192:195], v[42:45]
	v_mfma_f32_16x16x32_bf16 v[42:45], v[142:145], v[196:199], v[42:45]
	v_mfma_f32_16x16x32_bf16 v[58:61], v[142:145], v[188:191], v[58:61]
	v_mfma_f32_16x16x32_bf16 v[58:61], v[130:133], v[184:187], v[58:61]
	v_mfma_f32_16x16x32_bf16 v[54:57], v[146:149], v[184:187], v[54:57]
	v_mfma_f32_16x16x32_bf16 v[54:57], v[150:153], v[188:191], v[54:57]
	v_mfma_f32_16x16x32_bf16 v[38:41], v[150:153], v[196:199], v[38:41]
	v_mfma_f32_16x16x32_bf16 v[38:41], v[146:149], v[192:195], v[38:41]
	v_mfma_f32_16x16x32_bf16 v[22:25], v[146:149], v[200:203], v[22:25]
	v_mfma_f32_16x16x32_bf16 v[22:25], v[150:153], v[204:207], v[22:25]
	v_mfma_f32_16x16x32_bf16 v[6:9], v[150:153], v[212:215], v[6:9]
	v_mfma_f32_16x16x32_bf16 v[6:9], v[146:149], v[208:211], v[6:9]
	v_mfma_f32_16x16x32_bf16 v[2:5], v[174:177], v[208:211], v[2:5]
	v_mfma_f32_16x16x32_bf16 v[2:5], v[178:181], v[212:215], v[2:5]
	v_mfma_f32_16x16x32_bf16 v[18:21], v[178:181], v[204:207], v[18:21]
	v_mfma_f32_16x16x32_bf16 v[18:21], v[174:177], v[200:203], v[18:21]
	s_barrier
	s_setprio 2
	v_mfma_f32_16x16x32_bf16 v[34:37], v[174:177], v[192:195], v[34:37]
	v_mfma_f32_16x16x32_bf16 v[34:37], v[178:181], v[196:199], v[34:37]
	v_mfma_f32_16x16x32_bf16 v[50:53], v[178:181], v[188:191], v[50:53]
	v_mfma_f32_16x16x32_bf16 v[50:53], v[174:177], v[184:187], v[50:53]
	s_setprio 0
	s_add_u32 s92, s92, 0x1000
	s_addc_u32 s93, s93, 0
	s_add_u32 s11, s11, 0x1000
	s_addc_u32 s37, s37, 0
	s_cmp_ge_i32 s65, s80
	s_mov_b32 s39, s65
	s_cbranch_scc0 .LBB0_487
	s_and_b64 vcc, exec, s[34:35]
	s_cbranch_vccnz .LBB0_492
	s_lshl_b32 s11, s2, 8
	s_cmp_gt_i32 s2, 63
	s_mov_b64 s[68:69], -1
	s_cbranch_scc1 .LBB0_493

; #define PG8_WAIT_V(n) asm volatile("s_waitcnt vmcnt(" #n ")" ::: "memory")
; #define PG8_BAR __builtin_amdgcn_s_barrier()
; template <class Epi, class Sched, bool ALIGN_EPI = false, bool SP2 = false, bool ABLK = false>
; __device__ __forceinline__ void gemm_phase(PG8_LAS unsigned char* lds, const Gemm g, const Sched& S, const Epi& E) {
;     const int tid = threadIdx.x, wid = __builtin_amdgcn_readfirstlane(tid >> 6), lane = tid & 63, wr = wid >> 2, wc = wid & 3, fr = lane & 15, fq = lane >> 4;
;     const int K = g.K;
;     unsigned voffA[2], voffB[2];
; #pragma unroll
;     for (int i = 0; i < 2; ++i) { int R, C; stage_rc(tid * 16 + i * 8192, R, C); const int Rb = Epi::PERM ? ((R & ~31) + perm32(R & 31)) : R;
;         voffA[i] = (unsigned)(R * K + C) * 2u; (void)Rb;
;         if constexpr (ABLK) { const int st = (tid >> 6) + 8 * i; voffA[i] = (unsigned)(((st >> 1) * (K / 32) + (st & 1)) * 1024 + (tid & 63) * 16); }
;         { static_assert(Epi::PERM, "blocked weight copies are written in permuted row-slot order"); const int st = (tid >> 6) + 8 * i; voffB[i] = (unsigned)(((st >> 1) * (K / 32) + (st & 1)) * 1024 + (tid & 63) * 16); } }
;     const size_t kstep = ABLK ? (size_t)(BK / 32) * 1024 : (size_t)(BK * 2);
;     constexpr int KOA = ABLK ? 32 : 2;
;     const size_t pstep = (size_t)K * 128;
;     const size_t kstepB = (size_t)(BK / 32) * 1024;
;     const size_t hstep = (size_t)HALF * K * 2;
;     const size_t tstep = 2 * hstep;
;     const unsigned ldsw = (unsigned)wid * 1024u;
;     const int aoff = lds_byte(wr * 64 + fr, fq * 8), boff = lds_byte(wc * 32 + fr, fq * 8);
;     ...
;     const char* cA = (const char*)g.A + (size_t)cur.pm * tstep + (size_t)cur.ko * KOA; const char* cB = (const char*)g.Bt + (size_t)cur.pn * tstep + (size_t)cur.ko * 32; int nt = cur.nt;
;     S.a_ready(cur);
;     if constexpr (SP2) {
;         PG8_STAGE(PG8_SB(0, 0), cB, voffB); PG8_STAGE(PG8_SB(0, 1), cB + hstep, voffB); PG8_STAGE(PG8_SA(0, 0), cA, voffA); PG8_STAGE(PG8_SA(0, 1), cA + hstep, voffA);
;         if (wr == 1) PG8_BAR;
;         PG8_WAIT_V(2); PG8_BAR;
;         PG8_STAGE(PG8_SB(1, 0), cB + kstepB, voffB); PG8_STAGE(PG8_SA(1, 0), cA + kstep, voffA); PG8_STAGE(PG8_SB(1, 1), cB + hstep + kstepB, voffB);
;         PG8_WAIT_V(6); PG8_BAR;
.LBB0_604:
	s_add_u32 s4, s86, 0x8500000
	s_addc_u32 s5, s87, 0
	s_ashr_i32 s15, s14, 31
	s_lshl_b64 s[0:1], s[14:15], 20
	s_add_u32 s2, s38, s0
	s_addc_u32 s3, s39, s1
	s_ashr_i32 s91, s90, 31
	s_lshl_b64 s[0:1], s[90:91], 20
	s_add_u32 s16, s4, s0
	v_lshlrev_b32_e32 v3, 5, v183
	v_lshlrev_b32_e32 v2, 4, v0
	s_movk_i32 s0, 0xc1
	s_addc_u32 s17, s5, s1
	v_and_b32_e32 v2, 0x3f0, v2
	v_bitop3_b32 v3, v3, s0, v183 bitop3:0xc8
	s_lshl_b32 s91, s8, 10
	v_mov_b32_e32 v141, 0
	v_lshl_or_b32 v138, v3, 10, v2
	v_mov_b32_e32 v139, v141
	s_add_i32 s70, s91, 0
	v_lshl_add_u64 v[4:5], s[16:17], 0, v[138:139]
	s_add_i32 m0, s70, 0x10000
	s_mov_b64 s[22:23], 0x40000
	global_load_lds_dwordx4 v138, s[16:17]
	v_lshl_add_u64 v[6:7], v[4:5], 0, s[22:23]
	s_add_i32 m0, s70, 0x12000
	s_mov_b64 s[24:25], 0x80000
	global_load_lds_dwordx4 v[6:7], off sc1
	v_lshl_add_u64 v[6:7], v[4:5], 0, s[24:25]
	s_add_i32 m0, s70, 0x14000
	s_mov_b64 s[26:27], 0xc0000
	global_load_lds_dwordx4 v[6:7], off sc1
	v_lshl_add_u64 v[6:7], v[4:5], 0, s[26:27]
	s_add_i32 m0, s70, 0x16000
	s_add_i32 s71, s70, 0x2000
	global_load_lds_dwordx4 v[6:7], off sc1
	v_lshl_add_u64 v[6:7], s[2:3], 0, v[138:139]
	s_mov_b32 m0, s70
	v_lshl_add_u64 v[8:9], v[6:7], 0, s[22:23]
	global_load_lds_dwordx4 v138, s[2:3]
	s_mov_b32 m0, s71
	s_add_i32 s34, s70, 0x4000
	global_load_lds_dwordx4 v[8:9], off sc1
	v_lshl_add_u64 v[8:9], v[6:7], 0, s[24:25]
	s_mov_b32 m0, s34
	s_add_i32 s35, s70, 0x6000
	global_load_lds_dwordx4 v[8:9], off sc1
	v_lshl_add_u64 v[8:9], v[6:7], 0, s[26:27]
	s_mov_b32 m0, s35
	v_writelane_b32 v251, s36, 52
	global_load_lds_dwordx4 v[8:9], off sc1
	s_nop 0
	v_writelane_b32 v251, s37, 53
	v_writelane_b32 v251, s88, 54
	s_ashr_i32 s0, s8, 2
	s_cmp_eq_u32 s0, 1
	v_writelane_b32 v251, s89, 55
	v_writelane_b32 v251, s4, 44
	v_writelane_b32 v251, s5, 56
	s_cselect_b64 s[4:5], -1, 0
	s_mov_b32 s29, 0
	v_writelane_b32 v251, s4, 58
	s_cmp_lg_u32 s0, 1
	s_nop 0
	v_writelane_b32 v251, s5, 59
	s_cbranch_scc1 .LBB0_606
	s_barrier
.LBB0_606:
	s_add_u32 s4, s84, 0x9600000
	s_addc_u32 s5, s85, 0
	v_writelane_b32 v251, s4, 60
	s_mov_b64 s[92:93], 0x800
	v_lshl_add_u64 v[8:9], v[4:5], 0, s[92:93]
	v_writelane_b32 v251, s5, 61
	s_add_u32 s4, s84, 0xd612000
	s_addc_u32 s5, s85, 0
	v_writelane_b32 v251, s4, 62
	s_mov_b64 s[94:95], 0x40800
	s_waitcnt vmcnt(2)
	s_barrier
	v_writelane_b32 v251, s5, 63
	s_add_u32 s4, s86, 0x40000
	s_addc_u32 s5, s87, 0
	s_add_i32 m0, s70, 0x18000
	s_add_i32 s10, s70, 0x8000
	global_load_lds_dwordx4 v[8:9], off sc1
	v_lshl_add_u64 v[8:9], v[4:5], 0, s[94:95]
	s_add_i32 m0, s70, 0x1a000
	s_add_i32 s11, s70, 0xa000
	global_load_lds_dwordx4 v[8:9], off sc1
	v_lshl_add_u64 v[8:9], v[6:7], 0, s[92:93]
	s_mov_b32 m0, s10
	v_lshl_add_u64 v[6:7], v[6:7], 0, s[94:95]
	global_load_lds_dwordx4 v[8:9], off sc1
	s_mov_b32 m0, s11
	s_mov_b64 s[96:97], 0x80800
	global_load_lds_dwordx4 v[6:7], off sc1
	v_lshl_add_u64 v[6:7], v[4:5], 0, s[96:97]
	s_add_i32 m0, s70, 0x1c000
	s_mov_b64 s[88:89], 0xc0800
	global_load_lds_dwordx4 v[6:7], off sc1
	v_lshl_add_u64 v[4:5], v[4:5], 0, s[88:89]
	s_add_i32 m0, s70, 0x1e000
	v_lshrrev_b32_e32 v3, 1, v0
	global_load_lds_dwordx4 v[4:5], off sc1
	v_writelane_b32 v250, s4, 0
	v_and_b32_e32 v143, 15, v0
	v_and_b32_e32 v4, 24, v3
	v_and_b32_e32 v3, 48, v0
	v_lshlrev_b32_e32 v6, 2, v0
	v_writelane_b32 v250, s5, 1
	s_lshl_b32 s4, s0, 6
	v_lshl_or_b32 v5, v143, 6, v3
	s_lshl_b32 s0, s0, 13
	v_and_b32_e32 v6, 32, v6
	s_and_b32 s1, s8, 3
	v_bitop3_b32 v5, v5, s0, v6 bitop3:0xde
	v_lshlrev_b32_e32 v6, 6, v0
	s_movk_i32 s0, 0x3c0
	s_lshl_b32 s6, s1, 5
	v_and_or_b32 v6, v6, s0, v3
	s_lshl_b32 s0, s1, 12
	s_cmp_lt_u32 s8, 4
	v_writelane_b32 v250, s4, 2
	s_cselect_b64 s[12:13], -1, 0
	v_and_b32_e32 v7, 32, v1
	v_writelane_b32 v250, s12, 3
	v_bitop3_b32 v168, s0, v6, v7 bitop3:0xf6
	s_and_b32 s0, s8, -4
	v_writelane_b32 v250, s13, 4
	v_writelane_b32 v250, s0, 5
	s_lshl_b32 s0, s8, 6
	v_or3_b32 v170, s0, v3, v143
	s_movk_i32 s0, 0x100
	v_cmp_gt_i32_e64 s[8:9], s0, v170
	s_cmp_lt_u32 s1, 2
	v_or_b32_e32 v6, s6, v4
	v_writelane_b32 v250, s8, 6
	v_lshlrev_b32_e32 v140, 2, v6
	v_or_b32_e32 v169, 0xfffff000, v6
	v_writelane_b32 v250, s9, 7
	v_cmp_eq_u32_e64 s[8:9], 0, v170
	v_lshl_add_u64 v[6:7], s[86:87], 0, v[140:141]
	v_mov_b32_e32 v3, v141
	v_writelane_b32 v250, s8, 8
	v_lshl_add_u64 v[2:3], s[86:87], 0, v[2:3]
	s_waitcnt vmcnt(6)
	v_cmp_gt_u32_e64 s[4:5], 64, v0
	v_writelane_b32 v250, s9, 9
	s_cselect_b64 s[8:9], -1, 0
	v_writelane_b32 v250, s8, 10
	s_lshl_b32 s0, s1, 1
	s_mov_b32 s1, s29
	v_writelane_b32 v250, s9, 11
	v_writelane_b32 v250, s0, 12
	v_add_u32_e32 v142, -13, v143
	v_mov_b64_e32 v[150:151], 0xa92
	v_writelane_b32 v250, s1, 13
	v_cmp_lt_u32_e64 s[0:1], 12, v143
	v_mov_b64_e32 v[152:153], 0xa91
	v_mov_b32_e32 v172, 1
	v_writelane_b32 v250, s0, 14
	s_add_i32 s78, 0, 0x10000
	s_add_i32 s79, 0, 0x14000
	v_writelane_b32 v250, s1, 15
	v_readlane_b32 s0, v251, 46
	s_ashr_i32 s0, s0, 31
	v_add_u32_e32 v173, 0, v5
	v_writelane_b32 v250, s0, 16
	s_mov_b32 s0, s82
	v_writelane_b32 v251, s0, 24
	v_mov_b32_e32 v174, 0x358637bd
	s_mov_b32 s33, 0x800000
	v_writelane_b32 v251, s1, 25
	s_ashr_i32 s0, s82, 31
	v_writelane_b32 v250, s0, 17
	s_mov_b64 s[0:1], 0x44000000
	v_lshl_add_u64 v[144:145], v[6:7], 0, s[0:1]
	s_mov_b64 s[0:1], 0xea00000
	v_lshl_add_u64 v[146:147], v[2:3], 0, s[0:1]
	s_add_i32 s0, 0, 0x22800
	v_lshl_add_u32 v171, v170, 2, s0
	v_readlane_b32 s52, v251, 26
	s_add_i32 s0, 0, 0x22c00
	v_readlane_b32 s53, v251, 27
	v_readlane_b32 s54, v251, 28
	v_readlane_b32 s55, v251, 29
	v_readlane_b32 s56, v251, 30
	v_readlane_b32 s57, v251, 31
	v_readlane_b32 s58, v251, 32
	v_readlane_b32 s59, v251, 33
	v_readlane_b32 s60, v251, 34
	v_readlane_b32 s61, v251, 35
	v_readlane_b32 s62, v251, 36
	v_readlane_b32 s63, v251, 37
	v_readlane_b32 s64, v251, 38
	v_readlane_b32 s65, v251, 39
	v_readlane_b32 s66, v251, 40
	v_readlane_b32 s67, v251, 41
	v_writelane_b32 v251, s0, 50
	s_lshl_b32 s0, s6, 1
	v_lshl_add_u64 v[148:149], s[54:55], 0, v[140:141]
	s_mov_b32 s65, 0xbfb8aa3b
	s_mov_b32 s64, 0x3a83126f
	s_mov_b32 s82, 0x3f317217
	s_mov_b32 s83, 0x7f800000
	s_mov_b32 s52, 0xbeaaaaab
	v_writelane_b32 v250, s0, 18
	v_lshlrev_b32_e32 v140, 1, v4
	v_mov_b64_e32 v[154:155], 0x1e8481
	v_mov_b32_e32 v175, 0x41b17218
	s_mov_b32 s55, 0
	s_barrier
	v_writelane_b32 v250, s1, 19
	s_branch .LBB0_609

; #define PG8_STAGE(bufoff, gbase, voff) do { if constexpr (!pg8_noload<Epi>::value) { _Pragma("unroll") for (int _i = 0; _i < 2; ++_i) \
;         __builtin_amdgcn_global_load_lds((const unsigned*)((const char*)(gbase) + (size_t)_i * pstep + (voff)[0]), (PG8_LAS unsigned*)(lds + (bufoff) + ldsw + _i * 8192), 16, 0, 0); } } while (0)
; #define PG8_LDA(dst, b, h) do { _Pragma("unroll") for (int m = 0; m < 4; ++m) _Pragma("unroll") for (int k = 0; k < 2; ++k) dst[m][k] = *(const PG8_LAS bf16x8*)(lds + PG8_SA(b, h) + aoff + m * 2048 + k * 1024); } while (0)
; #define PG8_LDB(dst, b, h) do { _Pragma("unroll") for (int n = 0; n < 2; ++n) _Pragma("unroll") for (int k = 0; k < 2; ++k) dst[n][k] = *(const PG8_LAS bf16x8*)(lds + PG8_SB(b, h) + boff + n * 2048 + k * 1024); } while (0)
; #define PG8_WAIT_V(n) asm volatile("s_waitcnt vmcnt(" #n ")" ::: "memory")
; #define PG8_WAIT_L(n) asm volatile("s_waitcnt lgkmcnt(" #n ")" ::: "memory")
; #define PG8_BAR __builtin_amdgcn_s_barrier()
; template <class Epi, class Sched, bool ALIGN_EPI = false, bool SP2 = false, bool ABLK = false>
; __device__ __forceinline__ void gemm_phase(PG8_LAS unsigned char* lds, const Gemm g, const Sched& S, const Epi& E) {
;     ...
;         const char* nA = has_next ? (const char*)g.A + (size_t)nxt.pm * tstep + (size_t)nxt.ko * KOA : cA; const char* nB = has_next ? (const char*)g.Bt + (size_t)nxt.pn * tstep + (size_t)nxt.ko * 32 : cB;
;         for (int t = 0; t < nt; t += 2) {
;             const bool last = (t == nt - 2);
;             const char* a1 = cA + (size_t)(t + 1) * kstep;
;             const char* a2 = last ? nA : cA + (size_t)(t + 2) * kstep; const char* b2 = last ? nB : cB + (size_t)(t + 2) * kstepB;
;             const char* a3 = a2 + kstep; const char* b3 = b2 + kstepB;
;             if (last && has_next) S.a_ready(nxt);
;             if constexpr (SP2) {
;             PG8_LDB(B0, 0, 0); PG8_LDB(B1, 0, 1); PG8_SCHED; PG8_LDA(At, 0, 0); PG8_STAGE(PG8_SA(1, 1), a1 + hstep, voffA);
;             PG8_WAIT_V(8); PG8_WAIT_L(0); PG8_BAR; PG8_MMA(0, 0, At, B0); PG8_MMA(0, 1, At, B1); PG8_BAR; PG8_SCHED;
;             PG8_LDA(At, 0, 1); PG8_STAGE(PG8_SB(0, 0), b2, voffB); PG8_STAGE(PG8_SB(0, 1), b2 + hstep, voffB); PG8_STAGE(PG8_SA(0, 0), a2, voffA);
;             PG8_WAIT_V(8); PG8_WAIT_L(0); PG8_BAR; PG8_MMA(1, 0, At, B0); PG8_MMA(1, 1, At, B1); PG8_BAR; PG8_SCHED;
.LBB0_619:
	s_or_b32 s28, s57, 1
	s_lshl_b64 s[58:59], s[28:29], 11
	s_add_u32 s58, s2, s58
	s_addc_u32 s59, s3, s59
	s_add_i32 s28, s57, 2
	v_add_u32_e32 v160, s78, v168
	v_add_u32_e32 v180, s79, v168
	s_lshl_b64 s[60:61], s[28:29], 11
	ds_read_b128 v[130:133], v160
	ds_read_b128 v[134:137], v160 offset:1024
	ds_read_b128 v[156:159], v160 offset:2048
	ds_read_b128 v[160:163], v160 offset:3072
	ds_read_b128 v[164:167], v180
	ds_read_b128 v[176:179], v180 offset:1024
	ds_read_b128 v[184:187], v180 offset:2048
	ds_read_b128 v[188:191], v180 offset:3072
	s_add_u32 s66, s2, s60
	s_addc_u32 s67, s3, s61
	s_and_b64 s[62:63], s[68:69], exec
	s_cselect_b32 s73, s67, s7
	s_cselect_b32 s72, s66, s15
	s_add_u32 s62, s16, s60
	s_addc_u32 s63, s17, s61
	s_and_b64 s[60:61], s[68:69], exec
	s_cselect_b32 s61, s63, s9
	s_cselect_b32 s60, s62, s56
	v_lshl_add_u64 v[180:181], s[58:59], 0, v[138:139]
	v_lshl_add_u64 v[224:225], v[180:181], 0, s[24:25]
	s_add_i32 m0, s70, 0xc000
	ds_read_b128 v[192:195], v173
	ds_read_b128 v[196:199], v173 offset:1024
	ds_read_b128 v[200:203], v173 offset:2048
	ds_read_b128 v[204:207], v173 offset:3072
	ds_read_b128 v[208:211], v173 offset:4096
	ds_read_b128 v[212:215], v173 offset:5120
	ds_read_b128 v[216:219], v173 offset:6144
	ds_read_b128 v[220:223], v173 offset:7168
	global_load_lds_dwordx4 v[224:225], off sc1
	v_lshl_add_u64 v[180:181], v[180:181], 0, s[26:27]
	s_add_i32 m0, s70, 0xe000
	s_nop 0
	global_load_lds_dwordx4 v[180:181], off sc1
	s_waitcnt vmcnt(8)
	s_waitcnt lgkmcnt(0)
	s_barrier
	s_setprio 1
	s_waitcnt lgkmcnt(0)
	v_mfma_f32_16x16x32_bf16 v[126:129], v[130:133], v[192:195], v[126:129]
	v_mfma_f32_16x16x32_bf16 v[126:129], v[134:137], v[196:199], v[126:129]
	v_mfma_f32_16x16x32_bf16 v[110:113], v[134:137], v[204:207], v[110:113]
	v_mfma_f32_16x16x32_bf16 v[110:113], v[130:133], v[200:203], v[110:113]
	v_mfma_f32_16x16x32_bf16 v[94:97], v[130:133], v[208:211], v[94:97]
	v_mfma_f32_16x16x32_bf16 v[94:97], v[134:137], v[212:215], v[94:97]
	v_mfma_f32_16x16x32_bf16 v[78:81], v[134:137], v[220:223], v[78:81]
	v_mfma_f32_16x16x32_bf16 v[78:81], v[130:133], v[216:219], v[78:81]
	v_mfma_f32_16x16x32_bf16 v[74:77], v[156:159], v[216:219], v[74:77]
	v_mfma_f32_16x16x32_bf16 v[74:77], v[160:163], v[220:223], v[74:77]
	v_mfma_f32_16x16x32_bf16 v[90:93], v[160:163], v[212:215], v[90:93]
	v_mfma_f32_16x16x32_bf16 v[90:93], v[156:159], v[208:211], v[90:93]
	v_mfma_f32_16x16x32_bf16 v[106:109], v[156:159], v[200:203], v[106:109]
	v_mfma_f32_16x16x32_bf16 v[106:109], v[160:163], v[204:207], v[106:109]
	v_mfma_f32_16x16x32_bf16 v[122:125], v[160:163], v[196:199], v[122:125]
	v_mfma_f32_16x16x32_bf16 v[122:125], v[156:159], v[192:195], v[122:125]
	v_mfma_f32_16x16x32_bf16 v[118:121], v[164:167], v[192:195], v[118:121]
	v_mfma_f32_16x16x32_bf16 v[118:121], v[176:179], v[196:199], v[118:121]
	v_mfma_f32_16x16x32_bf16 v[102:105], v[176:179], v[204:207], v[102:105]
	v_mfma_f32_16x16x32_bf16 v[102:105], v[164:167], v[200:203], v[102:105]
	v_mfma_f32_16x16x32_bf16 v[86:89], v[164:167], v[208:211], v[86:89]
	v_mfma_f32_16x16x32_bf16 v[86:89], v[176:179], v[212:215], v[86:89]
	v_mfma_f32_16x16x32_bf16 v[70:73], v[176:179], v[220:223], v[70:73]
	v_mfma_f32_16x16x32_bf16 v[70:73], v[164:167], v[216:219], v[70:73]
	v_mfma_f32_16x16x32_bf16 v[66:69], v[184:187], v[216:219], v[66:69]
	v_mfma_f32_16x16x32_bf16 v[66:69], v[188:191], v[220:223], v[66:69]
	v_mfma_f32_16x16x32_bf16 v[82:85], v[188:191], v[212:215], v[82:85]
	v_mfma_f32_16x16x32_bf16 v[82:85], v[184:187], v[208:211], v[82:85]
	s_barrier
	s_setprio 2
	v_mfma_f32_16x16x32_bf16 v[98:101], v[184:187], v[200:203], v[98:101]
	v_mfma_f32_16x16x32_bf16 v[98:101], v[188:191], v[204:207], v[98:101]
	v_mfma_f32_16x16x32_bf16 v[114:117], v[188:191], v[196:199], v[114:117]
	v_mfma_f32_16x16x32_bf16 v[114:117], v[184:187], v[192:195], v[114:117]
	s_setprio 0
	s_add_i32 s58, s78, s91
	v_lshl_add_u64 v[180:181], s[60:61], 0, v[138:139]
	s_mov_b32 m0, s58
	ds_read_b128 v[192:195], v173 offset:16384
	ds_read_b128 v[196:199], v173 offset:17408
	ds_read_b128 v[200:203], v173 offset:18432
	ds_read_b128 v[204:207], v173 offset:19456
	ds_read_b128 v[208:211], v173 offset:20480
	ds_read_b128 v[212:215], v173 offset:21504
	ds_read_b128 v[216:219], v173 offset:22528
	ds_read_b128 v[220:223], v173 offset:23552
	global_load_lds_dwordx4 v[180:181], off sc1
	v_lshl_add_u64 v[224:225], v[180:181], 0, s[22:23]
	s_add_i32 m0, s58, 0x2000
	s_add_i32 s58, s79, s91
	global_load_lds_dwordx4 v[224:225], off sc1
	v_lshl_add_u64 v[224:225], v[180:181], 0, s[24:25]
	s_mov_b32 m0, s58
	s_nop 0
	global_load_lds_dwordx4 v[224:225], off sc1
	v_lshl_add_u64 v[224:225], v[180:181], 0, s[26:27]
	s_add_i32 m0, s58, 0x2000
	s_nop 0
	global_load_lds_dwordx4 v[224:225], off sc1
	v_lshl_add_u64 v[224:225], s[72:73], 0, v[138:139]
	s_mov_b32 m0, s70
	v_lshl_add_u64 v[226:227], v[224:225], 0, s[22:23]
	global_load_lds_dwordx4 v[224:225], off sc1
	s_mov_b32 m0, s71
	s_nop 0
	global_load_lds_dwordx4 v[226:227], off sc1
	s_waitcnt vmcnt(8)
	s_waitcnt lgkmcnt(0)
	s_barrier
; #define PG8_STAGE(bufoff, gbase, voff) do { if constexpr (!pg8_noload<Epi>::value) { _Pragma("unroll") for (int _i = 0; _i < 2; ++_i) \
;         __builtin_amdgcn_global_load_lds((const unsigned*)((const char*)(gbase) + (size_t)_i * pstep + (voff)[0]), (PG8_LAS unsigned*)(lds + (bufoff) + ldsw + _i * 8192), 16, 0, 0); } } while (0)
; #define PG8_LDA(dst, b, h) do { _Pragma("unroll") for (int m = 0; m < 4; ++m) _Pragma("unroll") for (int k = 0; k < 2; ++k) dst[m][k] = *(const PG8_LAS bf16x8*)(lds + PG8_SA(b, h) + aoff + m * 2048 + k * 1024); } while (0)
; #define PG8_LDB(dst, b, h) do { _Pragma("unroll") for (int n = 0; n < 2; ++n) _Pragma("unroll") for (int k = 0; k < 2; ++k) dst[n][k] = *(const PG8_LAS bf16x8*)(lds + PG8_SB(b, h) + boff + n * 2048 + k * 1024); } while (0)
; #define PG8_MMA(ai, bj, At, Bt) do { __builtin_amdgcn_s_setprio(1); _Pragma("unroll") for (int m = 0; m < 4; ++m) _Pragma("unroll") for (int n = 0; n < 2; ++n) _Pragma("unroll") for (int k = 0; k < 2; ++k) \
;         acc[ai][bj][m][n] = __builtin_amdgcn_mfma_f32_16x16x32_bf16(Bt[n][k], At[m][k], acc[ai][bj][m][n], 0, 0, 0); __builtin_amdgcn_s_setprio(0); } while (0)
; #define PG8_WAIT_V(n) asm volatile("s_waitcnt vmcnt(" #n ")" ::: "memory")
; #define PG8_WAIT_L(n) asm volatile("s_waitcnt lgkmcnt(" #n ")" ::: "memory")
; #define PG8_BAR __builtin_amdgcn_s_barrier()
; #define PG8_SCHED __builtin_amdgcn_sched_barrier(0)
; template <class Epi, class Sched, bool ALIGN_EPI = false, bool SP2 = false, bool ABLK = false>
; __device__ __forceinline__ void gemm_phase(PG8_LAS unsigned char* lds, const Gemm g, const Sched& S, const Epi& E) {
;     ...
;             PG8_WAIT_V(8); PG8_WAIT_L(0); PG8_BAR; PG8_MMA(1, 0, At, B0); PG8_MMA(1, 1, At, B1); PG8_BAR; PG8_SCHED;
;             PG8_LDB(B0, 1, 0); PG8_LDB(B1, 1, 1); PG8_SCHED; PG8_LDA(At, 1, 0); PG8_STAGE(PG8_SA(0, 1), a2 + hstep, voffA);
;             PG8_WAIT_V(8); PG8_WAIT_L(0); PG8_BAR; PG8_MMA(0, 0, At, B0); PG8_MMA(0, 1, At, B1); PG8_BAR; PG8_SCHED;
	s_setprio 1
	s_waitcnt lgkmcnt(0)
	v_mfma_f32_16x16x32_bf16 v[62:65], v[130:133], v[192:195], v[62:65]
	v_mfma_f32_16x16x32_bf16 v[62:65], v[134:137], v[196:199], v[62:65]
	v_mfma_f32_16x16x32_bf16 v[46:49], v[134:137], v[204:207], v[46:49]
	v_mfma_f32_16x16x32_bf16 v[46:49], v[130:133], v[200:203], v[46:49]
	v_mfma_f32_16x16x32_bf16 v[30:33], v[130:133], v[208:211], v[30:33]
	v_mfma_f32_16x16x32_bf16 v[30:33], v[134:137], v[212:215], v[30:33]
	v_mfma_f32_16x16x32_bf16 v[14:17], v[134:137], v[220:223], v[14:17]
	v_mfma_f32_16x16x32_bf16 v[14:17], v[130:133], v[216:219], v[14:17]
	v_mfma_f32_16x16x32_bf16 v[10:13], v[156:159], v[216:219], v[10:13]
	v_mfma_f32_16x16x32_bf16 v[10:13], v[160:163], v[220:223], v[10:13]
	v_mfma_f32_16x16x32_bf16 v[26:29], v[160:163], v[212:215], v[26:29]
	v_mfma_f32_16x16x32_bf16 v[26:29], v[156:159], v[208:211], v[26:29]
	v_mfma_f32_16x16x32_bf16 v[42:45], v[156:159], v[200:203], v[42:45]
	v_mfma_f32_16x16x32_bf16 v[42:45], v[160:163], v[204:207], v[42:45]
	v_mfma_f32_16x16x32_bf16 v[58:61], v[160:163], v[196:199], v[58:61]
	v_mfma_f32_16x16x32_bf16 v[58:61], v[156:159], v[192:195], v[58:61]
	v_mfma_f32_16x16x32_bf16 v[54:57], v[164:167], v[192:195], v[54:57]
	v_mfma_f32_16x16x32_bf16 v[54:57], v[176:179], v[196:199], v[54:57]
	v_mfma_f32_16x16x32_bf16 v[38:41], v[176:179], v[204:207], v[38:41]
	v_mfma_f32_16x16x32_bf16 v[38:41], v[164:167], v[200:203], v[38:41]
	v_mfma_f32_16x16x32_bf16 v[22:25], v[164:167], v[208:211], v[22:25]
	v_mfma_f32_16x16x32_bf16 v[22:25], v[176:179], v[212:215], v[22:25]
	v_mfma_f32_16x16x32_bf16 v[6:9], v[176:179], v[220:223], v[6:9]
	v_mfma_f32_16x16x32_bf16 v[6:9], v[164:167], v[216:219], v[6:9]
	v_mfma_f32_16x16x32_bf16 v[2:5], v[184:187], v[216:219], v[2:5]
	v_mfma_f32_16x16x32_bf16 v[2:5], v[188:191], v[220:223], v[2:5]
	v_mfma_f32_16x16x32_bf16 v[18:21], v[188:191], v[212:215], v[18:21]
	v_mfma_f32_16x16x32_bf16 v[18:21], v[184:187], v[208:211], v[18:21]
	s_barrier
	s_setprio 2
	v_mfma_f32_16x16x32_bf16 v[34:37], v[184:187], v[200:203], v[34:37]
	v_mfma_f32_16x16x32_bf16 v[34:37], v[188:191], v[204:207], v[34:37]
	v_mfma_f32_16x16x32_bf16 v[50:53], v[188:191], v[196:199], v[50:53]
	v_mfma_f32_16x16x32_bf16 v[50:53], v[184:187], v[192:195], v[50:53]
	s_setprio 0
	s_add_i32 s58, 0, 0x18000
	s_add_i32 s59, 0, 0x1c000
	v_add_u32_e32 v160, s58, v168
	v_add_u32_e32 v188, s59, v168
	ds_read_b128 v[130:133], v160
	ds_read_b128 v[134:137], v160 offset:1024
	ds_read_b128 v[156:159], v160 offset:2048
	ds_read_b128 v[160:163], v160 offset:3072
	ds_read_b128 v[164:167], v188
	ds_read_b128 v[176:179], v188 offset:1024
	ds_read_b128 v[184:187], v188 offset:2048
	ds_read_b128 v[188:191], v188 offset:3072
	s_mov_b32 m0, s34
	v_lshl_add_u64 v[226:227], v[224:225], 0, s[24:25]
	ds_read_b128 v[192:195], v173 offset:32768
	ds_read_b128 v[196:199], v173 offset:33792
	ds_read_b128 v[200:203], v173 offset:34816
	ds_read_b128 v[204:207], v173 offset:35840
	ds_read_b128 v[208:211], v173 offset:36864
	ds_read_b128 v[212:215], v173 offset:37888
	ds_read_b128 v[216:219], v173 offset:38912
	ds_read_b128 v[220:223], v173 offset:39936
	global_load_lds_dwordx4 v[226:227], off sc1
	v_lshl_add_u64 v[226:227], v[224:225], 0, s[26:27]
	s_mov_b32 m0, s35
	s_nop 0
	global_load_lds_dwordx4 v[226:227], off sc1
	s_waitcnt vmcnt(8)
	s_waitcnt lgkmcnt(0)
	s_barrier
	s_setprio 1
	s_waitcnt lgkmcnt(0)
	v_mfma_f32_16x16x32_bf16 v[126:129], v[130:133], v[192:195], v[126:129]
	v_mfma_f32_16x16x32_bf16 v[126:129], v[134:137], v[196:199], v[126:129]
	v_mfma_f32_16x16x32_bf16 v[110:113], v[134:137], v[204:207], v[110:113]
	v_mfma_f32_16x16x32_bf16 v[110:113], v[130:133], v[200:203], v[110:113]
	v_mfma_f32_16x16x32_bf16 v[94:97], v[130:133], v[208:211], v[94:97]
	v_mfma_f32_16x16x32_bf16 v[94:97], v[134:137], v[212:215], v[94:97]
	v_mfma_f32_16x16x32_bf16 v[78:81], v[134:137], v[220:223], v[78:81]
	v_mfma_f32_16x16x32_bf16 v[78:81], v[130:133], v[216:219], v[78:81]
	v_mfma_f32_16x16x32_bf16 v[74:77], v[156:159], v[216:219], v[74:77]
	v_mfma_f32_16x16x32_bf16 v[74:77], v[160:163], v[220:223], v[74:77]
	v_mfma_f32_16x16x32_bf16 v[90:93], v[160:163], v[212:215], v[90:93]
	v_mfma_f32_16x16x32_bf16 v[90:93], v[156:159], v[208:211], v[90:93]
	v_mfma_f32_16x16x32_bf16 v[106:109], v[156:159], v[200:203], v[106:109]
	v_mfma_f32_16x16x32_bf16 v[106:109], v[160:163], v[204:207], v[106:109]
	v_mfma_f32_16x16x32_bf16 v[122:125], v[160:163], v[196:199], v[122:125]
	v_mfma_f32_16x16x32_bf16 v[122:125], v[156:159], v[192:195], v[122:125]
	v_mfma_f32_16x16x32_bf16 v[118:121], v[164:167], v[192:195], v[118:121]
	v_mfma_f32_16x16x32_bf16 v[118:121], v[176:179], v[196:199], v[118:121]
	v_mfma_f32_16x16x32_bf16 v[102:105], v[176:179], v[204:207], v[102:105]
	v_mfma_f32_16x16x32_bf16 v[102:105], v[164:167], v[200:203], v[102:105]
	v_mfma_f32_16x16x32_bf16 v[86:89], v[164:167], v[208:211], v[86:89]
	v_mfma_f32_16x16x32_bf16 v[86:89], v[176:179], v[212:215], v[86:89]
	v_mfma_f32_16x16x32_bf16 v[70:73], v[176:179], v[220:223], v[70:73]
	v_mfma_f32_16x16x32_bf16 v[70:73], v[164:167], v[216:219], v[70:73]
	v_mfma_f32_16x16x32_bf16 v[66:69], v[184:187], v[216:219], v[66:69]
	v_mfma_f32_16x16x32_bf16 v[66:69], v[188:191], v[220:223], v[66:69]
	v_mfma_f32_16x16x32_bf16 v[82:85], v[188:191], v[212:215], v[82:85]
	v_mfma_f32_16x16x32_bf16 v[82:85], v[184:187], v[208:211], v[82:85]
	s_barrier
; #define PG8_STAGE(bufoff, gbase, voff) do { if constexpr (!pg8_noload<Epi>::value) { _Pragma("unroll") for (int _i = 0; _i < 2; ++_i) \
;         __builtin_amdgcn_global_load_lds((const unsigned*)((const char*)(gbase) + (size_t)_i * pstep + (voff)[0]), (PG8_LAS unsigned*)(lds + (bufoff) + ldsw + _i * 8192), 16, 0, 0); } } while (0)
; #define PG8_LDA(dst, b, h) do { _Pragma("unroll") for (int m = 0; m < 4; ++m) _Pragma("unroll") for (int k = 0; k < 2; ++k) dst[m][k] = *(const PG8_LAS bf16x8*)(lds + PG8_SA(b, h) + aoff + m * 2048 + k * 1024); } while (0)
; #define PG8_MMA(ai, bj, At, Bt) do { __builtin_amdgcn_s_setprio(1); _Pragma("unroll") for (int m = 0; m < 4; ++m) _Pragma("unroll") for (int n = 0; n < 2; ++n) _Pragma("unroll") for (int k = 0; k < 2; ++k) \
;         acc[ai][bj][m][n] = __builtin_amdgcn_mfma_f32_16x16x32_bf16(Bt[n][k], At[m][k], acc[ai][bj][m][n], 0, 0, 0); __builtin_amdgcn_s_setprio(0); } while (0)
; #define PG8_WAIT_V(n) asm volatile("s_waitcnt vmcnt(" #n ")" ::: "memory")
; #define PG8_WAIT_L(n) asm volatile("s_waitcnt lgkmcnt(" #n ")" ::: "memory")
; #define PG8_BAR __builtin_amdgcn_s_barrier()
; #define PG8_SCHED __builtin_amdgcn_sched_barrier(0)
; template <class Epi, class Sched, bool ALIGN_EPI = false, bool SP2 = false, bool ABLK = false>
; __device__ __forceinline__ void gemm_phase(PG8_LAS unsigned char* lds, const Gemm g, const Sched& S, const Epi& E) {
;     ...
;             PG8_WAIT_V(8); PG8_WAIT_L(0); PG8_BAR; PG8_MMA(0, 0, At, B0); PG8_MMA(0, 1, At, B1); PG8_BAR; PG8_SCHED;
;             PG8_LDA(At, 1, 1); PG8_STAGE(PG8_SB(1, 0), b3, voffB); PG8_STAGE(PG8_SB(1, 1), b3 + hstep, voffB); PG8_STAGE(PG8_SA(1, 0), a3, voffA);
;             PG8_WAIT_V(8); PG8_WAIT_L(0); PG8_BAR; PG8_MMA(1, 0, At, B0); PG8_MMA(1, 1, At, B1); PG8_BAR; PG8_SCHED;
	s_setprio 2
	v_mfma_f32_16x16x32_bf16 v[98:101], v[184:187], v[200:203], v[98:101]
	v_mfma_f32_16x16x32_bf16 v[98:101], v[188:191], v[204:207], v[98:101]
	v_mfma_f32_16x16x32_bf16 v[114:117], v[188:191], v[196:199], v[114:117]
	v_mfma_f32_16x16x32_bf16 v[114:117], v[184:187], v[192:195], v[114:117]
	s_setprio 0
	s_add_i32 s58, s58, s91
	v_lshl_add_u64 v[226:227], v[180:181], 0, s[92:93]
	s_mov_b32 m0, s58
	ds_read_b128 v[192:195], v173 offset:49152
	ds_read_b128 v[196:199], v173 offset:50176
	ds_read_b128 v[200:203], v173 offset:51200
	ds_read_b128 v[204:207], v173 offset:52224
	ds_read_b128 v[208:211], v173 offset:53248
	ds_read_b128 v[212:215], v173 offset:54272
	ds_read_b128 v[216:219], v173 offset:55296
	ds_read_b128 v[220:223], v173 offset:56320
	global_load_lds_dwordx4 v[226:227], off sc1
	v_lshl_add_u64 v[226:227], v[180:181], 0, s[94:95]
	s_add_i32 m0, s58, 0x2000
	s_add_i32 s58, s59, s91
	global_load_lds_dwordx4 v[226:227], off sc1
	v_lshl_add_u64 v[226:227], v[180:181], 0, s[96:97]
	s_mov_b32 m0, s58
	v_lshl_add_u64 v[180:181], v[180:181], 0, s[88:89]
	global_load_lds_dwordx4 v[226:227], off sc1
	s_add_i32 m0, s58, 0x2000
	s_nop 0
	global_load_lds_dwordx4 v[180:181], off sc1
	v_lshl_add_u64 v[180:181], v[224:225], 0, s[92:93]
	s_mov_b32 m0, s10
	s_nop 0
	global_load_lds_dwordx4 v[180:181], off sc1
	v_lshl_add_u64 v[180:181], v[224:225], 0, s[94:95]
	s_mov_b32 m0, s11
	s_nop 0
	global_load_lds_dwordx4 v[180:181], off sc1
	s_waitcnt vmcnt(8)
	s_waitcnt lgkmcnt(0)
	s_barrier
	s_setprio 1
	s_waitcnt lgkmcnt(0)
	v_mfma_f32_16x16x32_bf16 v[62:65], v[130:133], v[192:195], v[62:65]
	v_mfma_f32_16x16x32_bf16 v[62:65], v[134:137], v[196:199], v[62:65]
	v_mfma_f32_16x16x32_bf16 v[46:49], v[134:137], v[204:207], v[46:49]
	v_mfma_f32_16x16x32_bf16 v[46:49], v[130:133], v[200:203], v[46:49]
	v_mfma_f32_16x16x32_bf16 v[30:33], v[130:133], v[208:211], v[30:33]
	v_mfma_f32_16x16x32_bf16 v[30:33], v[134:137], v[212:215], v[30:33]
	v_mfma_f32_16x16x32_bf16 v[14:17], v[134:137], v[220:223], v[14:17]
	v_mfma_f32_16x16x32_bf16 v[14:17], v[130:133], v[216:219], v[14:17]
	v_mfma_f32_16x16x32_bf16 v[10:13], v[156:159], v[216:219], v[10:13]
	v_mfma_f32_16x16x32_bf16 v[10:13], v[160:163], v[220:223], v[10:13]
	v_mfma_f32_16x16x32_bf16 v[26:29], v[160:163], v[212:215], v[26:29]
	v_mfma_f32_16x16x32_bf16 v[26:29], v[156:159], v[208:211], v[26:29]
	v_mfma_f32_16x16x32_bf16 v[42:45], v[156:159], v[200:203], v[42:45]
	v_mfma_f32_16x16x32_bf16 v[42:45], v[160:163], v[204:207], v[42:45]
	v_mfma_f32_16x16x32_bf16 v[58:61], v[160:163], v[196:199], v[58:61]
	v_mfma_f32_16x16x32_bf16 v[58:61], v[156:159], v[192:195], v[58:61]
	v_mfma_f32_16x16x32_bf16 v[54:57], v[164:167], v[192:195], v[54:57]
	v_mfma_f32_16x16x32_bf16 v[54:57], v[176:179], v[196:199], v[54:57]
	v_mfma_f32_16x16x32_bf16 v[38:41], v[176:179], v[204:207], v[38:41]
	v_mfma_f32_16x16x32_bf16 v[38:41], v[164:167], v[200:203], v[38:41]
	v_mfma_f32_16x16x32_bf16 v[22:25], v[164:167], v[208:211], v[22:25]
	v_mfma_f32_16x16x32_bf16 v[22:25], v[176:179], v[212:215], v[22:25]
	v_mfma_f32_16x16x32_bf16 v[6:9], v[176:179], v[220:223], v[6:9]
	v_mfma_f32_16x16x32_bf16 v[6:9], v[164:167], v[216:219], v[6:9]
	v_mfma_f32_16x16x32_bf16 v[2:5], v[184:187], v[216:219], v[2:5]
	v_mfma_f32_16x16x32_bf16 v[2:5], v[188:191], v[220:223], v[2:5]
	v_mfma_f32_16x16x32_bf16 v[18:21], v[188:191], v[212:215], v[18:21]
	v_mfma_f32_16x16x32_bf16 v[18:21], v[184:187], v[208:211], v[18:21]
	s_barrier
	s_setprio 2
	v_mfma_f32_16x16x32_bf16 v[34:37], v[184:187], v[200:203], v[34:37]
	v_mfma_f32_16x16x32_bf16 v[34:37], v[188:191], v[204:207], v[34:37]
	v_mfma_f32_16x16x32_bf16 v[50:53], v[188:191], v[196:199], v[50:53]
	v_mfma_f32_16x16x32_bf16 v[50:53], v[184:187], v[192:195], v[50:53]
	s_setprio 0
	s_cmp_gt_u32 s57, 29
	s_mov_b32 s57, s28
	s_cbranch_scc1 .LBB0_631

; #define PG8_WAIT_V(n) asm volatile("s_waitcnt vmcnt(" #n ")" ::: "memory")
; #define PG8_BAR __builtin_amdgcn_s_barrier()
; template <class Epi, class Sched, bool ALIGN_EPI = false, bool SP2 = false, bool ABLK = false>
; __device__ __forceinline__ void gemm_phase(PG8_LAS unsigned char* lds, const Gemm g, const Sched& S, const Epi& E) {
;     const int tid = threadIdx.x, wid = __builtin_amdgcn_readfirstlane(tid >> 6), lane = tid & 63, wr = wid >> 2, wc = wid & 3, fr = lane & 15, fq = lane >> 4;
;     const int K = g.K;
;     unsigned voffA[2], voffB[2];
; #pragma unroll
;     for (int i = 0; i < 2; ++i) { int R, C; stage_rc(tid * 16 + i * 8192, R, C); const int Rb = Epi::PERM ? ((R & ~31) + perm32(R & 31)) : R;
;         voffA[i] = (unsigned)(R * K + C) * 2u; (void)Rb;
;         if constexpr (ABLK) { const int st = (tid >> 6) + 8 * i; voffA[i] = (unsigned)(((st >> 1) * (K / 32) + (st & 1)) * 1024 + (tid & 63) * 16); }
;         { static_assert(Epi::PERM, "blocked weight copies are written in permuted row-slot order"); const int st = (tid >> 6) + 8 * i; voffB[i] = (unsigned)(((st >> 1) * (K / 32) + (st & 1)) * 1024 + (tid & 63) * 16); } }
;     const size_t kstep = ABLK ? (size_t)(BK / 32) * 1024 : (size_t)(BK * 2);
;     constexpr int KOA = ABLK ? 32 : 2;
;     const size_t pstep = (size_t)K * 128;
;     const size_t kstepB = (size_t)(BK / 32) * 1024;
;     const size_t hstep = (size_t)HALF * K * 2;
;     const size_t tstep = 2 * hstep;
;     const unsigned ldsw = (unsigned)wid * 1024u;
;     const int aoff = lds_byte(wr * 64 + fr, fq * 8), boff = lds_byte(wc * 32 + fr, fq * 8);
;     ...
;     const char* cA = (const char*)g.A + (size_t)cur.pm * tstep + (size_t)cur.ko * KOA; const char* cB = (const char*)g.Bt + (size_t)cur.pn * tstep + (size_t)cur.ko * 32; int nt = cur.nt;
;     S.a_ready(cur);
;     if constexpr (SP2) {
;         PG8_STAGE(PG8_SB(0, 0), cB, voffB); PG8_STAGE(PG8_SB(0, 1), cB + hstep, voffB); PG8_STAGE(PG8_SA(0, 0), cA, voffA); PG8_STAGE(PG8_SA(0, 1), cA + hstep, voffA);
;         if (wr == 1) PG8_BAR;
;         PG8_WAIT_V(2); PG8_BAR;
;         PG8_STAGE(PG8_SB(1, 0), cB + kstepB, voffB); PG8_STAGE(PG8_SA(1, 0), cA + kstep, voffA); PG8_STAGE(PG8_SB(1, 1), cB + hstep + kstepB, voffB);
;         PG8_WAIT_V(6); PG8_BAR;
.LBB0_1513:
	s_andn2_b64 vcc, exec, s[4:5]
	s_cbranch_vccnz .LBB0_1562
	s_add_u32 s33, s86, 0x27a00000
	s_addc_u32 s52, s87, 0
	s_add_u32 s53, s86, 0xb000000
	v_and_b32_e32 v6, 1, v183
	s_movk_i32 s3, 0x180
	s_addc_u32 s54, s87, 0
	v_and_or_b32 v1, v0, s3, v6
	s_ashr_i32 s3, s2, 31
	s_ashr_i32 s67, s66, 31
	s_ashr_i32 s11, s10, 31
	s_ashr_i32 s6, s8, 2
	s_lshl_b32 s55, s8, 10
	s_lshl_b64 s[4:5], s[2:3], 21
	s_lshl_b64 s[18:19], s[66:67], 5
	s_lshl_b64 s[12:13], s[10:11], 21
	s_add_u32 s3, s53, s12
	s_addc_u32 s7, s54, s13
	s_add_u32 s70, s3, s18
	v_lshlrev_b32_e32 v7, 4, v182
	s_addc_u32 s71, s7, s19
	s_add_i32 s56, s55, 0
	v_lshl_or_b32 v154, v1, 10, v7
	v_mov_b32_e32 v155, 0
	s_add_i32 m0, s56, 0x10000
	s_waitcnt lgkmcnt(0)
	v_lshl_add_u64 v[2:3], s[70:71], 0, v[154:155]
	global_load_lds_dwordx4 v154, s[70:71]
	s_mov_b64 s[12:13], 0x80000
	s_add_i32 m0, s56, 0x12000
	v_lshl_add_u64 v[4:5], v[2:3], 0, s[12:13]
	s_add_u32 s3, s33, s4
	s_mov_b64 s[14:15], 0x100000
	global_load_lds_dwordx4 v[4:5], off sc1
	s_addc_u32 s4, s52, s5
	v_lshl_add_u64 v[4:5], v[2:3], 0, s[14:15]
	s_add_i32 m0, s56, 0x14000
	s_mov_b64 s[16:17], 0x180000
	global_load_lds_dwordx4 v[4:5], off sc1
	s_add_i32 m0, s56, 0x16000
	s_add_u32 s68, s3, s18
	v_lshl_add_u64 v[4:5], v[2:3], 0, s[16:17]
	s_addc_u32 s69, s4, s19
	global_load_lds_dwordx4 v[4:5], off sc1
	v_lshl_add_u64 v[4:5], s[68:69], 0, v[154:155]
	s_mov_b32 m0, s56
	s_add_i32 s57, s56, 0x2000
	global_load_lds_dwordx4 v154, s[68:69]
	v_lshl_add_u64 v[8:9], v[4:5], 0, s[12:13]
	s_mov_b32 m0, s57
	s_add_i32 s58, s56, 0x4000
	global_load_lds_dwordx4 v[8:9], off sc1
	v_lshl_add_u64 v[8:9], v[4:5], 0, s[14:15]
	s_mov_b32 m0, s58
	s_add_i32 s59, s56, 0x6000
	global_load_lds_dwordx4 v[8:9], off sc1
	v_lshl_add_u64 v[8:9], v[4:5], 0, s[16:17]
	s_mov_b32 m0, s59
	s_cmp_eq_u32 s6, 1
	global_load_lds_dwordx4 v[8:9], off sc1
	s_cselect_b64 s[18:19], -1, 0
	s_cmp_lg_u32 s6, 1
	s_mov_b32 s21, 0
	s_cbranch_scc1 .LBB0_1516
	s_barrier
.LBB0_1516:
	s_add_u32 s22, s86, 0x40000
	s_addc_u32 s23, s87, 0
	s_add_u32 s60, s86, 0x34000000
	s_mov_b64 s[24:25], 0x800
	s_addc_u32 s61, s87, 0
	v_lshl_add_u64 v[8:9], v[2:3], 0, s[24:25]
	s_add_i32 m0, s56, 0x18000
	s_mov_b64 s[26:27], 0x80800
	s_waitcnt vmcnt(2)
	s_barrier
	global_load_lds_dwordx4 v[8:9], off sc1
	v_lshl_add_u64 v[8:9], v[2:3], 0, s[26:27]
	s_add_i32 m0, s56, 0x1a000
	s_add_i32 s62, s56, 0x8000
	global_load_lds_dwordx4 v[8:9], off sc1
	v_lshl_add_u64 v[8:9], v[4:5], 0, s[24:25]
	s_mov_b32 m0, s62
	s_add_i32 s63, s56, 0xa000
	global_load_lds_dwordx4 v[8:9], off sc1
	v_lshl_add_u64 v[4:5], v[4:5], 0, s[26:27]
	s_mov_b32 m0, s63
	s_mov_b64 s[28:29], 0x100800
	global_load_lds_dwordx4 v[4:5], off sc1
	v_lshl_add_u64 v[4:5], v[2:3], 0, s[28:29]
	s_add_i32 m0, s56, 0x1c000
	s_mov_b64 s[30:31], 0x180800
	global_load_lds_dwordx4 v[4:5], off sc1
	v_lshl_add_u64 v[2:3], v[2:3], 0, s[30:31]
	s_add_i32 m0, s56, 0x1e000
	v_lshrrev_b32_e32 v1, 1, v0
	global_load_lds_dwordx4 v[2:3], off sc1
	v_and_b32_e32 v3, 15, v0
	v_and_b32_e32 v9, 48, v0
	v_lshlrev_b32_e32 v2, 6, v3
	v_lshlrev_b32_e32 v5, 2, v0
	v_and_b32_e32 v4, 24, v1
	v_or_b32_e32 v1, v2, v9
	s_lshl_b32 s4, s6, 13
	v_and_b32_e32 v10, 32, v5
	s_and_b32 s3, s8, 3
	v_bitop3_b32 v11, v1, s4, v10 bitop3:0xde
	v_lshlrev_b32_e32 v1, 6, v0
	s_movk_i32 s4, 0x3c0
	v_and_or_b32 v1, v1, s4, v9
	s_lshl_b32 s4, s3, 12
	s_cmp_lt_u32 s8, 4
	v_lshl_or_b32 v8, s6, 6, v3
	s_cselect_b64 s[34:35], -1, 0
	s_lshl_b32 s11, s6, 10
	s_lshl_b32 s6, s8, 6
	v_bitop3_b32 v1, s4, v1, v10 bitop3:0xf6
	v_lshlrev_b32_e32 v10, 4, v3
	v_or3_b32 v165, s6, v9, v3
	v_mov_b32_e32 v3, v155
	v_lshl_or_b32 v164, s3, 5, v4
	v_bitop3_b32 v4, v5, v9, 32 bitop3:0x6c
	v_mov_b32_e32 v5, v155
	v_lshl_add_u64 v[2:3], s[86:87], 0, v[2:3]
	s_and_b32 s67, s8, -4
	v_lshl_add_u64 v[2:3], v[2:3], 0, v[4:5]
	s_mov_b64 s[8:9], 0x16e00000
	s_lshl_b32 s20, s3, 1
	v_lshl_add_u64 v[156:157], v[2:3], 0, s[8:9]
	s_lshl_b32 s3, s3, 2
	v_lshlrev_b32_e32 v2, 10, v0
	v_lshlrev_b32_e32 v9, 4, v165
	s_add_i32 s3, s3, 0
	v_and_b32_e32 v2, 0x60000, v2
	v_lshlrev_b32_e32 v3, 10, v6
	s_waitcnt vmcnt(6)
	s_add_i32 s3, s3, s11
	v_or3_b32 v158, v2, v3, v7
	v_add_u32_e32 v2, 0, v9
	s_movk_i32 s6, 0x100
	s_add_i32 s3, s3, 0x20800
	s_add_i32 s74, 0, 0x10000
	s_add_i32 s75, 0, 0x14000
	v_add_u32_e32 v170, 0x20800, v2
	v_mbcnt_lo_u32_b32 v2, -1, 0
	v_cmp_gt_u32_e64 s[4:5], 16, v182
	v_cmp_gt_i32_e64 s[6:7], s6, v165
	s_ashr_i32 s72, s97, 31
	s_ashr_i32 s73, s82, 31
	v_add_u32_e32 v166, 0xffffc000, v8
	v_mov_b32_e32 v159, v155
	v_mov_b64_e32 v[160:161], 0x1ff
	v_add_u32_e32 v167, s74, v1
	v_add_u32_e32 v168, s75, v1
	v_add_u32_e32 v169, 0, v11
	s_mov_b32 s76, 0x20000
	v_mbcnt_hi_u32_b32 v171, -1, v2
	v_add_u32_e32 v172, s3, v10
	s_mov_b32 s77, s21
	s_barrier
	s_branch .LBB0_1519

; #define PG8_STAGE(bufoff, gbase, voff) do { if constexpr (!pg8_noload<Epi>::value) { _Pragma("unroll") for (int _i = 0; _i < 2; ++_i) \
;         __builtin_amdgcn_global_load_lds((const unsigned*)((const char*)(gbase) + (size_t)_i * pstep + (voff)[0]), (PG8_LAS unsigned*)(lds + (bufoff) + ldsw + _i * 8192), 16, 0, 0); } } while (0)
; #define PG8_LDA(dst, b, h) do { _Pragma("unroll") for (int m = 0; m < 4; ++m) _Pragma("unroll") for (int k = 0; k < 2; ++k) dst[m][k] = *(const PG8_LAS bf16x8*)(lds + PG8_SA(b, h) + aoff + m * 2048 + k * 1024); } while (0)
; #define PG8_LDB(dst, b, h) do { _Pragma("unroll") for (int n = 0; n < 2; ++n) _Pragma("unroll") for (int k = 0; k < 2; ++k) dst[n][k] = *(const PG8_LAS bf16x8*)(lds + PG8_SB(b, h) + boff + n * 2048 + k * 1024); } while (0)
; #define PG8_WAIT_V(n) asm volatile("s_waitcnt vmcnt(" #n ")" ::: "memory")
; #define PG8_WAIT_L(n) asm volatile("s_waitcnt lgkmcnt(" #n ")" ::: "memory")
; #define PG8_BAR __builtin_amdgcn_s_barrier()
; template <class Epi, class Sched, bool ALIGN_EPI = false, bool SP2 = false, bool ABLK = false>
; __device__ __forceinline__ void gemm_phase(PG8_LAS unsigned char* lds, const Gemm g, const Sched& S, const Epi& E) {
;     ...
;         const char* nA = has_next ? (const char*)g.A + (size_t)nxt.pm * tstep + (size_t)nxt.ko * KOA : cA; const char* nB = has_next ? (const char*)g.Bt + (size_t)nxt.pn * tstep + (size_t)nxt.ko * 32 : cB;
;         for (int t = 0; t < nt; t += 2) {
;             const bool last = (t == nt - 2);
;             const char* a1 = cA + (size_t)(t + 1) * kstep;
;             const char* a2 = last ? nA : cA + (size_t)(t + 2) * kstep; const char* b2 = last ? nB : cB + (size_t)(t + 2) * kstepB;
;             const char* a3 = a2 + kstep; const char* b3 = b2 + kstepB;
;             if (last && has_next) S.a_ready(nxt);
;             if constexpr (SP2) {
;             PG8_LDB(B0, 0, 0); PG8_LDB(B1, 0, 1); PG8_SCHED; PG8_LDA(At, 0, 0); PG8_STAGE(PG8_SA(1, 1), a1 + hstep, voffA);
;             PG8_WAIT_V(8); PG8_WAIT_L(0); PG8_BAR; PG8_MMA(0, 0, At, B0); PG8_MMA(0, 1, At, B1); PG8_BAR; PG8_SCHED;
;             PG8_LDA(At, 0, 1); PG8_STAGE(PG8_SB(0, 0), b2, voffB); PG8_STAGE(PG8_SB(0, 1), b2 + hstep, voffB); PG8_STAGE(PG8_SA(0, 0), a2, voffA);
;             PG8_WAIT_V(8); PG8_WAIT_L(0); PG8_BAR; PG8_MMA(1, 0, At, B0); PG8_MMA(1, 1, At, B1); PG8_BAR; PG8_SCHED;
.LBB0_1533:
	ds_read_b128 v[114:117], v167
	ds_read_b128 v[126:129], v167 offset:1024
	ds_read_b128 v[130:133], v167 offset:2048
	ds_read_b128 v[142:145], v167 offset:3072
	ds_read_b128 v[146:149], v168
	ds_read_b128 v[150:153], v168 offset:1024
	ds_read_b128 v[174:177], v168 offset:2048
	ds_read_b128 v[178:181], v168 offset:3072
	s_add_i32 s41, s39, 2
	s_add_u32 s70, s68, 0xfff00800
	s_addc_u32 s71, s69, -1
	s_cmp_eq_u32 s3, s39
	s_cselect_b32 s71, s43, s71
	s_cselect_b32 s70, s42, s70
	s_cselect_b32 s81, s65, s37
	s_cselect_b32 s80, s64, s11
	v_lshl_add_u64 v[162:163], s[68:69], 0, v[158:159]
	s_add_i32 m0, s56, 0xc000
	ds_read_b128 v[184:187], v169
	ds_read_b128 v[188:191], v169 offset:1024
	ds_read_b128 v[192:195], v169 offset:2048
	ds_read_b128 v[196:199], v169 offset:3072
	ds_read_b128 v[200:203], v169 offset:4096
	ds_read_b128 v[204:207], v169 offset:5120
	ds_read_b128 v[208:211], v169 offset:6144
	ds_read_b128 v[212:215], v169 offset:7168
	global_load_lds_dwordx4 v[162:163], off sc1
	v_lshl_add_u64 v[162:163], v[162:163], 0, s[12:13]
	s_add_i32 m0, s56, 0xe000
	s_nop 0
	global_load_lds_dwordx4 v[162:163], off sc1
	s_waitcnt vmcnt(8)
	s_waitcnt lgkmcnt(0)
	s_barrier
	s_setprio 1
	s_waitcnt lgkmcnt(0)
	v_mfma_f32_16x16x32_bf16 v[138:141], v[114:117], v[184:187], v[138:141]
	v_mfma_f32_16x16x32_bf16 v[138:141], v[126:129], v[188:191], v[138:141]
	v_mfma_f32_16x16x32_bf16 v[110:113], v[126:129], v[196:199], v[110:113]
	v_mfma_f32_16x16x32_bf16 v[110:113], v[114:117], v[192:195], v[110:113]
	v_mfma_f32_16x16x32_bf16 v[94:97], v[114:117], v[200:203], v[94:97]
	v_mfma_f32_16x16x32_bf16 v[94:97], v[126:129], v[204:207], v[94:97]
	v_mfma_f32_16x16x32_bf16 v[78:81], v[126:129], v[212:215], v[78:81]
	v_mfma_f32_16x16x32_bf16 v[78:81], v[114:117], v[208:211], v[78:81]
	v_mfma_f32_16x16x32_bf16 v[74:77], v[130:133], v[208:211], v[74:77]
	v_mfma_f32_16x16x32_bf16 v[74:77], v[142:145], v[212:215], v[74:77]
	v_mfma_f32_16x16x32_bf16 v[90:93], v[142:145], v[204:207], v[90:93]
	v_mfma_f32_16x16x32_bf16 v[90:93], v[130:133], v[200:203], v[90:93]
	v_mfma_f32_16x16x32_bf16 v[106:109], v[130:133], v[192:195], v[106:109]
	v_mfma_f32_16x16x32_bf16 v[106:109], v[142:145], v[196:199], v[106:109]
	v_mfma_f32_16x16x32_bf16 v[134:137], v[142:145], v[188:191], v[134:137]
	v_mfma_f32_16x16x32_bf16 v[134:137], v[130:133], v[184:187], v[134:137]
	v_mfma_f32_16x16x32_bf16 v[122:125], v[146:149], v[184:187], v[122:125]
	v_mfma_f32_16x16x32_bf16 v[122:125], v[150:153], v[188:191], v[122:125]
	v_mfma_f32_16x16x32_bf16 v[102:105], v[150:153], v[196:199], v[102:105]
	v_mfma_f32_16x16x32_bf16 v[102:105], v[146:149], v[192:195], v[102:105]
	v_mfma_f32_16x16x32_bf16 v[86:89], v[146:149], v[200:203], v[86:89]
	v_mfma_f32_16x16x32_bf16 v[86:89], v[150:153], v[204:207], v[86:89]
	v_mfma_f32_16x16x32_bf16 v[70:73], v[150:153], v[212:215], v[70:73]
	v_mfma_f32_16x16x32_bf16 v[70:73], v[146:149], v[208:211], v[70:73]
	v_mfma_f32_16x16x32_bf16 v[66:69], v[174:177], v[208:211], v[66:69]
	v_mfma_f32_16x16x32_bf16 v[66:69], v[178:181], v[212:215], v[66:69]
	v_mfma_f32_16x16x32_bf16 v[82:85], v[178:181], v[204:207], v[82:85]
	v_mfma_f32_16x16x32_bf16 v[82:85], v[174:177], v[200:203], v[82:85]
	s_barrier
	s_setprio 2
	v_mfma_f32_16x16x32_bf16 v[98:101], v[174:177], v[192:195], v[98:101]
	v_mfma_f32_16x16x32_bf16 v[98:101], v[178:181], v[196:199], v[98:101]
	v_mfma_f32_16x16x32_bf16 v[118:121], v[178:181], v[188:191], v[118:121]
	v_mfma_f32_16x16x32_bf16 v[118:121], v[174:177], v[184:187], v[118:121]
	s_setprio 0
	s_add_i32 s39, s74, s55
	v_lshl_add_u64 v[162:163], s[80:81], 0, v[154:155]
	s_mov_b32 m0, s39
	ds_read_b128 v[184:187], v169 offset:16384
	ds_read_b128 v[188:191], v169 offset:17408
	ds_read_b128 v[192:195], v169 offset:18432
	ds_read_b128 v[196:199], v169 offset:19456
	ds_read_b128 v[200:203], v169 offset:20480
	ds_read_b128 v[204:207], v169 offset:21504
	ds_read_b128 v[208:211], v169 offset:22528
	ds_read_b128 v[212:215], v169 offset:23552
	global_load_lds_dwordx4 v[162:163], off sc1
	v_lshl_add_u64 v[216:217], v[162:163], 0, s[12:13]
	s_add_i32 m0, s39, 0x2000
	s_add_i32 s39, s75, s55
	global_load_lds_dwordx4 v[216:217], off sc1
	v_lshl_add_u64 v[216:217], v[162:163], 0, s[14:15]
	s_mov_b32 m0, s39
	s_nop 0
	global_load_lds_dwordx4 v[216:217], off sc1
	v_lshl_add_u64 v[216:217], v[162:163], 0, s[16:17]
	s_add_i32 m0, s39, 0x2000
	s_nop 0
	global_load_lds_dwordx4 v[216:217], off sc1
	v_lshl_add_u64 v[216:217], s[70:71], 0, v[154:155]
	s_mov_b32 m0, s56
	v_lshl_add_u64 v[218:219], v[216:217], 0, s[12:13]
	global_load_lds_dwordx4 v[216:217], off sc1
	s_mov_b32 m0, s57
	s_nop 0
	global_load_lds_dwordx4 v[218:219], off sc1
	s_waitcnt vmcnt(8)
	s_waitcnt lgkmcnt(0)
	s_barrier
; #define PG8_STAGE(bufoff, gbase, voff) do { if constexpr (!pg8_noload<Epi>::value) { _Pragma("unroll") for (int _i = 0; _i < 2; ++_i) \
;         __builtin_amdgcn_global_load_lds((const unsigned*)((const char*)(gbase) + (size_t)_i * pstep + (voff)[0]), (PG8_LAS unsigned*)(lds + (bufoff) + ldsw + _i * 8192), 16, 0, 0); } } while (0)
; #define PG8_LDA(dst, b, h) do { _Pragma("unroll") for (int m = 0; m < 4; ++m) _Pragma("unroll") for (int k = 0; k < 2; ++k) dst[m][k] = *(const PG8_LAS bf16x8*)(lds + PG8_SA(b, h) + aoff + m * 2048 + k * 1024); } while (0)
; #define PG8_LDB(dst, b, h) do { _Pragma("unroll") for (int n = 0; n < 2; ++n) _Pragma("unroll") for (int k = 0; k < 2; ++k) dst[n][k] = *(const PG8_LAS bf16x8*)(lds + PG8_SB(b, h) + boff + n * 2048 + k * 1024); } while (0)
; #define PG8_MMA(ai, bj, At, Bt) do { __builtin_amdgcn_s_setprio(1); _Pragma("unroll") for (int m = 0; m < 4; ++m) _Pragma("unroll") for (int n = 0; n < 2; ++n) _Pragma("unroll") for (int k = 0; k < 2; ++k) \
;         acc[ai][bj][m][n] = __builtin_amdgcn_mfma_f32_16x16x32_bf16(Bt[n][k], At[m][k], acc[ai][bj][m][n], 0, 0, 0); __builtin_amdgcn_s_setprio(0); } while (0)
; #define PG8_WAIT_V(n) asm volatile("s_waitcnt vmcnt(" #n ")" ::: "memory")
; #define PG8_WAIT_L(n) asm volatile("s_waitcnt lgkmcnt(" #n ")" ::: "memory")
; #define PG8_BAR __builtin_amdgcn_s_barrier()
; #define PG8_SCHED __builtin_amdgcn_sched_barrier(0)
; template <class Epi, class Sched, bool ALIGN_EPI = false, bool SP2 = false, bool ABLK = false>
; __device__ __forceinline__ void gemm_phase(PG8_LAS unsigned char* lds, const Gemm g, const Sched& S, const Epi& E) {
;     ...
;             PG8_WAIT_V(8); PG8_WAIT_L(0); PG8_BAR; PG8_MMA(1, 0, At, B0); PG8_MMA(1, 1, At, B1); PG8_BAR; PG8_SCHED;
;             PG8_LDB(B0, 1, 0); PG8_LDB(B1, 1, 1); PG8_SCHED; PG8_LDA(At, 1, 0); PG8_STAGE(PG8_SA(0, 1), a2 + hstep, voffA);
;             PG8_WAIT_V(8); PG8_WAIT_L(0); PG8_BAR; PG8_MMA(0, 0, At, B0); PG8_MMA(0, 1, At, B1); PG8_BAR; PG8_SCHED;
	s_setprio 1
	s_waitcnt lgkmcnt(0)
	v_mfma_f32_16x16x32_bf16 v[62:65], v[114:117], v[184:187], v[62:65]
	v_mfma_f32_16x16x32_bf16 v[62:65], v[126:129], v[188:191], v[62:65]
	v_mfma_f32_16x16x32_bf16 v[46:49], v[126:129], v[196:199], v[46:49]
	v_mfma_f32_16x16x32_bf16 v[46:49], v[114:117], v[192:195], v[46:49]
	v_mfma_f32_16x16x32_bf16 v[30:33], v[114:117], v[200:203], v[30:33]
	v_mfma_f32_16x16x32_bf16 v[30:33], v[126:129], v[204:207], v[30:33]
	v_mfma_f32_16x16x32_bf16 v[14:17], v[126:129], v[212:215], v[14:17]
	v_mfma_f32_16x16x32_bf16 v[14:17], v[114:117], v[208:211], v[14:17]
	v_mfma_f32_16x16x32_bf16 v[10:13], v[130:133], v[208:211], v[10:13]
	v_mfma_f32_16x16x32_bf16 v[10:13], v[142:145], v[212:215], v[10:13]
	v_mfma_f32_16x16x32_bf16 v[26:29], v[142:145], v[204:207], v[26:29]
	v_mfma_f32_16x16x32_bf16 v[26:29], v[130:133], v[200:203], v[26:29]
	v_mfma_f32_16x16x32_bf16 v[42:45], v[130:133], v[192:195], v[42:45]
	v_mfma_f32_16x16x32_bf16 v[42:45], v[142:145], v[196:199], v[42:45]
	v_mfma_f32_16x16x32_bf16 v[58:61], v[142:145], v[188:191], v[58:61]
	v_mfma_f32_16x16x32_bf16 v[58:61], v[130:133], v[184:187], v[58:61]
	v_mfma_f32_16x16x32_bf16 v[54:57], v[146:149], v[184:187], v[54:57]
	v_mfma_f32_16x16x32_bf16 v[54:57], v[150:153], v[188:191], v[54:57]
	v_mfma_f32_16x16x32_bf16 v[38:41], v[150:153], v[196:199], v[38:41]
	v_mfma_f32_16x16x32_bf16 v[38:41], v[146:149], v[192:195], v[38:41]
	v_mfma_f32_16x16x32_bf16 v[22:25], v[146:149], v[200:203], v[22:25]
	v_mfma_f32_16x16x32_bf16 v[22:25], v[150:153], v[204:207], v[22:25]
	v_mfma_f32_16x16x32_bf16 v[6:9], v[150:153], v[212:215], v[6:9]
	v_mfma_f32_16x16x32_bf16 v[6:9], v[146:149], v[208:211], v[6:9]
	v_mfma_f32_16x16x32_bf16 v[2:5], v[174:177], v[208:211], v[2:5]
	v_mfma_f32_16x16x32_bf16 v[2:5], v[178:181], v[212:215], v[2:5]
	v_mfma_f32_16x16x32_bf16 v[18:21], v[178:181], v[204:207], v[18:21]
	v_mfma_f32_16x16x32_bf16 v[18:21], v[174:177], v[200:203], v[18:21]
	s_barrier
	s_setprio 2
	v_mfma_f32_16x16x32_bf16 v[34:37], v[174:177], v[192:195], v[34:37]
	v_mfma_f32_16x16x32_bf16 v[34:37], v[178:181], v[196:199], v[34:37]
	v_mfma_f32_16x16x32_bf16 v[50:53], v[178:181], v[188:191], v[50:53]
	v_mfma_f32_16x16x32_bf16 v[50:53], v[174:177], v[184:187], v[50:53]
	s_setprio 0
	s_add_i32 s39, 0, 0x18000
	s_add_i32 s70, 0, 0x1c000
	v_add_u32_e32 v142, s39, v1
	v_add_u32_e32 v173, s70, v1
	ds_read_b128 v[114:117], v142
	ds_read_b128 v[126:129], v142 offset:1024
	ds_read_b128 v[130:133], v142 offset:2048
	ds_read_b128 v[142:145], v142 offset:3072
	ds_read_b128 v[146:149], v173
	ds_read_b128 v[150:153], v173 offset:1024
	ds_read_b128 v[174:177], v173 offset:2048
	ds_read_b128 v[178:181], v173 offset:3072
	s_mov_b32 m0, s58
	v_lshl_add_u64 v[218:219], v[216:217], 0, s[14:15]
	ds_read_b128 v[184:187], v169 offset:32768
	ds_read_b128 v[188:191], v169 offset:33792
	ds_read_b128 v[192:195], v169 offset:34816
	ds_read_b128 v[196:199], v169 offset:35840
	ds_read_b128 v[200:203], v169 offset:36864
	ds_read_b128 v[204:207], v169 offset:37888
	ds_read_b128 v[208:211], v169 offset:38912
	ds_read_b128 v[212:215], v169 offset:39936
	global_load_lds_dwordx4 v[218:219], off sc1
	v_lshl_add_u64 v[218:219], v[216:217], 0, s[16:17]
	s_mov_b32 m0, s59
	s_nop 0
	global_load_lds_dwordx4 v[218:219], off sc1
	s_waitcnt vmcnt(8)
	s_waitcnt lgkmcnt(0)
	s_barrier
	s_setprio 1
	s_waitcnt lgkmcnt(0)
	v_mfma_f32_16x16x32_bf16 v[138:141], v[114:117], v[184:187], v[138:141]
	v_mfma_f32_16x16x32_bf16 v[138:141], v[126:129], v[188:191], v[138:141]
	v_mfma_f32_16x16x32_bf16 v[110:113], v[126:129], v[196:199], v[110:113]
	v_mfma_f32_16x16x32_bf16 v[110:113], v[114:117], v[192:195], v[110:113]
	v_mfma_f32_16x16x32_bf16 v[94:97], v[114:117], v[200:203], v[94:97]
	v_mfma_f32_16x16x32_bf16 v[94:97], v[126:129], v[204:207], v[94:97]
	v_mfma_f32_16x16x32_bf16 v[78:81], v[126:129], v[212:215], v[78:81]
	v_mfma_f32_16x16x32_bf16 v[78:81], v[114:117], v[208:211], v[78:81]
	v_mfma_f32_16x16x32_bf16 v[74:77], v[130:133], v[208:211], v[74:77]
	v_mfma_f32_16x16x32_bf16 v[74:77], v[142:145], v[212:215], v[74:77]
	v_mfma_f32_16x16x32_bf16 v[90:93], v[142:145], v[204:207], v[90:93]
	v_mfma_f32_16x16x32_bf16 v[90:93], v[130:133], v[200:203], v[90:93]
	v_mfma_f32_16x16x32_bf16 v[106:109], v[130:133], v[192:195], v[106:109]
	v_mfma_f32_16x16x32_bf16 v[106:109], v[142:145], v[196:199], v[106:109]
	v_mfma_f32_16x16x32_bf16 v[134:137], v[142:145], v[188:191], v[134:137]
	v_mfma_f32_16x16x32_bf16 v[134:137], v[130:133], v[184:187], v[134:137]
	v_mfma_f32_16x16x32_bf16 v[122:125], v[146:149], v[184:187], v[122:125]
	v_mfma_f32_16x16x32_bf16 v[122:125], v[150:153], v[188:191], v[122:125]
	v_mfma_f32_16x16x32_bf16 v[102:105], v[150:153], v[196:199], v[102:105]
	v_mfma_f32_16x16x32_bf16 v[102:105], v[146:149], v[192:195], v[102:105]
	v_mfma_f32_16x16x32_bf16 v[86:89], v[146:149], v[200:203], v[86:89]
	v_mfma_f32_16x16x32_bf16 v[86:89], v[150:153], v[204:207], v[86:89]
	v_mfma_f32_16x16x32_bf16 v[70:73], v[150:153], v[212:215], v[70:73]
	v_mfma_f32_16x16x32_bf16 v[70:73], v[146:149], v[208:211], v[70:73]
	v_mfma_f32_16x16x32_bf16 v[66:69], v[174:177], v[208:211], v[66:69]
	v_mfma_f32_16x16x32_bf16 v[66:69], v[178:181], v[212:215], v[66:69]
	v_mfma_f32_16x16x32_bf16 v[82:85], v[178:181], v[204:207], v[82:85]
	v_mfma_f32_16x16x32_bf16 v[82:85], v[174:177], v[200:203], v[82:85]
	s_barrier
; #define PG8_STAGE(bufoff, gbase, voff) do { if constexpr (!pg8_noload<Epi>::value) { _Pragma("unroll") for (int _i = 0; _i < 2; ++_i) \
;         __builtin_amdgcn_global_load_lds((const unsigned*)((const char*)(gbase) + (size_t)_i * pstep + (voff)[0]), (PG8_LAS unsigned*)(lds + (bufoff) + ldsw + _i * 8192), 16, 0, 0); } } while (0)
; #define PG8_LDA(dst, b, h) do { _Pragma("unroll") for (int m = 0; m < 4; ++m) _Pragma("unroll") for (int k = 0; k < 2; ++k) dst[m][k] = *(const PG8_LAS bf16x8*)(lds + PG8_SA(b, h) + aoff + m * 2048 + k * 1024); } while (0)
; #define PG8_MMA(ai, bj, At, Bt) do { __builtin_amdgcn_s_setprio(1); _Pragma("unroll") for (int m = 0; m < 4; ++m) _Pragma("unroll") for (int n = 0; n < 2; ++n) _Pragma("unroll") for (int k = 0; k < 2; ++k) \
;         acc[ai][bj][m][n] = __builtin_amdgcn_mfma_f32_16x16x32_bf16(Bt[n][k], At[m][k], acc[ai][bj][m][n], 0, 0, 0); __builtin_amdgcn_s_setprio(0); } while (0)
; #define PG8_WAIT_V(n) asm volatile("s_waitcnt vmcnt(" #n ")" ::: "memory")
; #define PG8_WAIT_L(n) asm volatile("s_waitcnt lgkmcnt(" #n ")" ::: "memory")
; #define PG8_BAR __builtin_amdgcn_s_barrier()
; #define PG8_SCHED __builtin_amdgcn_sched_barrier(0)
;     __device__ __forceinline__ void operator()(const f32x4 (&acc)[2][2][4][2], const Unit& u, int wr, int wc, int fr, int fq) const {
;         const int c0 = u.pn * BM + wc * 32 + 8 * fq;
;         if (u.pm * BM < seq) {
; template <class Epi, class Sched, bool ALIGN_EPI = false, bool SP2 = false, bool ABLK = false>
; __device__ __forceinline__ void gemm_phase(PG8_LAS unsigned char* lds, const Gemm g, const Sched& S, const Epi& E) {
;     ...
;             PG8_WAIT_V(8); PG8_WAIT_L(0); PG8_BAR; PG8_MMA(0, 0, At, B0); PG8_MMA(0, 1, At, B1); PG8_BAR; PG8_SCHED;
;             PG8_LDA(At, 1, 1); PG8_STAGE(PG8_SB(1, 0), b3, voffB); PG8_STAGE(PG8_SB(1, 1), b3 + hstep, voffB); PG8_STAGE(PG8_SA(1, 0), a3, voffA);
;             PG8_WAIT_V(8); PG8_WAIT_L(0); PG8_BAR; PG8_MMA(1, 0, At, B0); PG8_MMA(1, 1, At, B1); PG8_BAR; PG8_SCHED;
	s_setprio 2
	v_mfma_f32_16x16x32_bf16 v[98:101], v[174:177], v[192:195], v[98:101]
	v_mfma_f32_16x16x32_bf16 v[98:101], v[178:181], v[196:199], v[98:101]
	v_mfma_f32_16x16x32_bf16 v[118:121], v[178:181], v[188:191], v[118:121]
	v_mfma_f32_16x16x32_bf16 v[118:121], v[174:177], v[184:187], v[118:121]
	s_setprio 0
	s_add_i32 s39, s39, s55
	v_lshl_add_u64 v[218:219], v[162:163], 0, s[24:25]
	s_mov_b32 m0, s39
	ds_read_b128 v[184:187], v169 offset:49152
	ds_read_b128 v[188:191], v169 offset:50176
	ds_read_b128 v[192:195], v169 offset:51200
	ds_read_b128 v[196:199], v169 offset:52224
	ds_read_b128 v[200:203], v169 offset:53248
	ds_read_b128 v[204:207], v169 offset:54272
	ds_read_b128 v[208:211], v169 offset:55296
	ds_read_b128 v[212:215], v169 offset:56320
	global_load_lds_dwordx4 v[218:219], off sc1
	v_lshl_add_u64 v[218:219], v[162:163], 0, s[26:27]
	s_add_i32 m0, s39, 0x2000
	s_add_i32 s39, s70, s55
	global_load_lds_dwordx4 v[218:219], off sc1
	v_lshl_add_u64 v[218:219], v[162:163], 0, s[28:29]
	s_mov_b32 m0, s39
	v_lshl_add_u64 v[162:163], v[162:163], 0, s[30:31]
	global_load_lds_dwordx4 v[218:219], off sc1
	s_add_i32 m0, s39, 0x2000
	s_nop 0
	global_load_lds_dwordx4 v[162:163], off sc1
	v_lshl_add_u64 v[162:163], v[216:217], 0, s[24:25]
	s_mov_b32 m0, s62
	s_nop 0
	global_load_lds_dwordx4 v[162:163], off sc1
	v_lshl_add_u64 v[162:163], v[216:217], 0, s[26:27]
	s_mov_b32 m0, s63
	s_nop 0
	global_load_lds_dwordx4 v[162:163], off sc1
	s_waitcnt vmcnt(8)
	s_waitcnt lgkmcnt(0)
	s_barrier
	s_setprio 1
	s_waitcnt lgkmcnt(0)
	v_mfma_f32_16x16x32_bf16 v[62:65], v[114:117], v[184:187], v[62:65]
	v_mfma_f32_16x16x32_bf16 v[62:65], v[126:129], v[188:191], v[62:65]
	v_mfma_f32_16x16x32_bf16 v[46:49], v[126:129], v[196:199], v[46:49]
	v_mfma_f32_16x16x32_bf16 v[46:49], v[114:117], v[192:195], v[46:49]
	v_mfma_f32_16x16x32_bf16 v[30:33], v[114:117], v[200:203], v[30:33]
	v_mfma_f32_16x16x32_bf16 v[30:33], v[126:129], v[204:207], v[30:33]
	v_mfma_f32_16x16x32_bf16 v[14:17], v[126:129], v[212:215], v[14:17]
	v_mfma_f32_16x16x32_bf16 v[14:17], v[114:117], v[208:211], v[14:17]
	v_mfma_f32_16x16x32_bf16 v[10:13], v[130:133], v[208:211], v[10:13]
	v_mfma_f32_16x16x32_bf16 v[10:13], v[142:145], v[212:215], v[10:13]
	v_mfma_f32_16x16x32_bf16 v[26:29], v[142:145], v[204:207], v[26:29]
	v_mfma_f32_16x16x32_bf16 v[26:29], v[130:133], v[200:203], v[26:29]
	v_mfma_f32_16x16x32_bf16 v[42:45], v[130:133], v[192:195], v[42:45]
	v_mfma_f32_16x16x32_bf16 v[42:45], v[142:145], v[196:199], v[42:45]
	v_mfma_f32_16x16x32_bf16 v[58:61], v[142:145], v[188:191], v[58:61]
	v_mfma_f32_16x16x32_bf16 v[58:61], v[130:133], v[184:187], v[58:61]
	v_mfma_f32_16x16x32_bf16 v[54:57], v[146:149], v[184:187], v[54:57]
	v_mfma_f32_16x16x32_bf16 v[54:57], v[150:153], v[188:191], v[54:57]
	v_mfma_f32_16x16x32_bf16 v[38:41], v[150:153], v[196:199], v[38:41]
	v_mfma_f32_16x16x32_bf16 v[38:41], v[146:149], v[192:195], v[38:41]
	v_mfma_f32_16x16x32_bf16 v[22:25], v[146:149], v[200:203], v[22:25]
	v_mfma_f32_16x16x32_bf16 v[22:25], v[150:153], v[204:207], v[22:25]
	v_mfma_f32_16x16x32_bf16 v[6:9], v[150:153], v[212:215], v[6:9]
	v_mfma_f32_16x16x32_bf16 v[6:9], v[146:149], v[208:211], v[6:9]
	v_mfma_f32_16x16x32_bf16 v[2:5], v[174:177], v[208:211], v[2:5]
	v_mfma_f32_16x16x32_bf16 v[2:5], v[178:181], v[212:215], v[2:5]
	v_mfma_f32_16x16x32_bf16 v[18:21], v[178:181], v[204:207], v[18:21]
	v_mfma_f32_16x16x32_bf16 v[18:21], v[174:177], v[200:203], v[18:21]
	s_barrier
	s_setprio 2
	v_mfma_f32_16x16x32_bf16 v[34:37], v[174:177], v[192:195], v[34:37]
	v_mfma_f32_16x16x32_bf16 v[34:37], v[178:181], v[196:199], v[34:37]
	v_mfma_f32_16x16x32_bf16 v[50:53], v[178:181], v[188:191], v[50:53]
	v_mfma_f32_16x16x32_bf16 v[50:53], v[174:177], v[184:187], v[50:53]
	s_setprio 0
	s_add_u32 s68, s68, 0x1000
	s_addc_u32 s69, s69, 0
	s_add_u32 s11, s11, 0x1000
	s_addc_u32 s37, s37, 0
	s_cmp_ge_i32 s41, s79
	s_mov_b32 s39, s41
	s_cbranch_scc0 .LBB0_1533
	s_and_b64 vcc, exec, s[34:35]
	s_cbranch_vccnz .LBB0_1538
	s_lshl_b32 s11, s2, 8
	s_cmp_gt_i32 s2, 63
	s_mov_b64 s[68:69], -1
	s_cbranch_scc1 .LBB0_1539

; #define PG8_WAIT_V(n) asm volatile("s_waitcnt vmcnt(" #n ")" ::: "memory")
; #define PG8_BAR __builtin_amdgcn_s_barrier()
; template <class Epi, class Sched, bool ALIGN_EPI = false, bool SP2 = false, bool ABLK = false>
; __device__ __forceinline__ void gemm_phase(PG8_LAS unsigned char* lds, const Gemm g, const Sched& S, const Epi& E) {
;     const int tid = threadIdx.x, wid = __builtin_amdgcn_readfirstlane(tid >> 6), lane = tid & 63, wr = wid >> 2, wc = wid & 3, fr = lane & 15, fq = lane >> 4;
;     const int K = g.K;
;     unsigned voffA[2], voffB[2];
; #pragma unroll
;     for (int i = 0; i < 2; ++i) { int R, C; stage_rc(tid * 16 + i * 8192, R, C); const int Rb = Epi::PERM ? ((R & ~31) + perm32(R & 31)) : R;
;         voffA[i] = (unsigned)(R * K + C) * 2u; (void)Rb;
;         if constexpr (ABLK) { const int st = (tid >> 6) + 8 * i; voffA[i] = (unsigned)(((st >> 1) * (K / 32) + (st & 1)) * 1024 + (tid & 63) * 16); }
;         { static_assert(Epi::PERM, "blocked weight copies are written in permuted row-slot order"); const int st = (tid >> 6) + 8 * i; voffB[i] = (unsigned)(((st >> 1) * (K / 32) + (st & 1)) * 1024 + (tid & 63) * 16); } }
;     const size_t kstep = ABLK ? (size_t)(BK / 32) * 1024 : (size_t)(BK * 2);
;     constexpr int KOA = ABLK ? 32 : 2;
;     const size_t pstep = (size_t)K * 128;
;     const size_t kstepB = (size_t)(BK / 32) * 1024;
;     const size_t hstep = (size_t)HALF * K * 2;
;     const size_t tstep = 2 * hstep;
;     const unsigned ldsw = (unsigned)wid * 1024u;
;     const int aoff = lds_byte(wr * 64 + fr, fq * 8), boff = lds_byte(wc * 32 + fr, fq * 8);
;     ...
;     const char* cA = (const char*)g.A + (size_t)cur.pm * tstep + (size_t)cur.ko * KOA; const char* cB = (const char*)g.Bt + (size_t)cur.pn * tstep + (size_t)cur.ko * 32; int nt = cur.nt;
;     S.a_ready(cur);
;     if constexpr (SP2) {
;         PG8_STAGE(PG8_SB(0, 0), cB, voffB); PG8_STAGE(PG8_SB(0, 1), cB + hstep, voffB); PG8_STAGE(PG8_SA(0, 0), cA, voffA); PG8_STAGE(PG8_SA(0, 1), cA + hstep, voffA);
;         if (wr == 1) PG8_BAR;
;         PG8_WAIT_V(2); PG8_BAR;
;         PG8_STAGE(PG8_SB(1, 0), cB + kstepB, voffB); PG8_STAGE(PG8_SA(1, 0), cA + kstep, voffA); PG8_STAGE(PG8_SB(1, 1), cB + hstep + kstepB, voffB);
;         PG8_WAIT_V(6); PG8_BAR;
.LBB0_1646:
	s_add_u32 s53, s86, 0xc000000
	s_addc_u32 s54, s87, 0
	s_ashr_i32 s73, s72, 31
	s_lshl_b64 s[0:1], s[72:73], 20
	s_add_u32 s74, s33, s0
	s_addc_u32 s75, s52, s1
	s_ashr_i32 s3, s2, 31
	s_lshl_b64 s[0:1], s[2:3], 20
	s_add_u32 s76, s53, s0
	v_lshlrev_b32_e32 v3, 5, v183
	v_lshlrev_b32_e32 v2, 4, v0
	s_movk_i32 s0, 0xc1
	s_addc_u32 s77, s54, s1
	v_and_b32_e32 v2, 0x3f0, v2
	v_bitop3_b32 v3, v3, s0, v183 bitop3:0xc8
	s_lshl_b32 s55, s10, 10
	v_mov_b32_e32 v141, 0
	v_lshl_or_b32 v138, v3, 10, v2
	v_mov_b32_e32 v139, v141
	s_add_i32 s56, s55, 0
	v_lshl_add_u64 v[4:5], s[76:77], 0, v[138:139]
	s_add_i32 m0, s56, 0x10000
	s_mov_b64 s[18:19], 0x40000
	global_load_lds_dwordx4 v138, s[76:77]
	v_lshl_add_u64 v[6:7], v[4:5], 0, s[18:19]
	s_add_i32 m0, s56, 0x12000
	s_mov_b64 s[20:21], 0x80000
	global_load_lds_dwordx4 v[6:7], off sc1
	v_lshl_add_u64 v[6:7], v[4:5], 0, s[20:21]
	s_add_i32 m0, s56, 0x14000
	s_mov_b64 s[22:23], 0xc0000
	global_load_lds_dwordx4 v[6:7], off sc1
	v_lshl_add_u64 v[6:7], v[4:5], 0, s[22:23]
	s_add_i32 m0, s56, 0x16000
	s_add_i32 s57, s56, 0x2000
	global_load_lds_dwordx4 v[6:7], off sc1
	v_lshl_add_u64 v[6:7], s[74:75], 0, v[138:139]
	s_mov_b32 m0, s56
	v_lshl_add_u64 v[8:9], v[6:7], 0, s[18:19]
	global_load_lds_dwordx4 v138, s[74:75]
	s_mov_b32 m0, s57
	s_add_i32 s58, s56, 0x4000
	global_load_lds_dwordx4 v[8:9], off sc1
	v_lshl_add_u64 v[8:9], v[6:7], 0, s[20:21]
	s_mov_b32 m0, s58
	s_add_i32 s59, s56, 0x6000
	global_load_lds_dwordx4 v[8:9], off sc1
	v_lshl_add_u64 v[8:9], v[6:7], 0, s[22:23]
	s_mov_b32 m0, s59
	v_writelane_b32 v251, s42, 44
	global_load_lds_dwordx4 v[8:9], off sc1
	s_nop 0
	v_writelane_b32 v251, s43, 45
	s_ashr_i32 s0, s10, 2
	v_writelane_b32 v251, s88, 54
	s_cmp_eq_u32 s0, 1
	s_cselect_b64 s[4:5], -1, 0
	v_writelane_b32 v251, s89, 55
	v_writelane_b32 v251, s4, 26
	s_cmp_lg_u32 s0, 1
	s_mov_b32 s27, 0
	v_writelane_b32 v251, s5, 27
	s_cbranch_scc1 .LBB0_1648
	s_barrier
.LBB0_1648:
	s_add_u32 s60, s86, 0x1b400000
	s_addc_u32 s61, s87, 0
	s_add_u32 s4, s86, 0x40000
	s_mov_b64 s[30:31], 0x800
	s_addc_u32 s5, s87, 0
	v_lshl_add_u64 v[8:9], v[4:5], 0, s[30:31]
	s_add_i32 m0, s56, 0x18000
	s_mov_b64 s[34:35], 0x40800
	s_waitcnt vmcnt(2)
	s_barrier
	global_load_lds_dwordx4 v[8:9], off sc1
	v_lshl_add_u64 v[8:9], v[4:5], 0, s[34:35]
	s_add_i32 m0, s56, 0x1a000
	s_add_i32 s63, s56, 0x8000
	global_load_lds_dwordx4 v[8:9], off sc1
	v_lshl_add_u64 v[8:9], v[6:7], 0, s[30:31]
	s_mov_b32 m0, s63
	s_add_i32 s73, s56, 0xa000
	global_load_lds_dwordx4 v[8:9], off sc1
	v_lshl_add_u64 v[6:7], v[6:7], 0, s[34:35]
	s_mov_b32 m0, s73
	s_mov_b64 s[36:37], 0x80800
	global_load_lds_dwordx4 v[6:7], off sc1
	v_lshl_add_u64 v[6:7], v[4:5], 0, s[36:37]
	s_add_i32 m0, s56, 0x1c000
	s_mov_b64 s[38:39], 0xc0800
	global_load_lds_dwordx4 v[6:7], off sc1
	v_lshl_add_u64 v[4:5], v[4:5], 0, s[38:39]
	s_add_i32 m0, s56, 0x1e000
	v_and_b32_e32 v172, 15, v0
	global_load_lds_dwordx4 v[4:5], off sc1
	v_and_b32_e32 v4, 48, v0
	v_lshlrev_b32_e32 v6, 2, v0
	s_lshl_b32 s62, s0, 6
	v_lshl_or_b32 v5, v172, 6, v4
	s_lshl_b32 s0, s0, 13
	v_and_b32_e32 v6, 32, v6
	s_and_b32 s1, s10, 3
	v_bitop3_b32 v6, v5, s0, v6 bitop3:0xde
	v_lshlrev_b32_e32 v5, 6, v0
	s_movk_i32 s0, 0x3c0
	v_lshrrev_b32_e32 v3, 1, v0
	v_and_or_b32 v5, v5, s0, v4
	s_lshl_b32 s0, s1, 12
	v_and_b32_e32 v3, 24, v3
	v_and_b32_e32 v7, 32, v1
	s_cmp_lt_u32 s10, 4
	v_bitop3_b32 v173, s0, v5, v7 bitop3:0xf6
	s_cselect_b64 s[40:41], -1, 0
	s_lshl_b32 s0, s10, 6
	v_lshl_or_b32 v175, s1, 5, v3
	v_lshlrev_b32_e32 v140, 9, v172
	v_or3_b32 v174, s0, v4, v172
	s_movk_i32 s0, 0x100
	v_lshl_add_u64 v[4:5], s[84:85], 0, v[140:141]
	v_lshlrev_b32_e32 v140, 2, v175
	v_writelane_b32 v251, s4, 50
	v_cmp_gt_i32_e64 s[8:9], s0, v174
	s_lshl_b32 s42, s1, 1
	v_lshl_add_u64 v[4:5], v[4:5], 0, v[140:141]
	s_mov_b64 s[0:1], 0x1d852000
	v_writelane_b32 v251, s5, 51
	s_waitcnt vmcnt(6)
	v_lshl_add_u64 v[142:143], v[4:5], 0, s[0:1]
	v_lshl_add_u64 v[4:5], s[84:85], 0, v[140:141]
	s_mov_b64 s[0:1], 0xd852000
	v_mov_b32_e32 v3, v141
	v_writelane_b32 v251, s8, 24
	s_ashr_i32 s95, s97, 31
	v_lshl_add_u64 v[144:145], v[4:5], 0, s[0:1]
	s_add_i32 s97, 0, 0x22800
	v_lshl_add_u64 v[2:3], s[86:87], 0, v[2:3]
	s_mov_b64 s[0:1], 0x27a00000
	v_cmp_gt_u32_e64 s[4:5], 64, v0
	s_and_b32 s7, s10, -4
	v_writelane_b32 v251, s9, 25
	v_cmp_eq_u32_e64 s[8:9], 0, v174
	s_mov_b32 s43, s27
	s_ashr_i32 s96, s82, 31
	v_lshl_add_u32 v176, v174, 2, s97
	v_lshl_add_u64 v[146:147], v[2:3], 0, s[0:1]
	v_mov_b64_e32 v[148:149], 0x840
	v_mov_b64_e32 v[150:151], 0x83f
	v_mov_b32_e32 v177, 1
	s_add_i32 s12, 0, 0x10000
	s_add_i32 s13, 0, 0x14000
	v_add_u32_e32 v178, 0, v6
	s_add_i32 s28, 0, 0x22c00
	v_mov_b32_e32 v179, 0x358637bd
	s_movk_i32 s29, 0x3fff
	v_mov_b64_e32 v[152:153], 0x1e8481
	v_mov_b32_e32 v180, 0x3db504f3
	s_mov_b32 s24, 0
	s_barrier
	s_branch .LBB0_1651

; #define PG8_STAGE(bufoff, gbase, voff) do { if constexpr (!pg8_noload<Epi>::value) { _Pragma("unroll") for (int _i = 0; _i < 2; ++_i) \
;         __builtin_amdgcn_global_load_lds((const unsigned*)((const char*)(gbase) + (size_t)_i * pstep + (voff)[0]), (PG8_LAS unsigned*)(lds + (bufoff) + ldsw + _i * 8192), 16, 0, 0); } } while (0)
; #define PG8_LDA(dst, b, h) do { _Pragma("unroll") for (int m = 0; m < 4; ++m) _Pragma("unroll") for (int k = 0; k < 2; ++k) dst[m][k] = *(const PG8_LAS bf16x8*)(lds + PG8_SA(b, h) + aoff + m * 2048 + k * 1024); } while (0)
; #define PG8_LDB(dst, b, h) do { _Pragma("unroll") for (int n = 0; n < 2; ++n) _Pragma("unroll") for (int k = 0; k < 2; ++k) dst[n][k] = *(const PG8_LAS bf16x8*)(lds + PG8_SB(b, h) + boff + n * 2048 + k * 1024); } while (0)
; #define PG8_WAIT_V(n) asm volatile("s_waitcnt vmcnt(" #n ")" ::: "memory")
; #define PG8_WAIT_L(n) asm volatile("s_waitcnt lgkmcnt(" #n ")" ::: "memory")
; #define PG8_BAR __builtin_amdgcn_s_barrier()
; template <class Epi, class Sched, bool ALIGN_EPI = false, bool SP2 = false, bool ABLK = false>
; __device__ __forceinline__ void gemm_phase(PG8_LAS unsigned char* lds, const Gemm g, const Sched& S, const Epi& E) {
;     ...
;         const char* nA = has_next ? (const char*)g.A + (size_t)nxt.pm * tstep + (size_t)nxt.ko * KOA : cA; const char* nB = has_next ? (const char*)g.Bt + (size_t)nxt.pn * tstep + (size_t)nxt.ko * 32 : cB;
;         for (int t = 0; t < nt; t += 2) {
;             const bool last = (t == nt - 2);
;             const char* a1 = cA + (size_t)(t + 1) * kstep;
;             const char* a2 = last ? nA : cA + (size_t)(t + 2) * kstep; const char* b2 = last ? nB : cB + (size_t)(t + 2) * kstepB;
;             const char* a3 = a2 + kstep; const char* b3 = b2 + kstepB;
;             if (last && has_next) S.a_ready(nxt);
;             if constexpr (SP2) {
;             PG8_LDB(B0, 0, 0); PG8_LDB(B1, 0, 1); PG8_SCHED; PG8_LDA(At, 0, 0); PG8_STAGE(PG8_SA(1, 1), a1 + hstep, voffA);
;             PG8_WAIT_V(8); PG8_WAIT_L(0); PG8_BAR; PG8_MMA(0, 0, At, B0); PG8_MMA(0, 1, At, B1); PG8_BAR; PG8_SCHED;
;             PG8_LDA(At, 0, 1); PG8_STAGE(PG8_SB(0, 0), b2, voffB); PG8_STAGE(PG8_SB(0, 1), b2 + hstep, voffB); PG8_STAGE(PG8_SA(0, 0), a2, voffA);
;             PG8_WAIT_V(8); PG8_WAIT_L(0); PG8_BAR; PG8_MMA(1, 0, At, B0); PG8_MMA(1, 1, At, B1); PG8_BAR; PG8_SCHED;
.LBB0_1657:
	s_or_b32 s26, s94, 1
	s_lshl_b64 s[82:83], s[26:27], 11
	s_add_u32 s88, s74, s82
	v_add_u32_e32 v140, s12, v173
	s_addc_u32 s89, s75, s83
	s_add_i32 s26, s94, 2
	ds_read_b128 v[130:133], v140
	ds_read_b128 v[134:137], v140 offset:1024
	ds_read_b128 v[154:157], v140 offset:2048
	ds_read_b128 v[158:161], v140 offset:3072
	v_add_u32_e32 v140, s13, v173
	s_lshl_b64 s[90:91], s[26:27], 11
	ds_read_b128 v[162:165], v140
	ds_read_b128 v[166:169], v140 offset:1024
	ds_read_b128 v[184:187], v140 offset:2048
	ds_read_b128 v[188:191], v140 offset:3072
	s_add_u32 s92, s74, s90
	s_addc_u32 s93, s75, s91
	s_and_b64 s[82:83], s[80:81], exec
	s_cselect_b32 s83, s93, s3
	s_cselect_b32 s82, s92, s25
	s_add_u32 s90, s76, s90
	s_addc_u32 s91, s77, s91
	s_and_b64 s[80:81], s[80:81], exec
	s_cselect_b32 s81, s91, s65
	s_cselect_b32 s80, s90, s67
	v_lshl_add_u64 v[170:171], s[88:89], 0, v[138:139]
	v_lshl_add_u64 v[224:225], v[170:171], 0, s[20:21]
	s_add_i32 m0, s56, 0xc000
	ds_read_b128 v[192:195], v178
	ds_read_b128 v[196:199], v178 offset:1024
	ds_read_b128 v[200:203], v178 offset:2048
	ds_read_b128 v[204:207], v178 offset:3072
	ds_read_b128 v[208:211], v178 offset:4096
	ds_read_b128 v[212:215], v178 offset:5120
	ds_read_b128 v[216:219], v178 offset:6144
	ds_read_b128 v[220:223], v178 offset:7168
	global_load_lds_dwordx4 v[224:225], off sc1
	v_lshl_add_u64 v[170:171], v[170:171], 0, s[22:23]
	s_add_i32 m0, s56, 0xe000
	s_nop 0
	global_load_lds_dwordx4 v[170:171], off sc1
	s_waitcnt vmcnt(8)
	s_waitcnt lgkmcnt(0)
	s_barrier
	s_setprio 1
	s_waitcnt lgkmcnt(0)
	v_mfma_f32_16x16x32_bf16 v[126:129], v[130:133], v[192:195], v[126:129]
	v_mfma_f32_16x16x32_bf16 v[126:129], v[134:137], v[196:199], v[126:129]
	v_mfma_f32_16x16x32_bf16 v[110:113], v[134:137], v[204:207], v[110:113]
	v_mfma_f32_16x16x32_bf16 v[110:113], v[130:133], v[200:203], v[110:113]
	v_mfma_f32_16x16x32_bf16 v[94:97], v[130:133], v[208:211], v[94:97]
	v_mfma_f32_16x16x32_bf16 v[94:97], v[134:137], v[212:215], v[94:97]
	v_mfma_f32_16x16x32_bf16 v[78:81], v[134:137], v[220:223], v[78:81]
	v_mfma_f32_16x16x32_bf16 v[78:81], v[130:133], v[216:219], v[78:81]
	v_mfma_f32_16x16x32_bf16 v[74:77], v[154:157], v[216:219], v[74:77]
	v_mfma_f32_16x16x32_bf16 v[74:77], v[158:161], v[220:223], v[74:77]
	v_mfma_f32_16x16x32_bf16 v[90:93], v[158:161], v[212:215], v[90:93]
	v_mfma_f32_16x16x32_bf16 v[90:93], v[154:157], v[208:211], v[90:93]
	v_mfma_f32_16x16x32_bf16 v[106:109], v[154:157], v[200:203], v[106:109]
	v_mfma_f32_16x16x32_bf16 v[106:109], v[158:161], v[204:207], v[106:109]
	v_mfma_f32_16x16x32_bf16 v[122:125], v[158:161], v[196:199], v[122:125]
	v_mfma_f32_16x16x32_bf16 v[122:125], v[154:157], v[192:195], v[122:125]
	v_mfma_f32_16x16x32_bf16 v[118:121], v[162:165], v[192:195], v[118:121]
	v_mfma_f32_16x16x32_bf16 v[118:121], v[166:169], v[196:199], v[118:121]
	v_mfma_f32_16x16x32_bf16 v[102:105], v[166:169], v[204:207], v[102:105]
	v_mfma_f32_16x16x32_bf16 v[102:105], v[162:165], v[200:203], v[102:105]
	v_mfma_f32_16x16x32_bf16 v[86:89], v[162:165], v[208:211], v[86:89]
	v_mfma_f32_16x16x32_bf16 v[86:89], v[166:169], v[212:215], v[86:89]
	v_mfma_f32_16x16x32_bf16 v[70:73], v[166:169], v[220:223], v[70:73]
	v_mfma_f32_16x16x32_bf16 v[70:73], v[162:165], v[216:219], v[70:73]
	v_mfma_f32_16x16x32_bf16 v[66:69], v[184:187], v[216:219], v[66:69]
	v_mfma_f32_16x16x32_bf16 v[66:69], v[188:191], v[220:223], v[66:69]
	v_mfma_f32_16x16x32_bf16 v[82:85], v[188:191], v[212:215], v[82:85]
	v_mfma_f32_16x16x32_bf16 v[82:85], v[184:187], v[208:211], v[82:85]
	s_barrier
	s_setprio 2
	v_mfma_f32_16x16x32_bf16 v[98:101], v[184:187], v[200:203], v[98:101]
	v_mfma_f32_16x16x32_bf16 v[98:101], v[188:191], v[204:207], v[98:101]
	v_mfma_f32_16x16x32_bf16 v[114:117], v[188:191], v[196:199], v[114:117]
	v_mfma_f32_16x16x32_bf16 v[114:117], v[184:187], v[192:195], v[114:117]
	s_setprio 0
	v_lshl_add_u64 v[170:171], s[80:81], 0, v[138:139]
	s_add_i32 s80, s12, s55
	s_mov_b32 m0, s80
	ds_read_b128 v[192:195], v178 offset:16384
	ds_read_b128 v[196:199], v178 offset:17408
	ds_read_b128 v[200:203], v178 offset:18432
	ds_read_b128 v[204:207], v178 offset:19456
	ds_read_b128 v[208:211], v178 offset:20480
	ds_read_b128 v[212:215], v178 offset:21504
	ds_read_b128 v[216:219], v178 offset:22528
	ds_read_b128 v[220:223], v178 offset:23552
	global_load_lds_dwordx4 v[170:171], off sc1
	v_lshl_add_u64 v[224:225], v[170:171], 0, s[18:19]
	s_add_i32 m0, s80, 0x2000
	s_add_i32 s80, s13, s55
	global_load_lds_dwordx4 v[224:225], off sc1
	v_lshl_add_u64 v[224:225], v[170:171], 0, s[20:21]
	s_mov_b32 m0, s80
	s_nop 0
	global_load_lds_dwordx4 v[224:225], off sc1
	v_lshl_add_u64 v[224:225], v[170:171], 0, s[22:23]
	s_add_i32 m0, s80, 0x2000
	s_nop 0
	global_load_lds_dwordx4 v[224:225], off sc1
	v_lshl_add_u64 v[224:225], s[82:83], 0, v[138:139]
	s_mov_b32 m0, s56
	v_lshl_add_u64 v[226:227], v[224:225], 0, s[18:19]
	global_load_lds_dwordx4 v[224:225], off sc1
	s_mov_b32 m0, s57
	s_nop 0
	global_load_lds_dwordx4 v[226:227], off sc1
	s_waitcnt vmcnt(8)
	s_waitcnt lgkmcnt(0)
	s_barrier
; #define PG8_STAGE(bufoff, gbase, voff) do { if constexpr (!pg8_noload<Epi>::value) { _Pragma("unroll") for (int _i = 0; _i < 2; ++_i) \
;         __builtin_amdgcn_global_load_lds((const unsigned*)((const char*)(gbase) + (size_t)_i * pstep + (voff)[0]), (PG8_LAS unsigned*)(lds + (bufoff) + ldsw + _i * 8192), 16, 0, 0); } } while (0)
; #define PG8_LDA(dst, b, h) do { _Pragma("unroll") for (int m = 0; m < 4; ++m) _Pragma("unroll") for (int k = 0; k < 2; ++k) dst[m][k] = *(const PG8_LAS bf16x8*)(lds + PG8_SA(b, h) + aoff + m * 2048 + k * 1024); } while (0)
; #define PG8_LDB(dst, b, h) do { _Pragma("unroll") for (int n = 0; n < 2; ++n) _Pragma("unroll") for (int k = 0; k < 2; ++k) dst[n][k] = *(const PG8_LAS bf16x8*)(lds + PG8_SB(b, h) + boff + n * 2048 + k * 1024); } while (0)
; #define PG8_MMA(ai, bj, At, Bt) do { __builtin_amdgcn_s_setprio(1); _Pragma("unroll") for (int m = 0; m < 4; ++m) _Pragma("unroll") for (int n = 0; n < 2; ++n) _Pragma("unroll") for (int k = 0; k < 2; ++k) \
;         acc[ai][bj][m][n] = __builtin_amdgcn_mfma_f32_16x16x32_bf16(Bt[n][k], At[m][k], acc[ai][bj][m][n], 0, 0, 0); __builtin_amdgcn_s_setprio(0); } while (0)
; #define PG8_WAIT_V(n) asm volatile("s_waitcnt vmcnt(" #n ")" ::: "memory")
; #define PG8_WAIT_L(n) asm volatile("s_waitcnt lgkmcnt(" #n ")" ::: "memory")
; #define PG8_BAR __builtin_amdgcn_s_barrier()
; #define PG8_SCHED __builtin_amdgcn_sched_barrier(0)
; template <class Epi, class Sched, bool ALIGN_EPI = false, bool SP2 = false, bool ABLK = false>
; __device__ __forceinline__ void gemm_phase(PG8_LAS unsigned char* lds, const Gemm g, const Sched& S, const Epi& E) {
;     ...
;             PG8_WAIT_V(8); PG8_WAIT_L(0); PG8_BAR; PG8_MMA(1, 0, At, B0); PG8_MMA(1, 1, At, B1); PG8_BAR; PG8_SCHED;
;             PG8_LDB(B0, 1, 0); PG8_LDB(B1, 1, 1); PG8_SCHED; PG8_LDA(At, 1, 0); PG8_STAGE(PG8_SA(0, 1), a2 + hstep, voffA);
;             PG8_WAIT_V(8); PG8_WAIT_L(0); PG8_BAR; PG8_MMA(0, 0, At, B0); PG8_MMA(0, 1, At, B1); PG8_BAR; PG8_SCHED;
	s_setprio 1
	s_waitcnt lgkmcnt(0)
	v_mfma_f32_16x16x32_bf16 v[62:65], v[130:133], v[192:195], v[62:65]
	v_mfma_f32_16x16x32_bf16 v[62:65], v[134:137], v[196:199], v[62:65]
	v_mfma_f32_16x16x32_bf16 v[46:49], v[134:137], v[204:207], v[46:49]
	v_mfma_f32_16x16x32_bf16 v[46:49], v[130:133], v[200:203], v[46:49]
	v_mfma_f32_16x16x32_bf16 v[30:33], v[130:133], v[208:211], v[30:33]
	v_mfma_f32_16x16x32_bf16 v[30:33], v[134:137], v[212:215], v[30:33]
	v_mfma_f32_16x16x32_bf16 v[14:17], v[134:137], v[220:223], v[14:17]
	v_mfma_f32_16x16x32_bf16 v[14:17], v[130:133], v[216:219], v[14:17]
	v_mfma_f32_16x16x32_bf16 v[10:13], v[154:157], v[216:219], v[10:13]
	v_mfma_f32_16x16x32_bf16 v[10:13], v[158:161], v[220:223], v[10:13]
	v_mfma_f32_16x16x32_bf16 v[26:29], v[158:161], v[212:215], v[26:29]
	v_mfma_f32_16x16x32_bf16 v[26:29], v[154:157], v[208:211], v[26:29]
	v_mfma_f32_16x16x32_bf16 v[42:45], v[154:157], v[200:203], v[42:45]
	v_mfma_f32_16x16x32_bf16 v[42:45], v[158:161], v[204:207], v[42:45]
	v_mfma_f32_16x16x32_bf16 v[58:61], v[158:161], v[196:199], v[58:61]
	v_mfma_f32_16x16x32_bf16 v[58:61], v[154:157], v[192:195], v[58:61]
	v_mfma_f32_16x16x32_bf16 v[54:57], v[162:165], v[192:195], v[54:57]
	v_mfma_f32_16x16x32_bf16 v[54:57], v[166:169], v[196:199], v[54:57]
	v_mfma_f32_16x16x32_bf16 v[38:41], v[166:169], v[204:207], v[38:41]
	v_mfma_f32_16x16x32_bf16 v[38:41], v[162:165], v[200:203], v[38:41]
	v_mfma_f32_16x16x32_bf16 v[22:25], v[162:165], v[208:211], v[22:25]
	v_mfma_f32_16x16x32_bf16 v[22:25], v[166:169], v[212:215], v[22:25]
	v_mfma_f32_16x16x32_bf16 v[6:9], v[166:169], v[220:223], v[6:9]
	v_mfma_f32_16x16x32_bf16 v[6:9], v[162:165], v[216:219], v[6:9]
	v_mfma_f32_16x16x32_bf16 v[2:5], v[184:187], v[216:219], v[2:5]
	v_mfma_f32_16x16x32_bf16 v[2:5], v[188:191], v[220:223], v[2:5]
	v_mfma_f32_16x16x32_bf16 v[18:21], v[188:191], v[212:215], v[18:21]
	v_mfma_f32_16x16x32_bf16 v[18:21], v[184:187], v[208:211], v[18:21]
	s_barrier
	s_setprio 2
	v_mfma_f32_16x16x32_bf16 v[34:37], v[184:187], v[200:203], v[34:37]
	v_mfma_f32_16x16x32_bf16 v[34:37], v[188:191], v[204:207], v[34:37]
	v_mfma_f32_16x16x32_bf16 v[50:53], v[188:191], v[196:199], v[50:53]
	v_mfma_f32_16x16x32_bf16 v[50:53], v[184:187], v[192:195], v[50:53]
	s_setprio 0
	s_add_i32 s80, 0, 0x18000
	v_add_u32_e32 v140, s80, v173
	s_add_i32 s81, 0, 0x1c000
	ds_read_b128 v[130:133], v140
	ds_read_b128 v[134:137], v140 offset:1024
	ds_read_b128 v[154:157], v140 offset:2048
	ds_read_b128 v[158:161], v140 offset:3072
	v_add_u32_e32 v140, s81, v173
	ds_read_b128 v[162:165], v140
	ds_read_b128 v[166:169], v140 offset:1024
	ds_read_b128 v[184:187], v140 offset:2048
	ds_read_b128 v[188:191], v140 offset:3072
	s_mov_b32 m0, s58
	v_lshl_add_u64 v[226:227], v[224:225], 0, s[20:21]
	ds_read_b128 v[192:195], v178 offset:32768
	ds_read_b128 v[196:199], v178 offset:33792
	ds_read_b128 v[200:203], v178 offset:34816
	ds_read_b128 v[204:207], v178 offset:35840
	ds_read_b128 v[208:211], v178 offset:36864
	ds_read_b128 v[212:215], v178 offset:37888
	ds_read_b128 v[216:219], v178 offset:38912
	ds_read_b128 v[220:223], v178 offset:39936
	global_load_lds_dwordx4 v[226:227], off sc1
	v_lshl_add_u64 v[226:227], v[224:225], 0, s[22:23]
	s_mov_b32 m0, s59
	s_nop 0
	global_load_lds_dwordx4 v[226:227], off sc1
	s_waitcnt vmcnt(8)
	s_waitcnt lgkmcnt(0)
	s_barrier
	s_setprio 1
	s_waitcnt lgkmcnt(0)
	v_mfma_f32_16x16x32_bf16 v[126:129], v[130:133], v[192:195], v[126:129]
	v_mfma_f32_16x16x32_bf16 v[126:129], v[134:137], v[196:199], v[126:129]
	v_mfma_f32_16x16x32_bf16 v[110:113], v[134:137], v[204:207], v[110:113]
	v_mfma_f32_16x16x32_bf16 v[110:113], v[130:133], v[200:203], v[110:113]
	v_mfma_f32_16x16x32_bf16 v[94:97], v[130:133], v[208:211], v[94:97]
	v_mfma_f32_16x16x32_bf16 v[94:97], v[134:137], v[212:215], v[94:97]
	v_mfma_f32_16x16x32_bf16 v[78:81], v[134:137], v[220:223], v[78:81]
	v_mfma_f32_16x16x32_bf16 v[78:81], v[130:133], v[216:219], v[78:81]
	v_mfma_f32_16x16x32_bf16 v[74:77], v[154:157], v[216:219], v[74:77]
	v_mfma_f32_16x16x32_bf16 v[74:77], v[158:161], v[220:223], v[74:77]
	v_mfma_f32_16x16x32_bf16 v[90:93], v[158:161], v[212:215], v[90:93]
	v_mfma_f32_16x16x32_bf16 v[90:93], v[154:157], v[208:211], v[90:93]
	v_mfma_f32_16x16x32_bf16 v[106:109], v[154:157], v[200:203], v[106:109]
	v_mfma_f32_16x16x32_bf16 v[106:109], v[158:161], v[204:207], v[106:109]
	v_mfma_f32_16x16x32_bf16 v[122:125], v[158:161], v[196:199], v[122:125]
	v_mfma_f32_16x16x32_bf16 v[122:125], v[154:157], v[192:195], v[122:125]
	v_mfma_f32_16x16x32_bf16 v[118:121], v[162:165], v[192:195], v[118:121]
	v_mfma_f32_16x16x32_bf16 v[118:121], v[166:169], v[196:199], v[118:121]
	v_mfma_f32_16x16x32_bf16 v[102:105], v[166:169], v[204:207], v[102:105]
	v_mfma_f32_16x16x32_bf16 v[102:105], v[162:165], v[200:203], v[102:105]
	v_mfma_f32_16x16x32_bf16 v[86:89], v[162:165], v[208:211], v[86:89]
	v_mfma_f32_16x16x32_bf16 v[86:89], v[166:169], v[212:215], v[86:89]
	v_mfma_f32_16x16x32_bf16 v[70:73], v[166:169], v[220:223], v[70:73]
	v_mfma_f32_16x16x32_bf16 v[70:73], v[162:165], v[216:219], v[70:73]
	v_mfma_f32_16x16x32_bf16 v[66:69], v[184:187], v[216:219], v[66:69]
	v_mfma_f32_16x16x32_bf16 v[66:69], v[188:191], v[220:223], v[66:69]
	v_mfma_f32_16x16x32_bf16 v[82:85], v[188:191], v[212:215], v[82:85]
	v_mfma_f32_16x16x32_bf16 v[82:85], v[184:187], v[208:211], v[82:85]
	s_barrier
; #define PG8_STAGE(bufoff, gbase, voff) do { if constexpr (!pg8_noload<Epi>::value) { _Pragma("unroll") for (int _i = 0; _i < 2; ++_i) \
;         __builtin_amdgcn_global_load_lds((const unsigned*)((const char*)(gbase) + (size_t)_i * pstep + (voff)[0]), (PG8_LAS unsigned*)(lds + (bufoff) + ldsw + _i * 8192), 16, 0, 0); } } while (0)
; #define PG8_LDA(dst, b, h) do { _Pragma("unroll") for (int m = 0; m < 4; ++m) _Pragma("unroll") for (int k = 0; k < 2; ++k) dst[m][k] = *(const PG8_LAS bf16x8*)(lds + PG8_SA(b, h) + aoff + m * 2048 + k * 1024); } while (0)
; #define PG8_MMA(ai, bj, At, Bt) do { __builtin_amdgcn_s_setprio(1); _Pragma("unroll") for (int m = 0; m < 4; ++m) _Pragma("unroll") for (int n = 0; n < 2; ++n) _Pragma("unroll") for (int k = 0; k < 2; ++k) \
;         acc[ai][bj][m][n] = __builtin_amdgcn_mfma_f32_16x16x32_bf16(Bt[n][k], At[m][k], acc[ai][bj][m][n], 0, 0, 0); __builtin_amdgcn_s_setprio(0); } while (0)
; #define PG8_WAIT_V(n) asm volatile("s_waitcnt vmcnt(" #n ")" ::: "memory")
; #define PG8_WAIT_L(n) asm volatile("s_waitcnt lgkmcnt(" #n ")" ::: "memory")
; #define PG8_BAR __builtin_amdgcn_s_barrier()
; #define PG8_SCHED __builtin_amdgcn_sched_barrier(0)
; template <class Epi, class Sched, bool ALIGN_EPI = false, bool SP2 = false, bool ABLK = false>
; __device__ __forceinline__ void gemm_phase(PG8_LAS unsigned char* lds, const Gemm g, const Sched& S, const Epi& E) {
;     ...
;             PG8_WAIT_V(8); PG8_WAIT_L(0); PG8_BAR; PG8_MMA(0, 0, At, B0); PG8_MMA(0, 1, At, B1); PG8_BAR; PG8_SCHED;
;             PG8_LDA(At, 1, 1); PG8_STAGE(PG8_SB(1, 0), b3, voffB); PG8_STAGE(PG8_SB(1, 1), b3 + hstep, voffB); PG8_STAGE(PG8_SA(1, 0), a3, voffA);
;             PG8_WAIT_V(8); PG8_WAIT_L(0); PG8_BAR; PG8_MMA(1, 0, At, B0); PG8_MMA(1, 1, At, B1); PG8_BAR; PG8_SCHED;
	s_setprio 2
	v_mfma_f32_16x16x32_bf16 v[98:101], v[184:187], v[200:203], v[98:101]
	v_mfma_f32_16x16x32_bf16 v[98:101], v[188:191], v[204:207], v[98:101]
	v_mfma_f32_16x16x32_bf16 v[114:117], v[188:191], v[196:199], v[114:117]
	v_mfma_f32_16x16x32_bf16 v[114:117], v[184:187], v[192:195], v[114:117]
	s_setprio 0
	s_add_i32 s80, s80, s55
	v_lshl_add_u64 v[226:227], v[170:171], 0, s[30:31]
	s_mov_b32 m0, s80
	ds_read_b128 v[192:195], v178 offset:49152
	ds_read_b128 v[196:199], v178 offset:50176
	ds_read_b128 v[200:203], v178 offset:51200
	ds_read_b128 v[204:207], v178 offset:52224
	ds_read_b128 v[208:211], v178 offset:53248
	ds_read_b128 v[212:215], v178 offset:54272
	ds_read_b128 v[216:219], v178 offset:55296
	ds_read_b128 v[220:223], v178 offset:56320
	global_load_lds_dwordx4 v[226:227], off sc1
	v_lshl_add_u64 v[226:227], v[170:171], 0, s[34:35]
	s_add_i32 m0, s80, 0x2000
	s_add_i32 s80, s81, s55
	global_load_lds_dwordx4 v[226:227], off sc1
	v_lshl_add_u64 v[226:227], v[170:171], 0, s[36:37]
	s_mov_b32 m0, s80
	v_lshl_add_u64 v[170:171], v[170:171], 0, s[38:39]
	global_load_lds_dwordx4 v[226:227], off sc1
	s_add_i32 m0, s80, 0x2000
	s_nop 0
	global_load_lds_dwordx4 v[170:171], off sc1
	v_lshl_add_u64 v[170:171], v[224:225], 0, s[30:31]
	s_mov_b32 m0, s63
	s_nop 0
	global_load_lds_dwordx4 v[170:171], off sc1
	v_lshl_add_u64 v[170:171], v[224:225], 0, s[34:35]
	s_mov_b32 m0, s73
	s_nop 0
	global_load_lds_dwordx4 v[170:171], off sc1
	s_waitcnt vmcnt(8)
	s_waitcnt lgkmcnt(0)
	s_barrier
	s_setprio 1
	s_waitcnt lgkmcnt(0)
	v_mfma_f32_16x16x32_bf16 v[62:65], v[130:133], v[192:195], v[62:65]
	v_mfma_f32_16x16x32_bf16 v[62:65], v[134:137], v[196:199], v[62:65]
	v_mfma_f32_16x16x32_bf16 v[46:49], v[134:137], v[204:207], v[46:49]
	v_mfma_f32_16x16x32_bf16 v[46:49], v[130:133], v[200:203], v[46:49]
	v_mfma_f32_16x16x32_bf16 v[30:33], v[130:133], v[208:211], v[30:33]
	v_mfma_f32_16x16x32_bf16 v[30:33], v[134:137], v[212:215], v[30:33]
	v_mfma_f32_16x16x32_bf16 v[14:17], v[134:137], v[220:223], v[14:17]
	v_mfma_f32_16x16x32_bf16 v[14:17], v[130:133], v[216:219], v[14:17]
	v_mfma_f32_16x16x32_bf16 v[10:13], v[154:157], v[216:219], v[10:13]
	v_mfma_f32_16x16x32_bf16 v[10:13], v[158:161], v[220:223], v[10:13]
	v_mfma_f32_16x16x32_bf16 v[26:29], v[158:161], v[212:215], v[26:29]
	v_mfma_f32_16x16x32_bf16 v[26:29], v[154:157], v[208:211], v[26:29]
	v_mfma_f32_16x16x32_bf16 v[42:45], v[154:157], v[200:203], v[42:45]
	v_mfma_f32_16x16x32_bf16 v[42:45], v[158:161], v[204:207], v[42:45]
	v_mfma_f32_16x16x32_bf16 v[58:61], v[158:161], v[196:199], v[58:61]
	v_mfma_f32_16x16x32_bf16 v[58:61], v[154:157], v[192:195], v[58:61]
	v_mfma_f32_16x16x32_bf16 v[54:57], v[162:165], v[192:195], v[54:57]
	v_mfma_f32_16x16x32_bf16 v[54:57], v[166:169], v[196:199], v[54:57]
	v_mfma_f32_16x16x32_bf16 v[38:41], v[166:169], v[204:207], v[38:41]
	v_mfma_f32_16x16x32_bf16 v[38:41], v[162:165], v[200:203], v[38:41]
	v_mfma_f32_16x16x32_bf16 v[22:25], v[162:165], v[208:211], v[22:25]
	v_mfma_f32_16x16x32_bf16 v[22:25], v[166:169], v[212:215], v[22:25]
	v_mfma_f32_16x16x32_bf16 v[6:9], v[166:169], v[220:223], v[6:9]
	v_mfma_f32_16x16x32_bf16 v[6:9], v[162:165], v[216:219], v[6:9]
	v_mfma_f32_16x16x32_bf16 v[2:5], v[184:187], v[216:219], v[2:5]
	v_mfma_f32_16x16x32_bf16 v[2:5], v[188:191], v[220:223], v[2:5]
	v_mfma_f32_16x16x32_bf16 v[18:21], v[188:191], v[212:215], v[18:21]
	v_mfma_f32_16x16x32_bf16 v[18:21], v[184:187], v[208:211], v[18:21]
	s_barrier
	s_setprio 2
	v_mfma_f32_16x16x32_bf16 v[34:37], v[184:187], v[200:203], v[34:37]
	v_mfma_f32_16x16x32_bf16 v[34:37], v[188:191], v[204:207], v[34:37]
	v_mfma_f32_16x16x32_bf16 v[50:53], v[188:191], v[196:199], v[50:53]
	v_mfma_f32_16x16x32_bf16 v[50:53], v[184:187], v[192:195], v[50:53]
	s_setprio 0
	s_cmp_gt_u32 s94, 29
	s_mov_b32 s94, s26
	s_cbranch_scc1 .LBB0_1669

; #define PG8_WAIT_V(n) asm volatile("s_waitcnt vmcnt(" #n ")" ::: "memory")
; #define PG8_BAR __builtin_amdgcn_s_barrier()
; template <class Epi, class Sched, bool ALIGN_EPI = false, bool SP2 = false, bool ABLK = false>
; __device__ __forceinline__ void gemm_phase(PG8_LAS unsigned char* lds, const Gemm g, const Sched& S, const Epi& E) {
;     const int tid = threadIdx.x, wid = __builtin_amdgcn_readfirstlane(tid >> 6), lane = tid & 63, wr = wid >> 2, wc = wid & 3, fr = lane & 15, fq = lane >> 4;
;     const int K = g.K;
;     unsigned voffA[2], voffB[2];
; #pragma unroll
;     for (int i = 0; i < 2; ++i) { int R, C; stage_rc(tid * 16 + i * 8192, R, C); const int Rb = Epi::PERM ? ((R & ~31) + perm32(R & 31)) : R;
;         voffA[i] = (unsigned)(R * K + C) * 2u; (void)Rb;
;         if constexpr (ABLK) { const int st = (tid >> 6) + 8 * i; voffA[i] = (unsigned)(((st >> 1) * (K / 32) + (st & 1)) * 1024 + (tid & 63) * 16); }
;         { static_assert(Epi::PERM, "blocked weight copies are written in permuted row-slot order"); const int st = (tid >> 6) + 8 * i; voffB[i] = (unsigned)(((st >> 1) * (K / 32) + (st & 1)) * 1024 + (tid & 63) * 16); } }
;     const size_t kstep = ABLK ? (size_t)(BK / 32) * 1024 : (size_t)(BK * 2);
;     constexpr int KOA = ABLK ? 32 : 2;
;     const size_t pstep = (size_t)K * 128;
;     const size_t kstepB = (size_t)(BK / 32) * 1024;
;     const size_t hstep = (size_t)HALF * K * 2;
;     const size_t tstep = 2 * hstep;
;     const unsigned ldsw = (unsigned)wid * 1024u;
;     const int aoff = lds_byte(wr * 64 + fr, fq * 8), boff = lds_byte(wc * 32 + fr, fq * 8);
;     ...
;     const char* cA = (const char*)g.A + (size_t)cur.pm * tstep + (size_t)cur.ko * KOA; const char* cB = (const char*)g.Bt + (size_t)cur.pn * tstep + (size_t)cur.ko * 32; int nt = cur.nt;
;     S.a_ready(cur);
;     if constexpr (SP2) {
;         PG8_STAGE(PG8_SB(0, 0), cB, voffB); PG8_STAGE(PG8_SB(0, 1), cB + hstep, voffB); PG8_STAGE(PG8_SA(0, 0), cA, voffA); PG8_STAGE(PG8_SA(0, 1), cA + hstep, voffA);
;         if (wr == 1) PG8_BAR;
;         PG8_WAIT_V(2); PG8_BAR;
;         PG8_STAGE(PG8_SB(1, 0), cB + kstepB, voffB); PG8_STAGE(PG8_SA(1, 0), cA + kstep, voffA); PG8_STAGE(PG8_SB(1, 1), cB + hstep + kstepB, voffB);
;         PG8_WAIT_V(6); PG8_BAR;
.LBB0_1977:
	s_andn2_b64 vcc, exec, s[4:5]
	s_cbranch_vccnz .LBB0_2026
	s_add_u32 s33, s86, 0x2bc00000
	s_addc_u32 s54, s87, 0
	s_add_u32 s55, s86, 0xe200000
	v_and_b32_e32 v6, 1, v183
	v_lshrrev_b32_e32 v1, 1, v0
	s_movk_i32 s3, 0xc0
	s_addc_u32 s56, s87, 0
	v_and_or_b32 v2, v1, s3, v6
	s_ashr_i32 s3, s2, 31
	s_ashr_i32 s49, s48, 31
	s_ashr_i32 s11, s10, 31
	s_ashr_i32 s6, s8, 2
	s_lshl_b32 s57, s8, 10
	s_lshl_b64 s[4:5], s[2:3], 20
	s_lshl_b64 s[18:19], s[48:49], 5
	s_lshl_b64 s[12:13], s[10:11], 20
	s_add_u32 s3, s55, s12
	s_addc_u32 s7, s56, s13
	s_add_u32 s62, s3, s18
	v_lshlrev_b32_e32 v7, 4, v182
	s_addc_u32 s63, s7, s19
	s_add_i32 s49, s57, 0
	v_lshl_or_b32 v162, v2, 10, v7
	v_mov_b32_e32 v163, 0
	s_add_i32 m0, s49, 0x10000
	s_waitcnt lgkmcnt(0)
	v_lshl_add_u64 v[2:3], s[62:63], 0, v[162:163]
	global_load_lds_dwordx4 v162, s[62:63]
	s_mov_b64 s[12:13], 0x40000
	s_add_i32 m0, s49, 0x12000
	v_lshl_add_u64 v[4:5], v[2:3], 0, s[12:13]
	s_add_u32 s3, s33, s4
	s_mov_b64 s[14:15], 0x80000
	global_load_lds_dwordx4 v[4:5], off sc1
	s_addc_u32 s4, s54, s5
	v_lshl_add_u64 v[4:5], v[2:3], 0, s[14:15]
	s_add_i32 m0, s49, 0x14000
	s_mov_b64 s[16:17], 0xc0000
	global_load_lds_dwordx4 v[4:5], off sc1
	s_add_i32 m0, s49, 0x16000
	s_add_u32 s52, s3, s18
	v_lshl_add_u64 v[4:5], v[2:3], 0, s[16:17]
	s_addc_u32 s53, s4, s19
	global_load_lds_dwordx4 v[4:5], off sc1
	v_lshl_add_u64 v[4:5], s[52:53], 0, v[162:163]
	s_mov_b32 m0, s49
	s_add_i32 s58, s49, 0x2000
	global_load_lds_dwordx4 v162, s[52:53]
	v_lshl_add_u64 v[8:9], v[4:5], 0, s[12:13]
	s_mov_b32 m0, s58
	s_add_i32 s59, s49, 0x4000
	global_load_lds_dwordx4 v[8:9], off sc1
	v_lshl_add_u64 v[8:9], v[4:5], 0, s[14:15]
	s_mov_b32 m0, s59
	s_add_i32 s60, s49, 0x6000
	global_load_lds_dwordx4 v[8:9], off sc1
	v_lshl_add_u64 v[8:9], v[4:5], 0, s[16:17]
	s_mov_b32 m0, s60
	s_cmp_eq_u32 s6, 1
	global_load_lds_dwordx4 v[8:9], off sc1
	s_cselect_b64 s[18:19], -1, 0
	s_cmp_lg_u32 s6, 1
	s_mov_b32 s21, 0
	s_cbranch_scc1 .LBB0_1980
	s_barrier
.LBB0_1980:
	s_add_u32 s22, s86, 0x40000
	s_addc_u32 s23, s87, 0
	s_add_u32 s61, s86, 0x34a00000
	s_mov_b64 s[24:25], 0x800
	s_addc_u32 s64, s87, 0
	v_lshl_add_u64 v[8:9], v[2:3], 0, s[24:25]
	s_add_i32 m0, s49, 0x18000
	s_mov_b64 s[26:27], 0x40800
	s_waitcnt vmcnt(2)
	s_barrier
	global_load_lds_dwordx4 v[8:9], off sc1
	v_lshl_add_u64 v[8:9], v[2:3], 0, s[26:27]
	s_add_i32 m0, s49, 0x1a000
	s_add_i32 s65, s49, 0x8000
	global_load_lds_dwordx4 v[8:9], off sc1
	v_lshl_add_u64 v[8:9], v[4:5], 0, s[24:25]
	s_mov_b32 m0, s65
	s_add_i32 s66, s49, 0xa000
	global_load_lds_dwordx4 v[8:9], off sc1
	v_lshl_add_u64 v[4:5], v[4:5], 0, s[26:27]
	s_mov_b32 m0, s66
	s_mov_b64 s[28:29], 0x80800
	global_load_lds_dwordx4 v[4:5], off sc1
	v_lshl_add_u64 v[4:5], v[2:3], 0, s[28:29]
	s_add_i32 m0, s49, 0x1c000
	s_mov_b64 s[30:31], 0xc0800
	global_load_lds_dwordx4 v[4:5], off sc1
	v_lshl_add_u64 v[2:3], v[2:3], 0, s[30:31]
	s_add_i32 m0, s49, 0x1e000
	v_and_b32_e32 v9, 48, v0
	global_load_lds_dwordx4 v[2:3], off sc1
	v_and_b32_e32 v3, 15, v0
	v_lshlrev_b32_e32 v2, 6, v3
	v_lshlrev_b32_e32 v5, 2, v0
	v_and_b32_e32 v4, 24, v1
	v_or_b32_e32 v1, v2, v9
	s_lshl_b32 s4, s6, 13
	v_and_b32_e32 v10, 32, v5
	s_and_b32 s3, s8, 3
	v_bitop3_b32 v11, v1, s4, v10 bitop3:0xde
	v_lshlrev_b32_e32 v1, 6, v0
	s_movk_i32 s4, 0x3c0
	v_and_or_b32 v1, v1, s4, v9
	s_lshl_b32 s4, s3, 12
	s_cmp_lt_u32 s8, 4
	v_lshl_or_b32 v8, s6, 6, v3
	s_cselect_b64 s[34:35], -1, 0
	s_lshl_b32 s11, s6, 10
	s_lshl_b32 s6, s8, 6
	v_bitop3_b32 v1, s4, v1, v10 bitop3:0xf6
	v_lshlrev_b32_e32 v10, 4, v3
	v_or3_b32 v173, s6, v9, v3
	v_mov_b32_e32 v3, v163
	v_lshl_or_b32 v172, s3, 5, v4
	v_bitop3_b32 v4, v5, v9, 32 bitop3:0x6c
	v_mov_b32_e32 v5, v163
	v_lshl_add_u64 v[2:3], s[86:87], 0, v[2:3]
	s_and_b32 s67, s8, -4
	v_lshl_add_u64 v[2:3], v[2:3], 0, v[4:5]
	s_mov_b64 s[8:9], 0x16e00000
	s_lshl_b32 s20, s3, 1
	v_lshl_add_u64 v[164:165], v[2:3], 0, s[8:9]
	s_lshl_b32 s3, s3, 2
	v_lshlrev_b32_e32 v2, 9, v0
	v_lshlrev_b32_e32 v9, 4, v173
	s_add_i32 s3, s3, 0
	v_and_b32_e32 v2, 0x30000, v2
	v_lshlrev_b32_e32 v3, 10, v6
	s_waitcnt vmcnt(6)
	s_add_i32 s3, s3, s11
	v_or3_b32 v166, v2, v3, v7
	v_add_u32_e32 v2, 0, v9
	s_movk_i32 s6, 0x100
	s_add_i32 s3, s3, 0x20800
	s_add_i32 s70, 0, 0x10000
	s_add_i32 s71, 0, 0x14000
	v_add_u32_e32 v178, 0x20800, v2
	v_mbcnt_lo_u32_b32 v2, -1, 0
	v_cmp_gt_u32_e64 s[4:5], 16, v182
	v_cmp_gt_i32_e64 s[6:7], s6, v173
	s_ashr_i32 s68, s97, 31
	s_ashr_i32 s69, s82, 31
	v_add_u32_e32 v174, 0xffffc000, v8
	v_mov_b32_e32 v167, v163
	v_mov_b64_e32 v[168:169], 0x1ff
	v_add_u32_e32 v175, s70, v1
	v_add_u32_e32 v176, s71, v1
	v_add_u32_e32 v177, 0, v11
	s_mov_b32 s72, 0x20000
	s_mov_b64 s[36:37], 0xb0400
	v_mbcnt_hi_u32_b32 v179, -1, v2
	v_add_u32_e32 v180, s3, v10
	s_mov_b32 s73, s21
	s_barrier
	s_branch .LBB0_1983

; #define PG8_STAGE(bufoff, gbase, voff) do { if constexpr (!pg8_noload<Epi>::value) { _Pragma("unroll") for (int _i = 0; _i < 2; ++_i) \
;         __builtin_amdgcn_global_load_lds((const unsigned*)((const char*)(gbase) + (size_t)_i * pstep + (voff)[0]), (PG8_LAS unsigned*)(lds + (bufoff) + ldsw + _i * 8192), 16, 0, 0); } } while (0)
; #define PG8_LDA(dst, b, h) do { _Pragma("unroll") for (int m = 0; m < 4; ++m) _Pragma("unroll") for (int k = 0; k < 2; ++k) dst[m][k] = *(const PG8_LAS bf16x8*)(lds + PG8_SA(b, h) + aoff + m * 2048 + k * 1024); } while (0)
; #define PG8_LDB(dst, b, h) do { _Pragma("unroll") for (int n = 0; n < 2; ++n) _Pragma("unroll") for (int k = 0; k < 2; ++k) dst[n][k] = *(const PG8_LAS bf16x8*)(lds + PG8_SB(b, h) + boff + n * 2048 + k * 1024); } while (0)
; #define PG8_WAIT_V(n) asm volatile("s_waitcnt vmcnt(" #n ")" ::: "memory")
; #define PG8_WAIT_L(n) asm volatile("s_waitcnt lgkmcnt(" #n ")" ::: "memory")
; #define PG8_BAR __builtin_amdgcn_s_barrier()
; template <class Epi, class Sched, bool ALIGN_EPI = false, bool SP2 = false, bool ABLK = false>
; __device__ __forceinline__ void gemm_phase(PG8_LAS unsigned char* lds, const Gemm g, const Sched& S, const Epi& E) {
;     ...
;         const char* nA = has_next ? (const char*)g.A + (size_t)nxt.pm * tstep + (size_t)nxt.ko * KOA : cA; const char* nB = has_next ? (const char*)g.Bt + (size_t)nxt.pn * tstep + (size_t)nxt.ko * 32 : cB;
;         for (int t = 0; t < nt; t += 2) {
;             const bool last = (t == nt - 2);
;             const char* a1 = cA + (size_t)(t + 1) * kstep;
;             const char* a2 = last ? nA : cA + (size_t)(t + 2) * kstep; const char* b2 = last ? nB : cB + (size_t)(t + 2) * kstepB;
;             const char* a3 = a2 + kstep; const char* b3 = b2 + kstepB;
;             if (last && has_next) S.a_ready(nxt);
;             if constexpr (SP2) {
;             PG8_LDB(B0, 0, 0); PG8_LDB(B1, 0, 1); PG8_SCHED; PG8_LDA(At, 0, 0); PG8_STAGE(PG8_SA(1, 1), a1 + hstep, voffA);
;             PG8_WAIT_V(8); PG8_WAIT_L(0); PG8_BAR; PG8_MMA(0, 0, At, B0); PG8_MMA(0, 1, At, B1); PG8_BAR; PG8_SCHED;
;             PG8_LDA(At, 0, 1); PG8_STAGE(PG8_SB(0, 0), b2, voffB); PG8_STAGE(PG8_SB(0, 1), b2 + hstep, voffB); PG8_STAGE(PG8_SA(0, 0), a2, voffA);
;             PG8_WAIT_V(8); PG8_WAIT_L(0); PG8_BAR; PG8_MMA(1, 0, At, B0); PG8_MMA(1, 1, At, B1); PG8_BAR; PG8_SCHED;
.LBB0_1997:
	ds_read_b128 v[130:133], v175
	ds_read_b128 v[134:137], v175 offset:1024
	ds_read_b128 v[138:141], v175 offset:2048
	ds_read_b128 v[142:145], v175 offset:3072
	ds_read_b128 v[146:149], v176
	ds_read_b128 v[150:153], v176 offset:1024
	ds_read_b128 v[154:157], v176 offset:2048
	ds_read_b128 v[158:161], v176 offset:3072
	s_add_i32 s43, s41, 2
	s_add_u32 s62, s52, 0xfff80800
	s_addc_u32 s63, s53, -1
	s_cmp_eq_u32 s3, s41
	s_cselect_b32 s63, s45, s63
	s_cselect_b32 s62, s44, s62
	s_cselect_b32 s77, s47, s39
	s_cselect_b32 s76, s46, s11
	v_lshl_add_u64 v[170:171], s[52:53], 0, v[166:167]
	s_add_i32 m0, s49, 0xc000
	ds_read_b128 v[184:187], v177
	ds_read_b128 v[188:191], v177 offset:1024
	ds_read_b128 v[192:195], v177 offset:2048
	ds_read_b128 v[196:199], v177 offset:3072
	ds_read_b128 v[200:203], v177 offset:4096
	ds_read_b128 v[204:207], v177 offset:5120
	ds_read_b128 v[208:211], v177 offset:6144
	ds_read_b128 v[212:215], v177 offset:7168
	global_load_lds_dwordx4 v[170:171], off sc1
	v_lshl_add_u64 v[170:171], v[170:171], 0, s[12:13]
	s_add_i32 m0, s49, 0xe000
	s_nop 0
	global_load_lds_dwordx4 v[170:171], off sc1
	s_waitcnt vmcnt(8)
	s_waitcnt lgkmcnt(0)
	s_barrier
	s_setprio 1
	s_waitcnt lgkmcnt(0)
	v_mfma_f32_16x16x32_bf16 v[126:129], v[130:133], v[184:187], v[126:129]
	v_mfma_f32_16x16x32_bf16 v[126:129], v[134:137], v[188:191], v[126:129]
	v_mfma_f32_16x16x32_bf16 v[110:113], v[134:137], v[196:199], v[110:113]
	v_mfma_f32_16x16x32_bf16 v[110:113], v[130:133], v[192:195], v[110:113]
	v_mfma_f32_16x16x32_bf16 v[94:97], v[130:133], v[200:203], v[94:97]
	v_mfma_f32_16x16x32_bf16 v[94:97], v[134:137], v[204:207], v[94:97]
	v_mfma_f32_16x16x32_bf16 v[78:81], v[134:137], v[212:215], v[78:81]
	v_mfma_f32_16x16x32_bf16 v[78:81], v[130:133], v[208:211], v[78:81]
	v_mfma_f32_16x16x32_bf16 v[74:77], v[138:141], v[208:211], v[74:77]
	v_mfma_f32_16x16x32_bf16 v[74:77], v[142:145], v[212:215], v[74:77]
	v_mfma_f32_16x16x32_bf16 v[90:93], v[142:145], v[204:207], v[90:93]
	v_mfma_f32_16x16x32_bf16 v[90:93], v[138:141], v[200:203], v[90:93]
	v_mfma_f32_16x16x32_bf16 v[106:109], v[138:141], v[192:195], v[106:109]
	v_mfma_f32_16x16x32_bf16 v[106:109], v[142:145], v[196:199], v[106:109]
	v_mfma_f32_16x16x32_bf16 v[122:125], v[142:145], v[188:191], v[122:125]
	v_mfma_f32_16x16x32_bf16 v[122:125], v[138:141], v[184:187], v[122:125]
	v_mfma_f32_16x16x32_bf16 v[118:121], v[146:149], v[184:187], v[118:121]
	v_mfma_f32_16x16x32_bf16 v[118:121], v[150:153], v[188:191], v[118:121]
	v_mfma_f32_16x16x32_bf16 v[102:105], v[150:153], v[196:199], v[102:105]
	v_mfma_f32_16x16x32_bf16 v[102:105], v[146:149], v[192:195], v[102:105]
	v_mfma_f32_16x16x32_bf16 v[86:89], v[146:149], v[200:203], v[86:89]
	v_mfma_f32_16x16x32_bf16 v[86:89], v[150:153], v[204:207], v[86:89]
	v_mfma_f32_16x16x32_bf16 v[70:73], v[150:153], v[212:215], v[70:73]
	v_mfma_f32_16x16x32_bf16 v[70:73], v[146:149], v[208:211], v[70:73]
	v_mfma_f32_16x16x32_bf16 v[66:69], v[154:157], v[208:211], v[66:69]
	v_mfma_f32_16x16x32_bf16 v[66:69], v[158:161], v[212:215], v[66:69]
	v_mfma_f32_16x16x32_bf16 v[82:85], v[158:161], v[204:207], v[82:85]
	v_mfma_f32_16x16x32_bf16 v[82:85], v[154:157], v[200:203], v[82:85]
	s_barrier
	s_setprio 2
	v_mfma_f32_16x16x32_bf16 v[98:101], v[154:157], v[192:195], v[98:101]
	v_mfma_f32_16x16x32_bf16 v[98:101], v[158:161], v[196:199], v[98:101]
	v_mfma_f32_16x16x32_bf16 v[114:117], v[158:161], v[188:191], v[114:117]
	v_mfma_f32_16x16x32_bf16 v[114:117], v[154:157], v[184:187], v[114:117]
	s_setprio 0
	s_add_i32 s41, s70, s57
	v_lshl_add_u64 v[170:171], s[76:77], 0, v[162:163]
	s_mov_b32 m0, s41
	ds_read_b128 v[184:187], v177 offset:16384
	ds_read_b128 v[188:191], v177 offset:17408
	ds_read_b128 v[192:195], v177 offset:18432
	ds_read_b128 v[196:199], v177 offset:19456
	ds_read_b128 v[200:203], v177 offset:20480
	ds_read_b128 v[204:207], v177 offset:21504
	ds_read_b128 v[208:211], v177 offset:22528
	ds_read_b128 v[212:215], v177 offset:23552
	global_load_lds_dwordx4 v[170:171], off sc1
	v_lshl_add_u64 v[216:217], v[170:171], 0, s[12:13]
	s_add_i32 m0, s41, 0x2000
	s_add_i32 s41, s71, s57
	global_load_lds_dwordx4 v[216:217], off sc1
	v_lshl_add_u64 v[216:217], v[170:171], 0, s[14:15]
	s_mov_b32 m0, s41
	s_nop 0
	global_load_lds_dwordx4 v[216:217], off sc1
	v_lshl_add_u64 v[216:217], v[170:171], 0, s[16:17]
	s_add_i32 m0, s41, 0x2000
	s_nop 0
	global_load_lds_dwordx4 v[216:217], off sc1
	v_lshl_add_u64 v[216:217], s[62:63], 0, v[162:163]
	s_mov_b32 m0, s49
	v_lshl_add_u64 v[218:219], v[216:217], 0, s[12:13]
	global_load_lds_dwordx4 v[216:217], off sc1
	s_mov_b32 m0, s58
	s_nop 0
	global_load_lds_dwordx4 v[218:219], off sc1
	s_waitcnt vmcnt(8)
	s_waitcnt lgkmcnt(0)
	s_barrier
; #define PG8_STAGE(bufoff, gbase, voff) do { if constexpr (!pg8_noload<Epi>::value) { _Pragma("unroll") for (int _i = 0; _i < 2; ++_i) \
;         __builtin_amdgcn_global_load_lds((const unsigned*)((const char*)(gbase) + (size_t)_i * pstep + (voff)[0]), (PG8_LAS unsigned*)(lds + (bufoff) + ldsw + _i * 8192), 16, 0, 0); } } while (0)
; #define PG8_LDA(dst, b, h) do { _Pragma("unroll") for (int m = 0; m < 4; ++m) _Pragma("unroll") for (int k = 0; k < 2; ++k) dst[m][k] = *(const PG8_LAS bf16x8*)(lds + PG8_SA(b, h) + aoff + m * 2048 + k * 1024); } while (0)
; #define PG8_LDB(dst, b, h) do { _Pragma("unroll") for (int n = 0; n < 2; ++n) _Pragma("unroll") for (int k = 0; k < 2; ++k) dst[n][k] = *(const PG8_LAS bf16x8*)(lds + PG8_SB(b, h) + boff + n * 2048 + k * 1024); } while (0)
; #define PG8_MMA(ai, bj, At, Bt) do { __builtin_amdgcn_s_setprio(1); _Pragma("unroll") for (int m = 0; m < 4; ++m) _Pragma("unroll") for (int n = 0; n < 2; ++n) _Pragma("unroll") for (int k = 0; k < 2; ++k) \
;         acc[ai][bj][m][n] = __builtin_amdgcn_mfma_f32_16x16x32_bf16(Bt[n][k], At[m][k], acc[ai][bj][m][n], 0, 0, 0); __builtin_amdgcn_s_setprio(0); } while (0)
; #define PG8_WAIT_V(n) asm volatile("s_waitcnt vmcnt(" #n ")" ::: "memory")
; #define PG8_WAIT_L(n) asm volatile("s_waitcnt lgkmcnt(" #n ")" ::: "memory")
; #define PG8_BAR __builtin_amdgcn_s_barrier()
; #define PG8_SCHED __builtin_amdgcn_sched_barrier(0)
; template <class Epi, class Sched, bool ALIGN_EPI = false, bool SP2 = false, bool ABLK = false>
; __device__ __forceinline__ void gemm_phase(PG8_LAS unsigned char* lds, const Gemm g, const Sched& S, const Epi& E) {
;     ...
;             PG8_WAIT_V(8); PG8_WAIT_L(0); PG8_BAR; PG8_MMA(1, 0, At, B0); PG8_MMA(1, 1, At, B1); PG8_BAR; PG8_SCHED;
;             PG8_LDB(B0, 1, 0); PG8_LDB(B1, 1, 1); PG8_SCHED; PG8_LDA(At, 1, 0); PG8_STAGE(PG8_SA(0, 1), a2 + hstep, voffA);
;             PG8_WAIT_V(8); PG8_WAIT_L(0); PG8_BAR; PG8_MMA(0, 0, At, B0); PG8_MMA(0, 1, At, B1); PG8_BAR; PG8_SCHED;
	s_setprio 1
	s_waitcnt lgkmcnt(0)
	v_mfma_f32_16x16x32_bf16 v[62:65], v[130:133], v[184:187], v[62:65]
	v_mfma_f32_16x16x32_bf16 v[62:65], v[134:137], v[188:191], v[62:65]
	v_mfma_f32_16x16x32_bf16 v[46:49], v[134:137], v[196:199], v[46:49]
	v_mfma_f32_16x16x32_bf16 v[46:49], v[130:133], v[192:195], v[46:49]
	v_mfma_f32_16x16x32_bf16 v[30:33], v[130:133], v[200:203], v[30:33]
	v_mfma_f32_16x16x32_bf16 v[30:33], v[134:137], v[204:207], v[30:33]
	v_mfma_f32_16x16x32_bf16 v[14:17], v[134:137], v[212:215], v[14:17]
	v_mfma_f32_16x16x32_bf16 v[14:17], v[130:133], v[208:211], v[14:17]
	v_mfma_f32_16x16x32_bf16 v[10:13], v[138:141], v[208:211], v[10:13]
	v_mfma_f32_16x16x32_bf16 v[10:13], v[142:145], v[212:215], v[10:13]
	v_mfma_f32_16x16x32_bf16 v[26:29], v[142:145], v[204:207], v[26:29]
	v_mfma_f32_16x16x32_bf16 v[26:29], v[138:141], v[200:203], v[26:29]
	v_mfma_f32_16x16x32_bf16 v[42:45], v[138:141], v[192:195], v[42:45]
	v_mfma_f32_16x16x32_bf16 v[42:45], v[142:145], v[196:199], v[42:45]
	v_mfma_f32_16x16x32_bf16 v[58:61], v[142:145], v[188:191], v[58:61]
	v_mfma_f32_16x16x32_bf16 v[58:61], v[138:141], v[184:187], v[58:61]
	v_mfma_f32_16x16x32_bf16 v[54:57], v[146:149], v[184:187], v[54:57]
	v_mfma_f32_16x16x32_bf16 v[54:57], v[150:153], v[188:191], v[54:57]
	v_mfma_f32_16x16x32_bf16 v[38:41], v[150:153], v[196:199], v[38:41]
	v_mfma_f32_16x16x32_bf16 v[38:41], v[146:149], v[192:195], v[38:41]
	v_mfma_f32_16x16x32_bf16 v[22:25], v[146:149], v[200:203], v[22:25]
	v_mfma_f32_16x16x32_bf16 v[22:25], v[150:153], v[204:207], v[22:25]
	v_mfma_f32_16x16x32_bf16 v[6:9], v[150:153], v[212:215], v[6:9]
	v_mfma_f32_16x16x32_bf16 v[6:9], v[146:149], v[208:211], v[6:9]
	v_mfma_f32_16x16x32_bf16 v[2:5], v[154:157], v[208:211], v[2:5]
	v_mfma_f32_16x16x32_bf16 v[2:5], v[158:161], v[212:215], v[2:5]
	v_mfma_f32_16x16x32_bf16 v[18:21], v[158:161], v[204:207], v[18:21]
	v_mfma_f32_16x16x32_bf16 v[18:21], v[154:157], v[200:203], v[18:21]
	s_barrier
	s_setprio 2
	v_mfma_f32_16x16x32_bf16 v[34:37], v[154:157], v[192:195], v[34:37]
	v_mfma_f32_16x16x32_bf16 v[34:37], v[158:161], v[196:199], v[34:37]
	v_mfma_f32_16x16x32_bf16 v[50:53], v[158:161], v[188:191], v[50:53]
	v_mfma_f32_16x16x32_bf16 v[50:53], v[154:157], v[184:187], v[50:53]
	s_setprio 0
	s_add_i32 s41, 0, 0x18000
	s_add_i32 s62, 0, 0x1c000
	v_add_u32_e32 v142, s41, v1
	v_add_u32_e32 v158, s62, v1
	ds_read_b128 v[130:133], v142
	ds_read_b128 v[134:137], v142 offset:1024
	ds_read_b128 v[138:141], v142 offset:2048
	ds_read_b128 v[142:145], v142 offset:3072
	ds_read_b128 v[146:149], v158
	ds_read_b128 v[150:153], v158 offset:1024
	ds_read_b128 v[154:157], v158 offset:2048
	ds_read_b128 v[158:161], v158 offset:3072
	s_mov_b32 m0, s59
	v_lshl_add_u64 v[218:219], v[216:217], 0, s[14:15]
	ds_read_b128 v[184:187], v177 offset:32768
	ds_read_b128 v[188:191], v177 offset:33792
	ds_read_b128 v[192:195], v177 offset:34816
	ds_read_b128 v[196:199], v177 offset:35840
	ds_read_b128 v[200:203], v177 offset:36864
	ds_read_b128 v[204:207], v177 offset:37888
	ds_read_b128 v[208:211], v177 offset:38912
	ds_read_b128 v[212:215], v177 offset:39936
	global_load_lds_dwordx4 v[218:219], off sc1
	v_lshl_add_u64 v[218:219], v[216:217], 0, s[16:17]
	s_mov_b32 m0, s60
	s_nop 0
	global_load_lds_dwordx4 v[218:219], off sc1
	s_waitcnt vmcnt(8)
	s_waitcnt lgkmcnt(0)
	s_barrier
	s_setprio 1
	s_waitcnt lgkmcnt(0)
	v_mfma_f32_16x16x32_bf16 v[126:129], v[130:133], v[184:187], v[126:129]
	v_mfma_f32_16x16x32_bf16 v[126:129], v[134:137], v[188:191], v[126:129]
	v_mfma_f32_16x16x32_bf16 v[110:113], v[134:137], v[196:199], v[110:113]
	v_mfma_f32_16x16x32_bf16 v[110:113], v[130:133], v[192:195], v[110:113]
	v_mfma_f32_16x16x32_bf16 v[94:97], v[130:133], v[200:203], v[94:97]
	v_mfma_f32_16x16x32_bf16 v[94:97], v[134:137], v[204:207], v[94:97]
	v_mfma_f32_16x16x32_bf16 v[78:81], v[134:137], v[212:215], v[78:81]
	v_mfma_f32_16x16x32_bf16 v[78:81], v[130:133], v[208:211], v[78:81]
	v_mfma_f32_16x16x32_bf16 v[74:77], v[138:141], v[208:211], v[74:77]
	v_mfma_f32_16x16x32_bf16 v[74:77], v[142:145], v[212:215], v[74:77]
	v_mfma_f32_16x16x32_bf16 v[90:93], v[142:145], v[204:207], v[90:93]
	v_mfma_f32_16x16x32_bf16 v[90:93], v[138:141], v[200:203], v[90:93]
	v_mfma_f32_16x16x32_bf16 v[106:109], v[138:141], v[192:195], v[106:109]
	v_mfma_f32_16x16x32_bf16 v[106:109], v[142:145], v[196:199], v[106:109]
	v_mfma_f32_16x16x32_bf16 v[122:125], v[142:145], v[188:191], v[122:125]
	v_mfma_f32_16x16x32_bf16 v[122:125], v[138:141], v[184:187], v[122:125]
	v_mfma_f32_16x16x32_bf16 v[118:121], v[146:149], v[184:187], v[118:121]
	v_mfma_f32_16x16x32_bf16 v[118:121], v[150:153], v[188:191], v[118:121]
	v_mfma_f32_16x16x32_bf16 v[102:105], v[150:153], v[196:199], v[102:105]
	v_mfma_f32_16x16x32_bf16 v[102:105], v[146:149], v[192:195], v[102:105]
	v_mfma_f32_16x16x32_bf16 v[86:89], v[146:149], v[200:203], v[86:89]
	v_mfma_f32_16x16x32_bf16 v[86:89], v[150:153], v[204:207], v[86:89]
	v_mfma_f32_16x16x32_bf16 v[70:73], v[150:153], v[212:215], v[70:73]
	v_mfma_f32_16x16x32_bf16 v[70:73], v[146:149], v[208:211], v[70:73]
	v_mfma_f32_16x16x32_bf16 v[66:69], v[154:157], v[208:211], v[66:69]
	v_mfma_f32_16x16x32_bf16 v[66:69], v[158:161], v[212:215], v[66:69]
	v_mfma_f32_16x16x32_bf16 v[82:85], v[158:161], v[204:207], v[82:85]
	v_mfma_f32_16x16x32_bf16 v[82:85], v[154:157], v[200:203], v[82:85]
	s_barrier
; #define PG8_STAGE(bufoff, gbase, voff) do { if constexpr (!pg8_noload<Epi>::value) { _Pragma("unroll") for (int _i = 0; _i < 2; ++_i) \
;         __builtin_amdgcn_global_load_lds((const unsigned*)((const char*)(gbase) + (size_t)_i * pstep + (voff)[0]), (PG8_LAS unsigned*)(lds + (bufoff) + ldsw + _i * 8192), 16, 0, 0); } } while (0)
; #define PG8_LDA(dst, b, h) do { _Pragma("unroll") for (int m = 0; m < 4; ++m) _Pragma("unroll") for (int k = 0; k < 2; ++k) dst[m][k] = *(const PG8_LAS bf16x8*)(lds + PG8_SA(b, h) + aoff + m * 2048 + k * 1024); } while (0)
; #define PG8_MMA(ai, bj, At, Bt) do { __builtin_amdgcn_s_setprio(1); _Pragma("unroll") for (int m = 0; m < 4; ++m) _Pragma("unroll") for (int n = 0; n < 2; ++n) _Pragma("unroll") for (int k = 0; k < 2; ++k) \
;         acc[ai][bj][m][n] = __builtin_amdgcn_mfma_f32_16x16x32_bf16(Bt[n][k], At[m][k], acc[ai][bj][m][n], 0, 0, 0); __builtin_amdgcn_s_setprio(0); } while (0)
; #define PG8_WAIT_V(n) asm volatile("s_waitcnt vmcnt(" #n ")" ::: "memory")
; #define PG8_WAIT_L(n) asm volatile("s_waitcnt lgkmcnt(" #n ")" ::: "memory")
; #define PG8_BAR __builtin_amdgcn_s_barrier()
; #define PG8_SCHED __builtin_amdgcn_sched_barrier(0)
;     __device__ __forceinline__ void operator()(const f32x4 (&acc)[2][2][4][2], const Unit& u, int wr, int wc, int fr, int fq) const {
;         const int c0 = u.pn * BM + wc * 32 + 8 * fq;
;         if (u.pm * BM < seq) {
; template <class Epi, class Sched, bool ALIGN_EPI = false, bool SP2 = false, bool ABLK = false>
; __device__ __forceinline__ void gemm_phase(PG8_LAS unsigned char* lds, const Gemm g, const Sched& S, const Epi& E) {
;     ...
;             PG8_WAIT_V(8); PG8_WAIT_L(0); PG8_BAR; PG8_MMA(0, 0, At, B0); PG8_MMA(0, 1, At, B1); PG8_BAR; PG8_SCHED;
;             PG8_LDA(At, 1, 1); PG8_STAGE(PG8_SB(1, 0), b3, voffB); PG8_STAGE(PG8_SB(1, 1), b3 + hstep, voffB); PG8_STAGE(PG8_SA(1, 0), a3, voffA);
;             PG8_WAIT_V(8); PG8_WAIT_L(0); PG8_BAR; PG8_MMA(1, 0, At, B0); PG8_MMA(1, 1, At, B1); PG8_BAR; PG8_SCHED;
	s_setprio 2
	v_mfma_f32_16x16x32_bf16 v[98:101], v[154:157], v[192:195], v[98:101]
	v_mfma_f32_16x16x32_bf16 v[98:101], v[158:161], v[196:199], v[98:101]
	v_mfma_f32_16x16x32_bf16 v[114:117], v[158:161], v[188:191], v[114:117]
	v_mfma_f32_16x16x32_bf16 v[114:117], v[154:157], v[184:187], v[114:117]
	s_setprio 0
	s_add_i32 s41, s41, s57
	v_lshl_add_u64 v[218:219], v[170:171], 0, s[24:25]
	s_mov_b32 m0, s41
	ds_read_b128 v[184:187], v177 offset:49152
	ds_read_b128 v[188:191], v177 offset:50176
	ds_read_b128 v[192:195], v177 offset:51200
	ds_read_b128 v[196:199], v177 offset:52224
	ds_read_b128 v[200:203], v177 offset:53248
	ds_read_b128 v[204:207], v177 offset:54272
	ds_read_b128 v[208:211], v177 offset:55296
	ds_read_b128 v[212:215], v177 offset:56320
	global_load_lds_dwordx4 v[218:219], off sc1
	v_lshl_add_u64 v[218:219], v[170:171], 0, s[26:27]
	s_add_i32 m0, s41, 0x2000
	s_add_i32 s41, s62, s57
	global_load_lds_dwordx4 v[218:219], off sc1
	v_lshl_add_u64 v[218:219], v[170:171], 0, s[28:29]
	s_mov_b32 m0, s41
	v_lshl_add_u64 v[170:171], v[170:171], 0, s[30:31]
	global_load_lds_dwordx4 v[218:219], off sc1
	s_add_i32 m0, s41, 0x2000
	s_nop 0
	global_load_lds_dwordx4 v[170:171], off sc1
	v_lshl_add_u64 v[170:171], v[216:217], 0, s[24:25]
	s_mov_b32 m0, s65
	s_nop 0
	global_load_lds_dwordx4 v[170:171], off sc1
	v_lshl_add_u64 v[170:171], v[216:217], 0, s[26:27]
	s_mov_b32 m0, s66
	s_nop 0
	global_load_lds_dwordx4 v[170:171], off sc1
	s_waitcnt vmcnt(8)
	s_waitcnt lgkmcnt(0)
	s_barrier
	s_setprio 1
	s_waitcnt lgkmcnt(0)
	v_mfma_f32_16x16x32_bf16 v[62:65], v[130:133], v[184:187], v[62:65]
	v_mfma_f32_16x16x32_bf16 v[62:65], v[134:137], v[188:191], v[62:65]
	v_mfma_f32_16x16x32_bf16 v[46:49], v[134:137], v[196:199], v[46:49]
	v_mfma_f32_16x16x32_bf16 v[46:49], v[130:133], v[192:195], v[46:49]
	v_mfma_f32_16x16x32_bf16 v[30:33], v[130:133], v[200:203], v[30:33]
	v_mfma_f32_16x16x32_bf16 v[30:33], v[134:137], v[204:207], v[30:33]
	v_mfma_f32_16x16x32_bf16 v[14:17], v[134:137], v[212:215], v[14:17]
	v_mfma_f32_16x16x32_bf16 v[14:17], v[130:133], v[208:211], v[14:17]
	v_mfma_f32_16x16x32_bf16 v[10:13], v[138:141], v[208:211], v[10:13]
	v_mfma_f32_16x16x32_bf16 v[10:13], v[142:145], v[212:215], v[10:13]
	v_mfma_f32_16x16x32_bf16 v[26:29], v[142:145], v[204:207], v[26:29]
	v_mfma_f32_16x16x32_bf16 v[26:29], v[138:141], v[200:203], v[26:29]
	v_mfma_f32_16x16x32_bf16 v[42:45], v[138:141], v[192:195], v[42:45]
	v_mfma_f32_16x16x32_bf16 v[42:45], v[142:145], v[196:199], v[42:45]
	v_mfma_f32_16x16x32_bf16 v[58:61], v[142:145], v[188:191], v[58:61]
	v_mfma_f32_16x16x32_bf16 v[58:61], v[138:141], v[184:187], v[58:61]
	v_mfma_f32_16x16x32_bf16 v[54:57], v[146:149], v[184:187], v[54:57]
	v_mfma_f32_16x16x32_bf16 v[54:57], v[150:153], v[188:191], v[54:57]
	v_mfma_f32_16x16x32_bf16 v[38:41], v[150:153], v[196:199], v[38:41]
	v_mfma_f32_16x16x32_bf16 v[38:41], v[146:149], v[192:195], v[38:41]
	v_mfma_f32_16x16x32_bf16 v[22:25], v[146:149], v[200:203], v[22:25]
	v_mfma_f32_16x16x32_bf16 v[22:25], v[150:153], v[204:207], v[22:25]
	v_mfma_f32_16x16x32_bf16 v[6:9], v[150:153], v[212:215], v[6:9]
	v_mfma_f32_16x16x32_bf16 v[6:9], v[146:149], v[208:211], v[6:9]
	v_mfma_f32_16x16x32_bf16 v[2:5], v[154:157], v[208:211], v[2:5]
	v_mfma_f32_16x16x32_bf16 v[2:5], v[158:161], v[212:215], v[2:5]
	v_mfma_f32_16x16x32_bf16 v[18:21], v[158:161], v[204:207], v[18:21]
	v_mfma_f32_16x16x32_bf16 v[18:21], v[154:157], v[200:203], v[18:21]
	s_barrier
	s_setprio 2
	v_mfma_f32_16x16x32_bf16 v[34:37], v[154:157], v[192:195], v[34:37]
	v_mfma_f32_16x16x32_bf16 v[34:37], v[158:161], v[196:199], v[34:37]
	v_mfma_f32_16x16x32_bf16 v[50:53], v[158:161], v[188:191], v[50:53]
	v_mfma_f32_16x16x32_bf16 v[50:53], v[154:157], v[184:187], v[50:53]
	s_setprio 0
	s_add_u32 s52, s52, 0x1000
	s_addc_u32 s53, s53, 0
	s_add_u32 s11, s11, 0x1000
	s_addc_u32 s39, s39, 0
	s_cmp_ge_i32 s43, s75
	s_mov_b32 s41, s43
	s_cbranch_scc0 .LBB0_1997
	s_and_b64 vcc, exec, s[34:35]
	s_cbranch_vccnz .LBB0_2002
	s_lshl_b32 s11, s2, 8
	s_cmp_gt_i32 s2, 63
	s_mov_b64 s[52:53], -1
	s_cbranch_scc1 .LBB0_2003

; #define PG8_STAGE(bufoff, gbase, voff) do { if constexpr (!pg8_noload<Epi>::value) { _Pragma("unroll") for (int _i = 0; _i < 2; ++_i) \
;         __builtin_amdgcn_global_load_lds((const unsigned*)((const char*)(gbase) + (size_t)_i * pstep + (voff)[0]), (PG8_LAS unsigned*)(lds + (bufoff) + ldsw + _i * 8192), 16, 0, 0); } } while (0)
; #define PG8_WAIT_V(n) asm volatile("s_waitcnt vmcnt(" #n ")" ::: "memory")
; #define PG8_BAR __builtin_amdgcn_s_barrier()
; template <class Epi, class Sched, bool ALIGN_EPI = false, bool SP2 = false, bool ABLK = false>
; __device__ __forceinline__ void gemm_phase(PG8_LAS unsigned char* lds, const Gemm g, const Sched& S, const Epi& E) {
;     const int tid = threadIdx.x, wid = __builtin_amdgcn_readfirstlane(tid >> 6), lane = tid & 63, wr = wid >> 2, wc = wid & 3, fr = lane & 15, fq = lane >> 4;
;     const int K = g.K;
;     unsigned voffA[2], voffB[2];
; #pragma unroll
;     for (int i = 0; i < 2; ++i) { int R, C; stage_rc(tid * 16 + i * 8192, R, C); const int Rb = Epi::PERM ? ((R & ~31) + perm32(R & 31)) : R;
;         voffA[i] = (unsigned)(R * K + C) * 2u; (void)Rb;
;         if constexpr (ABLK) { const int st = (tid >> 6) + 8 * i; voffA[i] = (unsigned)(((st >> 1) * (K / 32) + (st & 1)) * 1024 + (tid & 63) * 16); }
;         { static_assert(Epi::PERM, "blocked weight copies are written in permuted row-slot order"); const int st = (tid >> 6) + 8 * i; voffB[i] = (unsigned)(((st >> 1) * (K / 32) + (st & 1)) * 1024 + (tid & 63) * 16); } }
;     const size_t kstep = ABLK ? (size_t)(BK / 32) * 1024 : (size_t)(BK * 2);
;     constexpr int KOA = ABLK ? 32 : 2;
;     const size_t pstep = (size_t)K * 128;
;     const size_t kstepB = (size_t)(BK / 32) * 1024;
;     const size_t hstep = (size_t)HALF * K * 2;
;     const size_t tstep = 2 * hstep;
;     const unsigned ldsw = (unsigned)wid * 1024u;
;     const int aoff = lds_byte(wr * 64 + fr, fq * 8), boff = lds_byte(wc * 32 + fr, fq * 8);
;     ...
;         PG8_STAGE(PG8_SB(0, 0), cB, voffB); PG8_STAGE(PG8_SB(0, 1), cB + hstep, voffB); PG8_STAGE(PG8_SA(0, 0), cA, voffA); PG8_STAGE(PG8_SA(0, 1), cA + hstep, voffA);
;         if (wr == 1) PG8_BAR;
;         PG8_WAIT_V(2); PG8_BAR;
;         PG8_STAGE(PG8_SB(1, 0), cB + kstepB, voffB); PG8_STAGE(PG8_SA(1, 0), cA + kstep, voffA); PG8_STAGE(PG8_SB(1, 1), cB + hstep + kstepB, voffB);
;         PG8_WAIT_V(6); PG8_BAR;
.LBB0_2108:
	s_add_u32 s54, s86, 0x3300000
	s_addc_u32 s55, s87, 0
	s_ashr_i32 s17, s16, 31
	s_lshl_b64 s[0:1], s[16:17], 20
	s_mov_b32 s8, s82
	s_add_u32 s82, s33, s0
	s_addc_u32 s83, s53, s1
	s_ashr_i32 s3, s2, 31
	s_lshl_b64 s[0:1], s[2:3], 20
	s_add_u32 s88, s54, s0
	v_lshlrev_b32_e32 v1, 5, v183
	s_movk_i32 s0, 0xc1
	s_addc_u32 s89, s55, s1
	v_lshlrev_b32_e32 v2, 4, v182
	v_bitop3_b32 v1, v1, s0, v183 bitop3:0xc8
	s_lshl_b32 s3, s10, 10
	v_mov_b32_e32 v132, 0
	v_lshl_or_b32 v130, v1, 10, v2
	v_mov_b32_e32 v131, v132
	s_add_i32 s17, s3, 0
	s_waitcnt lgkmcnt(0)
	v_lshl_add_u64 v[2:3], s[88:89], 0, v[130:131]
	s_add_i32 m0, s17, 0x10000
	s_mov_b64 s[22:23], 0x40000
	global_load_lds_dwordx4 v130, s[88:89]
	v_lshl_add_u64 v[4:5], v[2:3], 0, s[22:23]
	s_add_i32 m0, s17, 0x12000
	s_mov_b64 s[24:25], 0x80000
	global_load_lds_dwordx4 v[4:5], off sc1
	v_lshl_add_u64 v[4:5], v[2:3], 0, s[24:25]
	s_add_i32 m0, s17, 0x14000
	s_mov_b64 s[26:27], 0xc0000
	global_load_lds_dwordx4 v[4:5], off sc1
	v_lshl_add_u64 v[4:5], v[2:3], 0, s[26:27]
	s_add_i32 m0, s17, 0x16000
	s_add_i32 s56, s17, 0x2000
	global_load_lds_dwordx4 v[4:5], off sc1
	v_lshl_add_u64 v[4:5], s[82:83], 0, v[130:131]
	s_mov_b32 m0, s17
	v_lshl_add_u64 v[6:7], v[4:5], 0, s[22:23]
	global_load_lds_dwordx4 v130, s[82:83]
	s_mov_b32 m0, s56
	s_add_i32 s57, s17, 0x4000
	global_load_lds_dwordx4 v[6:7], off sc1
	v_lshl_add_u64 v[6:7], v[4:5], 0, s[24:25]
	s_mov_b32 m0, s57
	s_add_i32 s58, s17, 0x6000
	global_load_lds_dwordx4 v[6:7], off sc1
	v_lshl_add_u64 v[6:7], v[4:5], 0, s[26:27]
	s_mov_b32 m0, s58
	s_ashr_i32 s0, s10, 2
	global_load_lds_dwordx4 v[6:7], off sc1
	v_writelane_b32 v251, s46, 56
	s_cmp_eq_u32 s0, 1
	s_cselect_b64 s[4:5], -1, 0
	v_writelane_b32 v251, s47, 57
	v_writelane_b32 v251, s4, 26
	s_cmp_lg_u32 s0, 1
	s_mov_b32 s31, 0
	v_writelane_b32 v251, s5, 27
	s_cbranch_scc1 .LBB0_2110
	s_barrier
.LBB0_2110:
	s_add_u32 s9, s86, 0x1b400000
	s_addc_u32 s60, s87, 0
	s_add_u32 s4, s86, 0x34000000
	s_addc_u32 s5, s87, 0
	v_and_b32_e32 v7, 15, v0
	v_writelane_b32 v251, s4, 50
	v_lshl_or_b32 v1, s0, 6, v7
	v_and_b32_e32 v6, 48, v0
	v_writelane_b32 v251, s5, 51
	s_add_u32 s4, s86, 0x40000
	v_lshlrev_b32_e32 v10, 2, v1
	s_addc_u32 s5, s87, 0
	v_lshl_or_b32 v8, v7, 6, v6
	s_lshl_b32 s1, s0, 13
	v_and_b32_e32 v9, 32, v10
	s_and_b32 s12, s10, 3
	v_bitop3_b32 v11, v8, s1, v9 bitop3:0xde
	v_lshlrev_b32_e32 v8, 6, v0
	s_movk_i32 s1, 0x3c0
	v_and_or_b32 v8, v8, s1, v6
	s_lshl_b32 s1, s12, 12
	v_and_b32_e32 v9, 32, v46
	s_mov_b64 s[38:39], 0x800
	v_bitop3_b32 v148, s1, v8, v9 bitop3:0xf6
	v_lshl_add_u64 v[8:9], v[2:3], 0, s[38:39]
	s_add_i32 m0, s17, 0x18000
	s_mov_b64 s[40:41], 0x40800
	s_waitcnt vmcnt(2)
	s_barrier
	global_load_lds_dwordx4 v[8:9], off sc1
	v_lshl_add_u64 v[8:9], v[2:3], 0, s[40:41]
	s_add_i32 m0, s17, 0x1a000
	s_add_i32 s61, s17, 0x8000
	global_load_lds_dwordx4 v[8:9], off sc1
	v_lshl_add_u64 v[8:9], v[4:5], 0, s[38:39]
	s_mov_b32 m0, s61
	s_add_i32 s63, s17, 0xa000
	global_load_lds_dwordx4 v[8:9], off sc1
	v_lshl_add_u64 v[4:5], v[4:5], 0, s[40:41]
	s_mov_b32 m0, s63
	s_mov_b64 s[42:43], 0x80800
	global_load_lds_dwordx4 v[4:5], off sc1
	v_lshl_add_u64 v[4:5], v[2:3], 0, s[42:43]
	s_add_i32 m0, s17, 0x1c000
	s_mov_b64 s[44:45], 0xc0800
	global_load_lds_dwordx4 v[4:5], off sc1
	v_lshl_add_u64 v[2:3], v[2:3], 0, s[44:45]
	s_add_i32 m0, s17, 0x1e000
	s_cmp_lt_u32 s10, 4
	global_load_lds_dwordx4 v[2:3], off sc1
	s_cselect_b64 s[46:47], -1, 0
	s_lshl_b32 s0, s0, 8
	s_add_i32 s13, 0, 0x22800
	s_add_i32 s0, s13, s0
	s_and_b32 s65, s10, -4
	s_lshl_b32 s1, s10, 6
	s_lshl_b32 s48, s12, 1
	s_ashr_i32 s67, s97, 31
	s_ashr_i32 s69, s8, 31
	v_lshl_add_u32 v158, v7, 2, s0
	s_lshl_b32 s0, s12, 6
	v_or3_b32 v149, s1, v6, v7
	s_movk_i32 s1, 0x100
	s_add_u32 s0, s86, s0
	v_cmp_gt_i32_e64 s[6:7], s1, v149
	s_addc_u32 s1, s87, 0
	v_mov_b32_e32 v7, v132
	v_lshlrev_b32_e32 v2, 3, v0
	v_lshl_add_u64 v[4:5], s[0:1], 0, v[6:7]
	s_mov_b64 s[0:1], 0x23800000
	v_writelane_b32 v251, s4, 44
	v_and_b32_e32 v2, 0x1f8, v2
	v_lshlrev_b32_e32 v17, 5, v149
	v_lshl_add_u64 v[134:135], v[4:5], 0, s[0:1]
	s_lshl_b32 s0, s12, 3
	v_writelane_b32 v251, s5, 45
	s_waitcnt vmcnt(6)
	v_cmp_eq_u32_e64 s[10:11], 0, v149
	v_or_b32_e32 v150, 16, v1
	v_or_b32_e32 v151, 32, v1
	v_or_b32_e32 v152, 48, v1
	v_add_u32_e32 v153, 0x80, v1
	v_add_u32_e32 v154, 0x90, v1
	v_add_u32_e32 v155, 0xa0, v1
	v_add_u32_e32 v156, 0xb0, v1
	s_add_i32 s0, s0, 0
	v_lshlrev_b32_e32 v140, 1, v2
	v_add_u32_e32 v2, 0, v17
	v_writelane_b32 v251, s10, 24
	v_lshlrev_b32_e32 v3, 5, v1
	v_lshlrev_b32_e32 v8, 5, v150
	v_lshlrev_b32_e32 v9, 5, v151
	v_lshlrev_b32_e32 v12, 5, v152
	v_lshlrev_b32_e32 v13, 5, v153
	v_lshlrev_b32_e32 v14, 5, v154
	v_lshlrev_b32_e32 v15, 5, v155
	v_lshlrev_b32_e32 v16, 5, v156
	s_add_i32 s0, s0, 0x20800
	v_add_u32_e32 v178, 0x20800, v2
	v_mbcnt_lo_u32_b32 v2, -1, 0
	v_cmp_gt_u32_e64 s[4:5], 64, v0
	v_writelane_b32 v251, s11, 25
	s_mov_b32 s49, s31
	v_cmp_gt_u32_e64 s[10:11], 16, v182
	v_lshl_add_u32 v157, v149, 2, s13
	v_add_u32_e32 v159, s13, v10
	v_lshl_add_u32 v160, v150, 2, s13
	v_lshl_add_u32 v161, v151, 2, s13
	v_lshl_add_u32 v162, v152, 2, s13
	v_lshl_add_u32 v163, v153, 2, s13
	v_lshl_add_u32 v164, v154, 2, s13
	v_lshl_add_u32 v165, v155, 2, s13
	v_lshl_add_u32 v166, v156, 2, s13
	v_mov_b64_e32 v[136:137], 0xc60
	v_mov_b64_e32 v[138:139], 0xc5f
	v_mov_b32_e32 v167, 1
	s_add_i32 s71, 0, 0x10000
	s_add_i32 s73, 0, 0x14000
	v_add_u32_e32 v168, 0, v11
	s_add_i32 s36, 0, 0x22c00
	v_mov_b32_e32 v169, 0x358637bd
	s_mov_b32 s52, 0x3e6d3388
	s_mov_b32 s62, 0x3f07dc22
	s_mov_b32 s64, 0xbf3a00e3
	s_mov_b32 s66, 0x3f35f0e3
	s_mov_b32 s68, 0xbe11a98e
	s_mov_b32 s70, 0x3e027906
	s_mov_b32 s72, 0xbf38aa3b
	v_add_u32_e32 v170, s0, v3
	v_add_u32_e32 v171, s0, v8
	v_add_u32_e32 v172, s0, v9
	v_add_u32_e32 v173, s0, v12
	v_add_u32_e32 v174, s0, v13
	v_add_u32_e32 v175, s0, v14
	v_add_u32_e32 v176, s0, v15
	v_add_u32_e32 v177, s0, v16
	v_mov_b64_e32 v[142:143], 0x1e8481
	v_mbcnt_hi_u32_b32 v179, -1, v2
	s_mov_b32 s37, 0
	s_barrier
	s_branch .LBB0_2113

; #define PG8_STAGE(bufoff, gbase, voff) do { if constexpr (!pg8_noload<Epi>::value) { _Pragma("unroll") for (int _i = 0; _i < 2; ++_i) \
;         __builtin_amdgcn_global_load_lds((const unsigned*)((const char*)(gbase) + (size_t)_i * pstep + (voff)[0]), (PG8_LAS unsigned*)(lds + (bufoff) + ldsw + _i * 8192), 16, 0, 0); } } while (0)
; #define PG8_LDA(dst, b, h) do { _Pragma("unroll") for (int m = 0; m < 4; ++m) _Pragma("unroll") for (int k = 0; k < 2; ++k) dst[m][k] = *(const PG8_LAS bf16x8*)(lds + PG8_SA(b, h) + aoff + m * 2048 + k * 1024); } while (0)
; #define PG8_LDB(dst, b, h) do { _Pragma("unroll") for (int n = 0; n < 2; ++n) _Pragma("unroll") for (int k = 0; k < 2; ++k) dst[n][k] = *(const PG8_LAS bf16x8*)(lds + PG8_SB(b, h) + boff + n * 2048 + k * 1024); } while (0)
; #define PG8_MMA(ai, bj, At, Bt) do { __builtin_amdgcn_s_setprio(1); _Pragma("unroll") for (int m = 0; m < 4; ++m) _Pragma("unroll") for (int n = 0; n < 2; ++n) _Pragma("unroll") for (int k = 0; k < 2; ++k) \
;         acc[ai][bj][m][n] = __builtin_amdgcn_mfma_f32_16x16x32_bf16(Bt[n][k], At[m][k], acc[ai][bj][m][n], 0, 0, 0); __builtin_amdgcn_s_setprio(0); } while (0)
; #define PG8_BAR __builtin_amdgcn_s_barrier()
; template <class Epi, class Sched, bool ALIGN_EPI = false, bool SP2 = false, bool ABLK = false>
; __device__ __forceinline__ void gemm_phase(PG8_LAS unsigned char* lds, const Gemm g, const Sched& S, const Epi& E) {
;     ...
;         for (int t = 0; t < nt; t += 2) {
;             const bool last = (t == nt - 2);
;             const char* a1 = cA + (size_t)(t + 1) * kstep;
;             const char* a2 = last ? nA : cA + (size_t)(t + 2) * kstep; const char* b2 = last ? nB : cB + (size_t)(t + 2) * kstepB;
;             const char* a3 = a2 + kstep; const char* b3 = b2 + kstepB;
;             if (last && has_next) S.a_ready(nxt);
;             if constexpr (SP2) {
;             PG8_LDB(B0, 0, 0); PG8_LDB(B1, 0, 1); PG8_SCHED; PG8_LDA(At, 0, 0); PG8_STAGE(PG8_SA(1, 1), a1 + hstep, voffA);
;             PG8_WAIT_V(8); PG8_WAIT_L(0); PG8_BAR; PG8_MMA(0, 0, At, B0); PG8_MMA(0, 1, At, B1); PG8_BAR; PG8_SCHED;
;             PG8_LDA(At, 0, 1); PG8_STAGE(PG8_SB(0, 0), b2, voffB); PG8_STAGE(PG8_SB(0, 1), b2 + hstep, voffB); PG8_STAGE(PG8_SA(0, 0), a2, voffA);
;             PG8_WAIT_V(8); PG8_WAIT_L(0); PG8_BAR; PG8_MMA(1, 0, At, B0); PG8_MMA(1, 1, At, B1); PG8_BAR; PG8_SCHED;
.LBB0_2119:
	s_or_b32 s30, s59, 1
	s_lshl_b64 s[14:15], s[30:31], 11
	s_add_u32 s14, s82, s14
	v_add_u32_e32 v133, s71, v148
	s_addc_u32 s15, s83, s15
	s_add_i32 s30, s59, 2
	ds_read_b128 v[144:147], v133
	ds_read_b128 v[184:187], v133 offset:1024
	ds_read_b128 v[188:191], v133 offset:2048
	ds_read_b128 v[192:195], v133 offset:3072
	v_add_u32_e32 v133, s73, v148
	s_lshl_b64 s[34:35], s[30:31], 11
	ds_read_b128 v[196:199], v133
	ds_read_b128 v[200:203], v133 offset:1024
	ds_read_b128 v[204:207], v133 offset:2048
	ds_read_b128 v[208:211], v133 offset:3072
	s_add_u32 s96, s82, s34
	s_addc_u32 s97, s83, s35
	s_and_b64 s[94:95], s[92:93], exec
	s_cselect_b32 s95, s97, s77
	s_cselect_b32 s94, s96, s28
	s_add_u32 s96, s88, s34
	s_addc_u32 s97, s89, s35
	s_and_b64 s[34:35], s[92:93], exec
	s_cselect_b32 s35, s97, s29
	s_cselect_b32 s34, s96, s75
	v_lshl_add_u64 v[180:181], s[14:15], 0, v[130:131]
	v_lshl_add_u64 v[244:245], v[180:181], 0, s[24:25]
	s_add_i32 m0, s17, 0xc000
	ds_read_b128 v[212:215], v168
	ds_read_b128 v[216:219], v168 offset:1024
	ds_read_b128 v[220:223], v168 offset:2048
	ds_read_b128 v[224:227], v168 offset:3072
	ds_read_b128 v[228:231], v168 offset:4096
	ds_read_b128 v[232:235], v168 offset:5120
	ds_read_b128 v[236:239], v168 offset:6144
	ds_read_b128 v[240:243], v168 offset:7168
	global_load_lds_dwordx4 v[244:245], off sc1
	v_lshl_add_u64 v[180:181], v[180:181], 0, s[26:27]
	s_add_i32 m0, s17, 0xe000
	s_nop 0
	global_load_lds_dwordx4 v[180:181], off sc1
	s_waitcnt vmcnt(8)
	s_waitcnt lgkmcnt(0)
	s_barrier
	s_setprio 1
	s_waitcnt lgkmcnt(0)
	v_mfma_f32_16x16x32_bf16 v[126:129], v[144:147], v[212:215], v[126:129]
	v_mfma_f32_16x16x32_bf16 v[126:129], v[184:187], v[216:219], v[126:129]
	v_mfma_f32_16x16x32_bf16 v[110:113], v[184:187], v[224:227], v[110:113]
	v_mfma_f32_16x16x32_bf16 v[110:113], v[144:147], v[220:223], v[110:113]
	v_mfma_f32_16x16x32_bf16 v[94:97], v[144:147], v[228:231], v[94:97]
	v_mfma_f32_16x16x32_bf16 v[94:97], v[184:187], v[232:235], v[94:97]
	v_mfma_f32_16x16x32_bf16 v[78:81], v[184:187], v[240:243], v[78:81]
	v_mfma_f32_16x16x32_bf16 v[78:81], v[144:147], v[236:239], v[78:81]
	v_mfma_f32_16x16x32_bf16 v[74:77], v[188:191], v[236:239], v[74:77]
	v_mfma_f32_16x16x32_bf16 v[74:77], v[192:195], v[240:243], v[74:77]
	v_mfma_f32_16x16x32_bf16 v[90:93], v[192:195], v[232:235], v[90:93]
	v_mfma_f32_16x16x32_bf16 v[90:93], v[188:191], v[228:231], v[90:93]
	v_mfma_f32_16x16x32_bf16 v[106:109], v[188:191], v[220:223], v[106:109]
	v_mfma_f32_16x16x32_bf16 v[106:109], v[192:195], v[224:227], v[106:109]
	v_mfma_f32_16x16x32_bf16 v[122:125], v[192:195], v[216:219], v[122:125]
	v_mfma_f32_16x16x32_bf16 v[122:125], v[188:191], v[212:215], v[122:125]
	v_mfma_f32_16x16x32_bf16 v[118:121], v[196:199], v[212:215], v[118:121]
	v_mfma_f32_16x16x32_bf16 v[118:121], v[200:203], v[216:219], v[118:121]
	v_mfma_f32_16x16x32_bf16 v[102:105], v[200:203], v[224:227], v[102:105]
	v_mfma_f32_16x16x32_bf16 v[102:105], v[196:199], v[220:223], v[102:105]
	v_mfma_f32_16x16x32_bf16 v[86:89], v[196:199], v[228:231], v[86:89]
	v_mfma_f32_16x16x32_bf16 v[86:89], v[200:203], v[232:235], v[86:89]
	v_mfma_f32_16x16x32_bf16 v[70:73], v[200:203], v[240:243], v[70:73]
	v_mfma_f32_16x16x32_bf16 v[70:73], v[196:199], v[236:239], v[70:73]
	v_mfma_f32_16x16x32_bf16 v[66:69], v[204:207], v[236:239], v[66:69]
	v_mfma_f32_16x16x32_bf16 v[66:69], v[208:211], v[240:243], v[66:69]
	v_mfma_f32_16x16x32_bf16 v[82:85], v[208:211], v[232:235], v[82:85]
	v_mfma_f32_16x16x32_bf16 v[82:85], v[204:207], v[228:231], v[82:85]
	s_barrier
	s_setprio 2
	v_mfma_f32_16x16x32_bf16 v[98:101], v[204:207], v[220:223], v[98:101]
	v_mfma_f32_16x16x32_bf16 v[98:101], v[208:211], v[224:227], v[98:101]
	v_mfma_f32_16x16x32_bf16 v[114:117], v[208:211], v[216:219], v[114:117]
	v_mfma_f32_16x16x32_bf16 v[114:117], v[204:207], v[212:215], v[114:117]
	s_setprio 0
	s_add_i32 s14, s71, s3
	v_lshl_add_u64 v[180:181], s[34:35], 0, v[130:131]
	s_mov_b32 m0, s14
	ds_read_b128 v[212:215], v168 offset:16384
	ds_read_b128 v[216:219], v168 offset:17408
	ds_read_b128 v[220:223], v168 offset:18432
	ds_read_b128 v[224:227], v168 offset:19456
	ds_read_b128 v[228:231], v168 offset:20480
	ds_read_b128 v[232:235], v168 offset:21504
	ds_read_b128 v[236:239], v168 offset:22528
	ds_read_b128 v[240:243], v168 offset:23552
	global_load_lds_dwordx4 v[180:181], off sc1
	v_lshl_add_u64 v[244:245], v[180:181], 0, s[22:23]
	s_add_i32 m0, s14, 0x2000
	s_add_i32 s14, s73, s3
	global_load_lds_dwordx4 v[244:245], off sc1
	v_lshl_add_u64 v[244:245], v[180:181], 0, s[24:25]
	s_mov_b32 m0, s14
	s_nop 0
	global_load_lds_dwordx4 v[244:245], off sc1
	v_lshl_add_u64 v[244:245], v[180:181], 0, s[26:27]
	s_add_i32 m0, s14, 0x2000
	s_nop 0
	global_load_lds_dwordx4 v[244:245], off sc1
	v_lshl_add_u64 v[244:245], s[94:95], 0, v[130:131]
	s_mov_b32 m0, s17
	v_lshl_add_u64 v[246:247], v[244:245], 0, s[22:23]
	global_load_lds_dwordx4 v[244:245], off sc1
	s_mov_b32 m0, s56
	s_nop 0
	global_load_lds_dwordx4 v[246:247], off sc1
	s_waitcnt vmcnt(8)
	s_waitcnt lgkmcnt(0)
	s_barrier
; #define PG8_STAGE(bufoff, gbase, voff) do { if constexpr (!pg8_noload<Epi>::value) { _Pragma("unroll") for (int _i = 0; _i < 2; ++_i) \
;         __builtin_amdgcn_global_load_lds((const unsigned*)((const char*)(gbase) + (size_t)_i * pstep + (voff)[0]), (PG8_LAS unsigned*)(lds + (bufoff) + ldsw + _i * 8192), 16, 0, 0); } } while (0)
; #define PG8_LDA(dst, b, h) do { _Pragma("unroll") for (int m = 0; m < 4; ++m) _Pragma("unroll") for (int k = 0; k < 2; ++k) dst[m][k] = *(const PG8_LAS bf16x8*)(lds + PG8_SA(b, h) + aoff + m * 2048 + k * 1024); } while (0)
; #define PG8_LDB(dst, b, h) do { _Pragma("unroll") for (int n = 0; n < 2; ++n) _Pragma("unroll") for (int k = 0; k < 2; ++k) dst[n][k] = *(const PG8_LAS bf16x8*)(lds + PG8_SB(b, h) + boff + n * 2048 + k * 1024); } while (0)
; #define PG8_MMA(ai, bj, At, Bt) do { __builtin_amdgcn_s_setprio(1); _Pragma("unroll") for (int m = 0; m < 4; ++m) _Pragma("unroll") for (int n = 0; n < 2; ++n) _Pragma("unroll") for (int k = 0; k < 2; ++k) \
;         acc[ai][bj][m][n] = __builtin_amdgcn_mfma_f32_16x16x32_bf16(Bt[n][k], At[m][k], acc[ai][bj][m][n], 0, 0, 0); __builtin_amdgcn_s_setprio(0); } while (0)
; #define PG8_WAIT_V(n) asm volatile("s_waitcnt vmcnt(" #n ")" ::: "memory")
; #define PG8_WAIT_L(n) asm volatile("s_waitcnt lgkmcnt(" #n ")" ::: "memory")
; #define PG8_BAR __builtin_amdgcn_s_barrier()
; #define PG8_SCHED __builtin_amdgcn_sched_barrier(0)
; template <class Epi, class Sched, bool ALIGN_EPI = false, bool SP2 = false, bool ABLK = false>
; __device__ __forceinline__ void gemm_phase(PG8_LAS unsigned char* lds, const Gemm g, const Sched& S, const Epi& E) {
;     ...
;             PG8_WAIT_V(8); PG8_WAIT_L(0); PG8_BAR; PG8_MMA(1, 0, At, B0); PG8_MMA(1, 1, At, B1); PG8_BAR; PG8_SCHED;
;             PG8_LDB(B0, 1, 0); PG8_LDB(B1, 1, 1); PG8_SCHED; PG8_LDA(At, 1, 0); PG8_STAGE(PG8_SA(0, 1), a2 + hstep, voffA);
;             PG8_WAIT_V(8); PG8_WAIT_L(0); PG8_BAR; PG8_MMA(0, 0, At, B0); PG8_MMA(0, 1, At, B1); PG8_BAR; PG8_SCHED;
	s_setprio 1
	s_waitcnt lgkmcnt(0)
	v_mfma_f32_16x16x32_bf16 v[62:65], v[144:147], v[212:215], v[62:65]
	v_mfma_f32_16x16x32_bf16 v[62:65], v[184:187], v[216:219], v[62:65]
	v_mfma_f32_16x16x32_bf16 v[46:49], v[184:187], v[224:227], v[46:49]
	v_mfma_f32_16x16x32_bf16 v[46:49], v[144:147], v[220:223], v[46:49]
	v_mfma_f32_16x16x32_bf16 v[30:33], v[144:147], v[228:231], v[30:33]
	v_mfma_f32_16x16x32_bf16 v[30:33], v[184:187], v[232:235], v[30:33]
	v_mfma_f32_16x16x32_bf16 v[14:17], v[184:187], v[240:243], v[14:17]
	v_mfma_f32_16x16x32_bf16 v[14:17], v[144:147], v[236:239], v[14:17]
	v_mfma_f32_16x16x32_bf16 v[10:13], v[188:191], v[236:239], v[10:13]
	v_mfma_f32_16x16x32_bf16 v[10:13], v[192:195], v[240:243], v[10:13]
	v_mfma_f32_16x16x32_bf16 v[26:29], v[192:195], v[232:235], v[26:29]
	v_mfma_f32_16x16x32_bf16 v[26:29], v[188:191], v[228:231], v[26:29]
	v_mfma_f32_16x16x32_bf16 v[42:45], v[188:191], v[220:223], v[42:45]
	v_mfma_f32_16x16x32_bf16 v[42:45], v[192:195], v[224:227], v[42:45]
	v_mfma_f32_16x16x32_bf16 v[58:61], v[192:195], v[216:219], v[58:61]
	v_mfma_f32_16x16x32_bf16 v[58:61], v[188:191], v[212:215], v[58:61]
	v_mfma_f32_16x16x32_bf16 v[54:57], v[196:199], v[212:215], v[54:57]
	v_mfma_f32_16x16x32_bf16 v[54:57], v[200:203], v[216:219], v[54:57]
	v_mfma_f32_16x16x32_bf16 v[38:41], v[200:203], v[224:227], v[38:41]
	v_mfma_f32_16x16x32_bf16 v[38:41], v[196:199], v[220:223], v[38:41]
	v_mfma_f32_16x16x32_bf16 v[22:25], v[196:199], v[228:231], v[22:25]
	v_mfma_f32_16x16x32_bf16 v[22:25], v[200:203], v[232:235], v[22:25]
	v_mfma_f32_16x16x32_bf16 v[6:9], v[200:203], v[240:243], v[6:9]
	v_mfma_f32_16x16x32_bf16 v[6:9], v[196:199], v[236:239], v[6:9]
	v_mfma_f32_16x16x32_bf16 v[2:5], v[204:207], v[236:239], v[2:5]
	v_mfma_f32_16x16x32_bf16 v[2:5], v[208:211], v[240:243], v[2:5]
	v_mfma_f32_16x16x32_bf16 v[18:21], v[208:211], v[232:235], v[18:21]
	v_mfma_f32_16x16x32_bf16 v[18:21], v[204:207], v[228:231], v[18:21]
	s_barrier
	s_setprio 2
	v_mfma_f32_16x16x32_bf16 v[34:37], v[204:207], v[220:223], v[34:37]
	v_mfma_f32_16x16x32_bf16 v[34:37], v[208:211], v[224:227], v[34:37]
	v_mfma_f32_16x16x32_bf16 v[50:53], v[208:211], v[216:219], v[50:53]
	v_mfma_f32_16x16x32_bf16 v[50:53], v[204:207], v[212:215], v[50:53]
	s_setprio 0
	s_add_i32 s14, 0, 0x18000
	v_add_u32_e32 v133, s14, v148
	s_add_i32 s15, 0, 0x1c000
	ds_read_b128 v[144:147], v133
	ds_read_b128 v[184:187], v133 offset:1024
	ds_read_b128 v[188:191], v133 offset:2048
	ds_read_b128 v[192:195], v133 offset:3072
	v_add_u32_e32 v133, s15, v148
	ds_read_b128 v[196:199], v133
	ds_read_b128 v[200:203], v133 offset:1024
	ds_read_b128 v[204:207], v133 offset:2048
	ds_read_b128 v[208:211], v133 offset:3072
	s_mov_b32 m0, s57
	v_lshl_add_u64 v[246:247], v[244:245], 0, s[24:25]
	ds_read_b128 v[212:215], v168 offset:32768
	ds_read_b128 v[216:219], v168 offset:33792
	ds_read_b128 v[220:223], v168 offset:34816
	ds_read_b128 v[224:227], v168 offset:35840
	ds_read_b128 v[228:231], v168 offset:36864
	ds_read_b128 v[232:235], v168 offset:37888
	ds_read_b128 v[236:239], v168 offset:38912
	ds_read_b128 v[240:243], v168 offset:39936
	global_load_lds_dwordx4 v[246:247], off sc1
	v_lshl_add_u64 v[246:247], v[244:245], 0, s[26:27]
	s_mov_b32 m0, s58
	s_nop 0
	global_load_lds_dwordx4 v[246:247], off sc1
	s_waitcnt vmcnt(8)
	s_waitcnt lgkmcnt(0)
	s_barrier
	s_setprio 1
	s_waitcnt lgkmcnt(0)
	v_mfma_f32_16x16x32_bf16 v[126:129], v[144:147], v[212:215], v[126:129]
	v_mfma_f32_16x16x32_bf16 v[126:129], v[184:187], v[216:219], v[126:129]
	v_mfma_f32_16x16x32_bf16 v[110:113], v[184:187], v[224:227], v[110:113]
	v_mfma_f32_16x16x32_bf16 v[110:113], v[144:147], v[220:223], v[110:113]
	v_mfma_f32_16x16x32_bf16 v[94:97], v[144:147], v[228:231], v[94:97]
	v_mfma_f32_16x16x32_bf16 v[94:97], v[184:187], v[232:235], v[94:97]
	v_mfma_f32_16x16x32_bf16 v[78:81], v[184:187], v[240:243], v[78:81]
	v_mfma_f32_16x16x32_bf16 v[78:81], v[144:147], v[236:239], v[78:81]
	v_mfma_f32_16x16x32_bf16 v[74:77], v[188:191], v[236:239], v[74:77]
	v_mfma_f32_16x16x32_bf16 v[74:77], v[192:195], v[240:243], v[74:77]
	v_mfma_f32_16x16x32_bf16 v[90:93], v[192:195], v[232:235], v[90:93]
	v_mfma_f32_16x16x32_bf16 v[90:93], v[188:191], v[228:231], v[90:93]
	v_mfma_f32_16x16x32_bf16 v[106:109], v[188:191], v[220:223], v[106:109]
	v_mfma_f32_16x16x32_bf16 v[106:109], v[192:195], v[224:227], v[106:109]
	v_mfma_f32_16x16x32_bf16 v[122:125], v[192:195], v[216:219], v[122:125]
	v_mfma_f32_16x16x32_bf16 v[122:125], v[188:191], v[212:215], v[122:125]
	v_mfma_f32_16x16x32_bf16 v[118:121], v[196:199], v[212:215], v[118:121]
	v_mfma_f32_16x16x32_bf16 v[118:121], v[200:203], v[216:219], v[118:121]
	v_mfma_f32_16x16x32_bf16 v[102:105], v[200:203], v[224:227], v[102:105]
	v_mfma_f32_16x16x32_bf16 v[102:105], v[196:199], v[220:223], v[102:105]
	v_mfma_f32_16x16x32_bf16 v[86:89], v[196:199], v[228:231], v[86:89]
	v_mfma_f32_16x16x32_bf16 v[86:89], v[200:203], v[232:235], v[86:89]
	v_mfma_f32_16x16x32_bf16 v[70:73], v[200:203], v[240:243], v[70:73]
	v_mfma_f32_16x16x32_bf16 v[70:73], v[196:199], v[236:239], v[70:73]
	v_mfma_f32_16x16x32_bf16 v[66:69], v[204:207], v[236:239], v[66:69]
	v_mfma_f32_16x16x32_bf16 v[66:69], v[208:211], v[240:243], v[66:69]
	v_mfma_f32_16x16x32_bf16 v[82:85], v[208:211], v[232:235], v[82:85]
	v_mfma_f32_16x16x32_bf16 v[82:85], v[204:207], v[228:231], v[82:85]
	s_barrier
; #define PG8_STAGE(bufoff, gbase, voff) do { if constexpr (!pg8_noload<Epi>::value) { _Pragma("unroll") for (int _i = 0; _i < 2; ++_i) \
;         __builtin_amdgcn_global_load_lds((const unsigned*)((const char*)(gbase) + (size_t)_i * pstep + (voff)[0]), (PG8_LAS unsigned*)(lds + (bufoff) + ldsw + _i * 8192), 16, 0, 0); } } while (0)
; #define PG8_LDA(dst, b, h) do { _Pragma("unroll") for (int m = 0; m < 4; ++m) _Pragma("unroll") for (int k = 0; k < 2; ++k) dst[m][k] = *(const PG8_LAS bf16x8*)(lds + PG8_SA(b, h) + aoff + m * 2048 + k * 1024); } while (0)
; #define PG8_MMA(ai, bj, At, Bt) do { __builtin_amdgcn_s_setprio(1); _Pragma("unroll") for (int m = 0; m < 4; ++m) _Pragma("unroll") for (int n = 0; n < 2; ++n) _Pragma("unroll") for (int k = 0; k < 2; ++k) \
;         acc[ai][bj][m][n] = __builtin_amdgcn_mfma_f32_16x16x32_bf16(Bt[n][k], At[m][k], acc[ai][bj][m][n], 0, 0, 0); __builtin_amdgcn_s_setprio(0); } while (0)
; #define PG8_WAIT_V(n) asm volatile("s_waitcnt vmcnt(" #n ")" ::: "memory")
; #define PG8_WAIT_L(n) asm volatile("s_waitcnt lgkmcnt(" #n ")" ::: "memory")
; #define PG8_BAR __builtin_amdgcn_s_barrier()
; #define PG8_SCHED __builtin_amdgcn_sched_barrier(0)
; template <class Epi, class Sched, bool ALIGN_EPI = false, bool SP2 = false, bool ABLK = false>
; __device__ __forceinline__ void gemm_phase(PG8_LAS unsigned char* lds, const Gemm g, const Sched& S, const Epi& E) {
;     ...
;         for (int t = 0; t < nt; t += 2) {
;     ...
;             PG8_WAIT_V(8); PG8_WAIT_L(0); PG8_BAR; PG8_MMA(0, 0, At, B0); PG8_MMA(0, 1, At, B1); PG8_BAR; PG8_SCHED;
;             PG8_LDA(At, 1, 1); PG8_STAGE(PG8_SB(1, 0), b3, voffB); PG8_STAGE(PG8_SB(1, 1), b3 + hstep, voffB); PG8_STAGE(PG8_SA(1, 0), a3, voffA);
;             PG8_WAIT_V(8); PG8_WAIT_L(0); PG8_BAR; PG8_MMA(1, 0, At, B0); PG8_MMA(1, 1, At, B1); PG8_BAR; PG8_SCHED;
	s_setprio 2
	v_mfma_f32_16x16x32_bf16 v[98:101], v[204:207], v[220:223], v[98:101]
	v_mfma_f32_16x16x32_bf16 v[98:101], v[208:211], v[224:227], v[98:101]
	v_mfma_f32_16x16x32_bf16 v[114:117], v[208:211], v[216:219], v[114:117]
	v_mfma_f32_16x16x32_bf16 v[114:117], v[204:207], v[212:215], v[114:117]
	s_setprio 0
	s_add_i32 s14, s14, s3
	v_lshl_add_u64 v[246:247], v[180:181], 0, s[38:39]
	s_mov_b32 m0, s14
	ds_read_b128 v[212:215], v168 offset:49152
	ds_read_b128 v[216:219], v168 offset:50176
	ds_read_b128 v[220:223], v168 offset:51200
	ds_read_b128 v[224:227], v168 offset:52224
	ds_read_b128 v[228:231], v168 offset:53248
	ds_read_b128 v[232:235], v168 offset:54272
	ds_read_b128 v[236:239], v168 offset:55296
	ds_read_b128 v[240:243], v168 offset:56320
	global_load_lds_dwordx4 v[246:247], off sc1
	v_lshl_add_u64 v[246:247], v[180:181], 0, s[40:41]
	s_add_i32 m0, s14, 0x2000
	s_add_i32 s14, s15, s3
	global_load_lds_dwordx4 v[246:247], off sc1
	v_lshl_add_u64 v[246:247], v[180:181], 0, s[42:43]
	s_mov_b32 m0, s14
	v_lshl_add_u64 v[180:181], v[180:181], 0, s[44:45]
	global_load_lds_dwordx4 v[246:247], off sc1
	s_add_i32 m0, s14, 0x2000
	s_nop 0
	global_load_lds_dwordx4 v[180:181], off sc1
	v_lshl_add_u64 v[180:181], v[244:245], 0, s[38:39]
	s_mov_b32 m0, s61
	s_nop 0
	global_load_lds_dwordx4 v[180:181], off sc1
	v_lshl_add_u64 v[180:181], v[244:245], 0, s[40:41]
	s_mov_b32 m0, s63
	s_nop 0
	global_load_lds_dwordx4 v[180:181], off sc1
	s_waitcnt vmcnt(8)
	s_waitcnt lgkmcnt(0)
	s_barrier
	s_setprio 1
	s_waitcnt lgkmcnt(0)
	v_mfma_f32_16x16x32_bf16 v[62:65], v[144:147], v[212:215], v[62:65]
	v_mfma_f32_16x16x32_bf16 v[62:65], v[184:187], v[216:219], v[62:65]
	v_mfma_f32_16x16x32_bf16 v[46:49], v[184:187], v[224:227], v[46:49]
	v_mfma_f32_16x16x32_bf16 v[46:49], v[144:147], v[220:223], v[46:49]
	v_mfma_f32_16x16x32_bf16 v[30:33], v[144:147], v[228:231], v[30:33]
	v_mfma_f32_16x16x32_bf16 v[30:33], v[184:187], v[232:235], v[30:33]
	v_mfma_f32_16x16x32_bf16 v[14:17], v[184:187], v[240:243], v[14:17]
	v_mfma_f32_16x16x32_bf16 v[14:17], v[144:147], v[236:239], v[14:17]
	v_mfma_f32_16x16x32_bf16 v[10:13], v[188:191], v[236:239], v[10:13]
	v_mfma_f32_16x16x32_bf16 v[10:13], v[192:195], v[240:243], v[10:13]
	v_mfma_f32_16x16x32_bf16 v[26:29], v[192:195], v[232:235], v[26:29]
	v_mfma_f32_16x16x32_bf16 v[26:29], v[188:191], v[228:231], v[26:29]
	v_mfma_f32_16x16x32_bf16 v[42:45], v[188:191], v[220:223], v[42:45]
	v_mfma_f32_16x16x32_bf16 v[42:45], v[192:195], v[224:227], v[42:45]
	v_mfma_f32_16x16x32_bf16 v[58:61], v[192:195], v[216:219], v[58:61]
	v_mfma_f32_16x16x32_bf16 v[58:61], v[188:191], v[212:215], v[58:61]
	v_mfma_f32_16x16x32_bf16 v[54:57], v[196:199], v[212:215], v[54:57]
	v_mfma_f32_16x16x32_bf16 v[54:57], v[200:203], v[216:219], v[54:57]
	v_mfma_f32_16x16x32_bf16 v[38:41], v[200:203], v[224:227], v[38:41]
	v_mfma_f32_16x16x32_bf16 v[38:41], v[196:199], v[220:223], v[38:41]
	v_mfma_f32_16x16x32_bf16 v[22:25], v[196:199], v[228:231], v[22:25]
	v_mfma_f32_16x16x32_bf16 v[22:25], v[200:203], v[232:235], v[22:25]
	v_mfma_f32_16x16x32_bf16 v[6:9], v[200:203], v[240:243], v[6:9]
	v_mfma_f32_16x16x32_bf16 v[6:9], v[196:199], v[236:239], v[6:9]
	v_mfma_f32_16x16x32_bf16 v[2:5], v[204:207], v[236:239], v[2:5]
	v_mfma_f32_16x16x32_bf16 v[2:5], v[208:211], v[240:243], v[2:5]
	v_mfma_f32_16x16x32_bf16 v[18:21], v[208:211], v[232:235], v[18:21]
	v_mfma_f32_16x16x32_bf16 v[18:21], v[204:207], v[228:231], v[18:21]
	s_barrier
	s_setprio 2
	v_mfma_f32_16x16x32_bf16 v[34:37], v[204:207], v[220:223], v[34:37]
	v_mfma_f32_16x16x32_bf16 v[34:37], v[208:211], v[224:227], v[34:37]
	v_mfma_f32_16x16x32_bf16 v[50:53], v[208:211], v[216:219], v[50:53]
	v_mfma_f32_16x16x32_bf16 v[50:53], v[204:207], v[212:215], v[50:53]
	s_setprio 0
	s_cmp_gt_u32 s59, 29
	s_mov_b32 s59, s30
	s_cbranch_scc1 .LBB0_2131

; #define PG8_STAGE(bufoff, gbase, voff) do { if constexpr (!pg8_noload<Epi>::value) { _Pragma("unroll") for (int _i = 0; _i < 2; ++_i) \
;         __builtin_amdgcn_global_load_lds((const unsigned*)((const char*)(gbase) + (size_t)_i * pstep + (voff)[0]), (PG8_LAS unsigned*)(lds + (bufoff) + ldsw + _i * 8192), 16, 0, 0); } } while (0)
; #define PG8_WAIT_V(n) asm volatile("s_waitcnt vmcnt(" #n ")" ::: "memory")
; #define PG8_BAR __builtin_amdgcn_s_barrier()
; template <class Epi, class Sched, bool ALIGN_EPI = false, bool SP2 = false, bool ABLK = false>
; __device__ __forceinline__ void gemm_phase(PG8_LAS unsigned char* lds, const Gemm g, const Sched& S, const Epi& E) {
;     const int tid = threadIdx.x, wid = __builtin_amdgcn_readfirstlane(tid >> 6), lane = tid & 63, wr = wid >> 2, wc = wid & 3, fr = lane & 15, fq = lane >> 4;
;     const int K = g.K;
;     unsigned voffA[2], voffB[2];
; #pragma unroll
;     for (int i = 0; i < 2; ++i) { int R, C; stage_rc(tid * 16 + i * 8192, R, C); const int Rb = Epi::PERM ? ((R & ~31) + perm32(R & 31)) : R;
;         voffA[i] = (unsigned)(R * K + C) * 2u; (void)Rb;
;         if constexpr (ABLK) { const int st = (tid >> 6) + 8 * i; voffA[i] = (unsigned)(((st >> 1) * (K / 32) + (st & 1)) * 1024 + (tid & 63) * 16); }
;         { static_assert(Epi::PERM, "blocked weight copies are written in permuted row-slot order"); const int st = (tid >> 6) + 8 * i; voffB[i] = (unsigned)(((st >> 1) * (K / 32) + (st & 1)) * 1024 + (tid & 63) * 16); } }
;     const size_t kstep = ABLK ? (size_t)(BK / 32) * 1024 : (size_t)(BK * 2);
;     constexpr int KOA = ABLK ? 32 : 2;
;     const size_t pstep = (size_t)K * 128;
;     const size_t kstepB = (size_t)(BK / 32) * 1024;
;     const size_t hstep = (size_t)HALF * K * 2;
;     const size_t tstep = 2 * hstep;
;     const unsigned ldsw = (unsigned)wid * 1024u;
;     const int aoff = lds_byte(wr * 64 + fr, fq * 8), boff = lds_byte(wc * 32 + fr, fq * 8);
;     ...
;         PG8_STAGE(PG8_SB(0, 0), cB, voffB); PG8_STAGE(PG8_SB(0, 1), cB + hstep, voffB); PG8_STAGE(PG8_SA(0, 0), cA, voffA); PG8_STAGE(PG8_SA(0, 1), cA + hstep, voffA);
;         if (wr == 1) PG8_BAR;
;         PG8_WAIT_V(2); PG8_BAR;
;         PG8_STAGE(PG8_SB(1, 0), cB + kstepB, voffB); PG8_STAGE(PG8_SA(1, 0), cA + kstep, voffA); PG8_STAGE(PG8_SB(1, 1), cB + hstep + kstepB, voffB);
;         PG8_WAIT_V(6); PG8_BAR;
.LBB0_2379:
	s_andn2_b64 vcc, exec, s[4:5]
	s_cbranch_vccnz .LBB0_2428
	s_add_u32 s33, s86, 0x38a00000
	s_addc_u32 s66, s87, 0
	s_add_u32 s67, s86, 0x7500000
	v_and_b32_e32 v6, 1, v183
	s_movk_i32 s3, 0x180
	s_addc_u32 s68, s87, 0
	v_and_or_b32 v1, v0, s3, v6
	s_ashr_i32 s3, s2, 31
	s_ashr_i32 s61, s60, 31
	s_ashr_i32 s11, s10, 31
	s_ashr_i32 s6, s8, 2
	s_lshl_b32 s69, s8, 10
	s_lshl_b64 s[4:5], s[2:3], 21
	s_lshl_b64 s[18:19], s[60:61], 5
	s_lshl_b64 s[12:13], s[10:11], 21
	s_add_u32 s3, s67, s12
	s_addc_u32 s7, s68, s13
	s_add_u32 s64, s3, s18
	v_lshlrev_b32_e32 v7, 4, v182
	s_addc_u32 s65, s7, s19
	s_add_i32 s61, s69, 0
	v_lshl_or_b32 v162, v1, 10, v7
	v_mov_b32_e32 v163, 0
	s_add_i32 m0, s61, 0x10000
	s_waitcnt lgkmcnt(0)
	v_lshl_add_u64 v[2:3], s[64:65], 0, v[162:163]
	global_load_lds_dwordx4 v162, s[64:65]
	s_mov_b64 s[12:13], 0x80000
	s_add_i32 m0, s61, 0x12000
	v_lshl_add_u64 v[4:5], v[2:3], 0, s[12:13]
	s_add_u32 s3, s33, s4
	s_mov_b64 s[14:15], 0x100000
	global_load_lds_dwordx4 v[4:5], off sc1
	s_addc_u32 s4, s66, s5
	v_lshl_add_u64 v[4:5], v[2:3], 0, s[14:15]
	s_add_i32 m0, s61, 0x14000
	s_mov_b64 s[16:17], 0x180000
	global_load_lds_dwordx4 v[4:5], off sc1
	s_add_i32 m0, s61, 0x16000
	s_add_u32 s62, s3, s18
	v_lshl_add_u64 v[4:5], v[2:3], 0, s[16:17]
	s_addc_u32 s63, s4, s19
	global_load_lds_dwordx4 v[4:5], off sc1
	v_lshl_add_u64 v[4:5], s[62:63], 0, v[162:163]
	s_mov_b32 m0, s61
	s_add_i32 s70, s61, 0x2000
	global_load_lds_dwordx4 v162, s[62:63]
	v_lshl_add_u64 v[8:9], v[4:5], 0, s[12:13]
	s_mov_b32 m0, s70
	s_add_i32 s71, s61, 0x4000
	global_load_lds_dwordx4 v[8:9], off sc1
	v_lshl_add_u64 v[8:9], v[4:5], 0, s[14:15]
	s_mov_b32 m0, s71
	s_add_i32 s72, s61, 0x6000
	global_load_lds_dwordx4 v[8:9], off sc1
	v_lshl_add_u64 v[8:9], v[4:5], 0, s[16:17]
	s_mov_b32 m0, s72
	s_cmp_eq_u32 s6, 1
	global_load_lds_dwordx4 v[8:9], off sc1
	s_cselect_b64 s[18:19], -1, 0
	s_cmp_lg_u32 s6, 1
	s_mov_b32 s21, 0
	s_cbranch_scc1 .LBB0_2382
	s_barrier
.LBB0_2382:
	s_add_u32 s22, s86, 0x40000
	s_addc_u32 s23, s87, 0
	s_add_u32 s73, s86, 0x1b400000
	s_mov_b64 s[24:25], 0x800
	s_addc_u32 s74, s87, 0
	v_lshl_add_u64 v[8:9], v[2:3], 0, s[24:25]
	s_add_i32 m0, s61, 0x18000
	s_mov_b64 s[26:27], 0x80800
	s_waitcnt vmcnt(2)
	s_barrier
	global_load_lds_dwordx4 v[8:9], off sc1
	v_lshl_add_u64 v[8:9], v[2:3], 0, s[26:27]
	s_add_i32 m0, s61, 0x1a000
	s_add_i32 s75, s61, 0x8000
	global_load_lds_dwordx4 v[8:9], off sc1
	v_lshl_add_u64 v[8:9], v[4:5], 0, s[24:25]
	s_mov_b32 m0, s75
	s_add_i32 s76, s61, 0xa000
	global_load_lds_dwordx4 v[8:9], off sc1
	v_lshl_add_u64 v[4:5], v[4:5], 0, s[26:27]
	s_mov_b32 m0, s76
	s_mov_b64 s[28:29], 0x100800
	global_load_lds_dwordx4 v[4:5], off sc1
	v_lshl_add_u64 v[4:5], v[2:3], 0, s[28:29]
	s_add_i32 m0, s61, 0x1c000
	s_mov_b64 s[30:31], 0x180800
	global_load_lds_dwordx4 v[4:5], off sc1
	v_lshl_add_u64 v[2:3], v[2:3], 0, s[30:31]
	s_add_i32 m0, s61, 0x1e000
	v_lshrrev_b32_e32 v1, 1, v0
	global_load_lds_dwordx4 v[2:3], off sc1
	v_and_b32_e32 v3, 15, v0
	v_and_b32_e32 v9, 48, v0
	v_lshlrev_b32_e32 v2, 6, v3
	v_lshlrev_b32_e32 v5, 2, v0
	v_and_b32_e32 v4, 24, v1
	v_or_b32_e32 v1, v2, v9
	s_lshl_b32 s4, s6, 13
	v_and_b32_e32 v10, 32, v5
	s_and_b32 s3, s8, 3
	v_bitop3_b32 v11, v1, s4, v10 bitop3:0xde
	v_lshlrev_b32_e32 v1, 6, v0
	s_movk_i32 s4, 0x3c0
	v_and_or_b32 v1, v1, s4, v9
	s_lshl_b32 s4, s3, 12
	s_cmp_lt_u32 s8, 4
	v_lshl_or_b32 v8, s6, 6, v3
	s_cselect_b64 s[34:35], -1, 0
	s_lshl_b32 s11, s6, 10
	s_lshl_b32 s6, s8, 6
	v_bitop3_b32 v1, s4, v1, v10 bitop3:0xf6
	v_lshlrev_b32_e32 v10, 4, v3
	v_or3_b32 v173, s6, v9, v3
	v_mov_b32_e32 v3, v163
	v_lshl_or_b32 v172, s3, 5, v4
	v_bitop3_b32 v4, v5, v9, 32 bitop3:0x6c
	v_mov_b32_e32 v5, v163
	v_lshl_add_u64 v[2:3], s[86:87], 0, v[2:3]
	s_and_b32 s77, s8, -4
	v_lshl_add_u64 v[2:3], v[2:3], 0, v[4:5]
	s_mov_b64 s[8:9], 0x16e00000
	s_lshl_b32 s20, s3, 1
	v_lshl_add_u64 v[164:165], v[2:3], 0, s[8:9]
	s_lshl_b32 s3, s3, 2
	v_lshlrev_b32_e32 v2, 10, v0
	v_lshlrev_b32_e32 v9, 4, v173
	s_add_i32 s3, s3, 0
	v_and_b32_e32 v2, 0x60000, v2
	v_lshlrev_b32_e32 v3, 10, v6
	s_waitcnt vmcnt(6)
	s_add_i32 s3, s3, s11
	v_or3_b32 v166, v2, v3, v7
	v_add_u32_e32 v2, 0, v9
	s_movk_i32 s6, 0x100
	s_add_i32 s3, s3, 0x20800
	s_add_i32 s80, 0, 0x10000
	s_add_i32 s81, 0, 0x14000
	v_add_u32_e32 v178, 0x20800, v2
	v_mbcnt_lo_u32_b32 v2, -1, 0
	v_cmp_gt_u32_e64 s[4:5], 16, v182
	v_cmp_gt_i32_e64 s[6:7], s6, v173
	s_ashr_i32 s78, s97, 31
	s_mov_b32 s92, s82
	s_ashr_i32 s79, s82, 31
	v_add_u32_e32 v174, 0xffffc000, v8
	v_mov_b32_e32 v167, v163
	v_mov_b64_e32 v[168:169], 0x1ff
	v_add_u32_e32 v175, s80, v1
	v_add_u32_e32 v176, s81, v1
	v_add_u32_e32 v177, 0, v11
	s_mov_b32 s82, 0x20000
	s_mov_b64 s[36:37], 0x90000
	s_mov_b64 s[38:39], 0x90400
	s_mov_b64 s[40:41], 0xa0000
	s_mov_b64 s[42:43], 0xa0400
	s_mov_b64 s[44:45], 0xb0000
	s_mov_b64 s[46:47], 0xb0400
	v_mbcnt_hi_u32_b32 v179, -1, v2
	v_add_u32_e32 v180, s3, v10
	s_mov_b32 s83, s21
	s_barrier
	s_branch .LBB0_2385

; #define PG8_STAGE(bufoff, gbase, voff) do { if constexpr (!pg8_noload<Epi>::value) { _Pragma("unroll") for (int _i = 0; _i < 2; ++_i) \
;         __builtin_amdgcn_global_load_lds((const unsigned*)((const char*)(gbase) + (size_t)_i * pstep + (voff)[0]), (PG8_LAS unsigned*)(lds + (bufoff) + ldsw + _i * 8192), 16, 0, 0); } } while (0)
; #define PG8_LDA(dst, b, h) do { _Pragma("unroll") for (int m = 0; m < 4; ++m) _Pragma("unroll") for (int k = 0; k < 2; ++k) dst[m][k] = *(const PG8_LAS bf16x8*)(lds + PG8_SA(b, h) + aoff + m * 2048 + k * 1024); } while (0)
; #define PG8_LDB(dst, b, h) do { _Pragma("unroll") for (int n = 0; n < 2; ++n) _Pragma("unroll") for (int k = 0; k < 2; ++k) dst[n][k] = *(const PG8_LAS bf16x8*)(lds + PG8_SB(b, h) + boff + n * 2048 + k * 1024); } while (0)
; #define PG8_MMA(ai, bj, At, Bt) do { __builtin_amdgcn_s_setprio(1); _Pragma("unroll") for (int m = 0; m < 4; ++m) _Pragma("unroll") for (int n = 0; n < 2; ++n) _Pragma("unroll") for (int k = 0; k < 2; ++k) \
;         acc[ai][bj][m][n] = __builtin_amdgcn_mfma_f32_16x16x32_bf16(Bt[n][k], At[m][k], acc[ai][bj][m][n], 0, 0, 0); __builtin_amdgcn_s_setprio(0); } while (0)
; #define PG8_BAR __builtin_amdgcn_s_barrier()
; template <class Epi, class Sched, bool ALIGN_EPI = false, bool SP2 = false, bool ABLK = false>
; __device__ __forceinline__ void gemm_phase(PG8_LAS unsigned char* lds, const Gemm g, const Sched& S, const Epi& E) {
;     ...
;         for (int t = 0; t < nt; t += 2) {
;             const bool last = (t == nt - 2);
;             const char* a1 = cA + (size_t)(t + 1) * kstep;
;             const char* a2 = last ? nA : cA + (size_t)(t + 2) * kstep; const char* b2 = last ? nB : cB + (size_t)(t + 2) * kstepB;
;             const char* a3 = a2 + kstep; const char* b3 = b2 + kstepB;
;             if (last && has_next) S.a_ready(nxt);
;             if constexpr (SP2) {
;             PG8_LDB(B0, 0, 0); PG8_LDB(B1, 0, 1); PG8_SCHED; PG8_LDA(At, 0, 0); PG8_STAGE(PG8_SA(1, 1), a1 + hstep, voffA);
;             PG8_WAIT_V(8); PG8_WAIT_L(0); PG8_BAR; PG8_MMA(0, 0, At, B0); PG8_MMA(0, 1, At, B1); PG8_BAR; PG8_SCHED;
;             PG8_LDA(At, 0, 1); PG8_STAGE(PG8_SB(0, 0), b2, voffB); PG8_STAGE(PG8_SB(0, 1), b2 + hstep, voffB); PG8_STAGE(PG8_SA(0, 0), a2, voffA);
;             PG8_WAIT_V(8); PG8_WAIT_L(0); PG8_BAR; PG8_MMA(1, 0, At, B0); PG8_MMA(1, 1, At, B1); PG8_BAR; PG8_SCHED;
.LBB0_2399:
	ds_read_b128 v[130:133], v175
	ds_read_b128 v[134:137], v175 offset:1024
	ds_read_b128 v[138:141], v175 offset:2048
	ds_read_b128 v[142:145], v175 offset:3072
	ds_read_b128 v[146:149], v176
	ds_read_b128 v[150:153], v176 offset:1024
	ds_read_b128 v[154:157], v176 offset:2048
	ds_read_b128 v[158:161], v176 offset:3072
	s_add_i32 s55, s53, 2
	s_add_u32 s64, s62, 0xfff00800
	s_addc_u32 s65, s63, -1
	s_cmp_eq_u32 s3, s53
	s_cselect_b32 s65, s57, s65
	s_cselect_b32 s64, s56, s64
	s_cselect_b32 s91, s59, s49
	s_cselect_b32 s90, s58, s11
	v_lshl_add_u64 v[170:171], s[62:63], 0, v[166:167]
	s_add_i32 m0, s61, 0xc000
	ds_read_b128 v[184:187], v177
	ds_read_b128 v[188:191], v177 offset:1024
	ds_read_b128 v[192:195], v177 offset:2048
	ds_read_b128 v[196:199], v177 offset:3072
	ds_read_b128 v[200:203], v177 offset:4096
	ds_read_b128 v[204:207], v177 offset:5120
	ds_read_b128 v[208:211], v177 offset:6144
	ds_read_b128 v[212:215], v177 offset:7168
	global_load_lds_dwordx4 v[170:171], off sc1
	v_lshl_add_u64 v[170:171], v[170:171], 0, s[12:13]
	s_add_i32 m0, s61, 0xe000
	s_nop 0
	global_load_lds_dwordx4 v[170:171], off sc1
	s_waitcnt vmcnt(8)
	s_waitcnt lgkmcnt(0)
	s_barrier
	s_setprio 1
	s_waitcnt lgkmcnt(0)
	v_mfma_f32_16x16x32_bf16 v[126:129], v[130:133], v[184:187], v[126:129]
	v_mfma_f32_16x16x32_bf16 v[126:129], v[134:137], v[188:191], v[126:129]
	v_mfma_f32_16x16x32_bf16 v[110:113], v[134:137], v[196:199], v[110:113]
	v_mfma_f32_16x16x32_bf16 v[110:113], v[130:133], v[192:195], v[110:113]
	v_mfma_f32_16x16x32_bf16 v[94:97], v[130:133], v[200:203], v[94:97]
	v_mfma_f32_16x16x32_bf16 v[94:97], v[134:137], v[204:207], v[94:97]
	v_mfma_f32_16x16x32_bf16 v[78:81], v[134:137], v[212:215], v[78:81]
	v_mfma_f32_16x16x32_bf16 v[78:81], v[130:133], v[208:211], v[78:81]
	v_mfma_f32_16x16x32_bf16 v[74:77], v[138:141], v[208:211], v[74:77]
	v_mfma_f32_16x16x32_bf16 v[74:77], v[142:145], v[212:215], v[74:77]
	v_mfma_f32_16x16x32_bf16 v[90:93], v[142:145], v[204:207], v[90:93]
	v_mfma_f32_16x16x32_bf16 v[90:93], v[138:141], v[200:203], v[90:93]
	v_mfma_f32_16x16x32_bf16 v[106:109], v[138:141], v[192:195], v[106:109]
	v_mfma_f32_16x16x32_bf16 v[106:109], v[142:145], v[196:199], v[106:109]
	v_mfma_f32_16x16x32_bf16 v[122:125], v[142:145], v[188:191], v[122:125]
	v_mfma_f32_16x16x32_bf16 v[122:125], v[138:141], v[184:187], v[122:125]
	v_mfma_f32_16x16x32_bf16 v[118:121], v[146:149], v[184:187], v[118:121]
	v_mfma_f32_16x16x32_bf16 v[118:121], v[150:153], v[188:191], v[118:121]
	v_mfma_f32_16x16x32_bf16 v[102:105], v[150:153], v[196:199], v[102:105]
	v_mfma_f32_16x16x32_bf16 v[102:105], v[146:149], v[192:195], v[102:105]
	v_mfma_f32_16x16x32_bf16 v[86:89], v[146:149], v[200:203], v[86:89]
	v_mfma_f32_16x16x32_bf16 v[86:89], v[150:153], v[204:207], v[86:89]
	v_mfma_f32_16x16x32_bf16 v[70:73], v[150:153], v[212:215], v[70:73]
	v_mfma_f32_16x16x32_bf16 v[70:73], v[146:149], v[208:211], v[70:73]
	v_mfma_f32_16x16x32_bf16 v[66:69], v[154:157], v[208:211], v[66:69]
	v_mfma_f32_16x16x32_bf16 v[66:69], v[158:161], v[212:215], v[66:69]
	v_mfma_f32_16x16x32_bf16 v[82:85], v[158:161], v[204:207], v[82:85]
	v_mfma_f32_16x16x32_bf16 v[82:85], v[154:157], v[200:203], v[82:85]
	s_barrier
	s_setprio 2
	v_mfma_f32_16x16x32_bf16 v[98:101], v[154:157], v[192:195], v[98:101]
	v_mfma_f32_16x16x32_bf16 v[98:101], v[158:161], v[196:199], v[98:101]
	v_mfma_f32_16x16x32_bf16 v[114:117], v[158:161], v[188:191], v[114:117]
	v_mfma_f32_16x16x32_bf16 v[114:117], v[154:157], v[184:187], v[114:117]
	s_setprio 0
	s_add_i32 s53, s80, s69
	v_lshl_add_u64 v[170:171], s[90:91], 0, v[162:163]
	s_mov_b32 m0, s53
	ds_read_b128 v[184:187], v177 offset:16384
	ds_read_b128 v[188:191], v177 offset:17408
	ds_read_b128 v[192:195], v177 offset:18432
	ds_read_b128 v[196:199], v177 offset:19456
	ds_read_b128 v[200:203], v177 offset:20480
	ds_read_b128 v[204:207], v177 offset:21504
	ds_read_b128 v[208:211], v177 offset:22528
	ds_read_b128 v[212:215], v177 offset:23552
	global_load_lds_dwordx4 v[170:171], off sc1
	v_lshl_add_u64 v[216:217], v[170:171], 0, s[12:13]
	s_add_i32 m0, s53, 0x2000
	s_add_i32 s53, s81, s69
	global_load_lds_dwordx4 v[216:217], off sc1
	v_lshl_add_u64 v[216:217], v[170:171], 0, s[14:15]
	s_mov_b32 m0, s53
	s_nop 0
	global_load_lds_dwordx4 v[216:217], off sc1
	v_lshl_add_u64 v[216:217], v[170:171], 0, s[16:17]
	s_add_i32 m0, s53, 0x2000
	s_nop 0
	global_load_lds_dwordx4 v[216:217], off sc1
	v_lshl_add_u64 v[216:217], s[64:65], 0, v[162:163]
	s_mov_b32 m0, s61
	v_lshl_add_u64 v[218:219], v[216:217], 0, s[12:13]
	global_load_lds_dwordx4 v[216:217], off sc1
	s_mov_b32 m0, s70
	s_nop 0
	global_load_lds_dwordx4 v[218:219], off sc1
	s_waitcnt vmcnt(8)
	s_waitcnt lgkmcnt(0)
	s_barrier
; #define PG8_STAGE(bufoff, gbase, voff) do { if constexpr (!pg8_noload<Epi>::value) { _Pragma("unroll") for (int _i = 0; _i < 2; ++_i) \
;         __builtin_amdgcn_global_load_lds((const unsigned*)((const char*)(gbase) + (size_t)_i * pstep + (voff)[0]), (PG8_LAS unsigned*)(lds + (bufoff) + ldsw + _i * 8192), 16, 0, 0); } } while (0)
; #define PG8_LDA(dst, b, h) do { _Pragma("unroll") for (int m = 0; m < 4; ++m) _Pragma("unroll") for (int k = 0; k < 2; ++k) dst[m][k] = *(const PG8_LAS bf16x8*)(lds + PG8_SA(b, h) + aoff + m * 2048 + k * 1024); } while (0)
; #define PG8_LDB(dst, b, h) do { _Pragma("unroll") for (int n = 0; n < 2; ++n) _Pragma("unroll") for (int k = 0; k < 2; ++k) dst[n][k] = *(const PG8_LAS bf16x8*)(lds + PG8_SB(b, h) + boff + n * 2048 + k * 1024); } while (0)
; #define PG8_MMA(ai, bj, At, Bt) do { __builtin_amdgcn_s_setprio(1); _Pragma("unroll") for (int m = 0; m < 4; ++m) _Pragma("unroll") for (int n = 0; n < 2; ++n) _Pragma("unroll") for (int k = 0; k < 2; ++k) \
;         acc[ai][bj][m][n] = __builtin_amdgcn_mfma_f32_16x16x32_bf16(Bt[n][k], At[m][k], acc[ai][bj][m][n], 0, 0, 0); __builtin_amdgcn_s_setprio(0); } while (0)
; #define PG8_WAIT_V(n) asm volatile("s_waitcnt vmcnt(" #n ")" ::: "memory")
; #define PG8_WAIT_L(n) asm volatile("s_waitcnt lgkmcnt(" #n ")" ::: "memory")
; #define PG8_BAR __builtin_amdgcn_s_barrier()
; #define PG8_SCHED __builtin_amdgcn_sched_barrier(0)
; template <class Epi, class Sched, bool ALIGN_EPI = false, bool SP2 = false, bool ABLK = false>
; __device__ __forceinline__ void gemm_phase(PG8_LAS unsigned char* lds, const Gemm g, const Sched& S, const Epi& E) {
;     ...
;             PG8_WAIT_V(8); PG8_WAIT_L(0); PG8_BAR; PG8_MMA(1, 0, At, B0); PG8_MMA(1, 1, At, B1); PG8_BAR; PG8_SCHED;
;             PG8_LDB(B0, 1, 0); PG8_LDB(B1, 1, 1); PG8_SCHED; PG8_LDA(At, 1, 0); PG8_STAGE(PG8_SA(0, 1), a2 + hstep, voffA);
;             PG8_WAIT_V(8); PG8_WAIT_L(0); PG8_BAR; PG8_MMA(0, 0, At, B0); PG8_MMA(0, 1, At, B1); PG8_BAR; PG8_SCHED;
	s_setprio 1
	s_waitcnt lgkmcnt(0)
	v_mfma_f32_16x16x32_bf16 v[62:65], v[130:133], v[184:187], v[62:65]
	v_mfma_f32_16x16x32_bf16 v[62:65], v[134:137], v[188:191], v[62:65]
	v_mfma_f32_16x16x32_bf16 v[46:49], v[134:137], v[196:199], v[46:49]
	v_mfma_f32_16x16x32_bf16 v[46:49], v[130:133], v[192:195], v[46:49]
	v_mfma_f32_16x16x32_bf16 v[30:33], v[130:133], v[200:203], v[30:33]
	v_mfma_f32_16x16x32_bf16 v[30:33], v[134:137], v[204:207], v[30:33]
	v_mfma_f32_16x16x32_bf16 v[14:17], v[134:137], v[212:215], v[14:17]
	v_mfma_f32_16x16x32_bf16 v[14:17], v[130:133], v[208:211], v[14:17]
	v_mfma_f32_16x16x32_bf16 v[10:13], v[138:141], v[208:211], v[10:13]
	v_mfma_f32_16x16x32_bf16 v[10:13], v[142:145], v[212:215], v[10:13]
	v_mfma_f32_16x16x32_bf16 v[26:29], v[142:145], v[204:207], v[26:29]
	v_mfma_f32_16x16x32_bf16 v[26:29], v[138:141], v[200:203], v[26:29]
	v_mfma_f32_16x16x32_bf16 v[42:45], v[138:141], v[192:195], v[42:45]
	v_mfma_f32_16x16x32_bf16 v[42:45], v[142:145], v[196:199], v[42:45]
	v_mfma_f32_16x16x32_bf16 v[58:61], v[142:145], v[188:191], v[58:61]
	v_mfma_f32_16x16x32_bf16 v[58:61], v[138:141], v[184:187], v[58:61]
	v_mfma_f32_16x16x32_bf16 v[54:57], v[146:149], v[184:187], v[54:57]
	v_mfma_f32_16x16x32_bf16 v[54:57], v[150:153], v[188:191], v[54:57]
	v_mfma_f32_16x16x32_bf16 v[38:41], v[150:153], v[196:199], v[38:41]
	v_mfma_f32_16x16x32_bf16 v[38:41], v[146:149], v[192:195], v[38:41]
	v_mfma_f32_16x16x32_bf16 v[22:25], v[146:149], v[200:203], v[22:25]
	v_mfma_f32_16x16x32_bf16 v[22:25], v[150:153], v[204:207], v[22:25]
	v_mfma_f32_16x16x32_bf16 v[6:9], v[150:153], v[212:215], v[6:9]
	v_mfma_f32_16x16x32_bf16 v[6:9], v[146:149], v[208:211], v[6:9]
	v_mfma_f32_16x16x32_bf16 v[2:5], v[154:157], v[208:211], v[2:5]
	v_mfma_f32_16x16x32_bf16 v[2:5], v[158:161], v[212:215], v[2:5]
	v_mfma_f32_16x16x32_bf16 v[18:21], v[158:161], v[204:207], v[18:21]
	v_mfma_f32_16x16x32_bf16 v[18:21], v[154:157], v[200:203], v[18:21]
	s_barrier
	s_setprio 2
	v_mfma_f32_16x16x32_bf16 v[34:37], v[154:157], v[192:195], v[34:37]
	v_mfma_f32_16x16x32_bf16 v[34:37], v[158:161], v[196:199], v[34:37]
	v_mfma_f32_16x16x32_bf16 v[50:53], v[158:161], v[188:191], v[50:53]
	v_mfma_f32_16x16x32_bf16 v[50:53], v[154:157], v[184:187], v[50:53]
	s_setprio 0
	s_add_i32 s53, 0, 0x18000
	s_add_i32 s64, 0, 0x1c000
	v_add_u32_e32 v142, s53, v1
	v_add_u32_e32 v158, s64, v1
	ds_read_b128 v[130:133], v142
	ds_read_b128 v[134:137], v142 offset:1024
	ds_read_b128 v[138:141], v142 offset:2048
	ds_read_b128 v[142:145], v142 offset:3072
	ds_read_b128 v[146:149], v158
	ds_read_b128 v[150:153], v158 offset:1024
	ds_read_b128 v[154:157], v158 offset:2048
	ds_read_b128 v[158:161], v158 offset:3072
	s_mov_b32 m0, s71
	v_lshl_add_u64 v[218:219], v[216:217], 0, s[14:15]
	ds_read_b128 v[184:187], v177 offset:32768
	ds_read_b128 v[188:191], v177 offset:33792
	ds_read_b128 v[192:195], v177 offset:34816
	ds_read_b128 v[196:199], v177 offset:35840
	ds_read_b128 v[200:203], v177 offset:36864
	ds_read_b128 v[204:207], v177 offset:37888
	ds_read_b128 v[208:211], v177 offset:38912
	ds_read_b128 v[212:215], v177 offset:39936
	global_load_lds_dwordx4 v[218:219], off sc1
	v_lshl_add_u64 v[218:219], v[216:217], 0, s[16:17]
	s_mov_b32 m0, s72
	s_nop 0
	global_load_lds_dwordx4 v[218:219], off sc1
	s_waitcnt vmcnt(8)
	s_waitcnt lgkmcnt(0)
	s_barrier
	s_setprio 1
	s_waitcnt lgkmcnt(0)
	v_mfma_f32_16x16x32_bf16 v[126:129], v[130:133], v[184:187], v[126:129]
	v_mfma_f32_16x16x32_bf16 v[126:129], v[134:137], v[188:191], v[126:129]
	v_mfma_f32_16x16x32_bf16 v[110:113], v[134:137], v[196:199], v[110:113]
	v_mfma_f32_16x16x32_bf16 v[110:113], v[130:133], v[192:195], v[110:113]
	v_mfma_f32_16x16x32_bf16 v[94:97], v[130:133], v[200:203], v[94:97]
	v_mfma_f32_16x16x32_bf16 v[94:97], v[134:137], v[204:207], v[94:97]
	v_mfma_f32_16x16x32_bf16 v[78:81], v[134:137], v[212:215], v[78:81]
	v_mfma_f32_16x16x32_bf16 v[78:81], v[130:133], v[208:211], v[78:81]
	v_mfma_f32_16x16x32_bf16 v[74:77], v[138:141], v[208:211], v[74:77]
	v_mfma_f32_16x16x32_bf16 v[74:77], v[142:145], v[212:215], v[74:77]
	v_mfma_f32_16x16x32_bf16 v[90:93], v[142:145], v[204:207], v[90:93]
	v_mfma_f32_16x16x32_bf16 v[90:93], v[138:141], v[200:203], v[90:93]
	v_mfma_f32_16x16x32_bf16 v[106:109], v[138:141], v[192:195], v[106:109]
	v_mfma_f32_16x16x32_bf16 v[106:109], v[142:145], v[196:199], v[106:109]
	v_mfma_f32_16x16x32_bf16 v[122:125], v[142:145], v[188:191], v[122:125]
	v_mfma_f32_16x16x32_bf16 v[122:125], v[138:141], v[184:187], v[122:125]
	v_mfma_f32_16x16x32_bf16 v[118:121], v[146:149], v[184:187], v[118:121]
	v_mfma_f32_16x16x32_bf16 v[118:121], v[150:153], v[188:191], v[118:121]
	v_mfma_f32_16x16x32_bf16 v[102:105], v[150:153], v[196:199], v[102:105]
	v_mfma_f32_16x16x32_bf16 v[102:105], v[146:149], v[192:195], v[102:105]
	v_mfma_f32_16x16x32_bf16 v[86:89], v[146:149], v[200:203], v[86:89]
	v_mfma_f32_16x16x32_bf16 v[86:89], v[150:153], v[204:207], v[86:89]
	v_mfma_f32_16x16x32_bf16 v[70:73], v[150:153], v[212:215], v[70:73]
	v_mfma_f32_16x16x32_bf16 v[70:73], v[146:149], v[208:211], v[70:73]
	v_mfma_f32_16x16x32_bf16 v[66:69], v[154:157], v[208:211], v[66:69]
	v_mfma_f32_16x16x32_bf16 v[66:69], v[158:161], v[212:215], v[66:69]
	v_mfma_f32_16x16x32_bf16 v[82:85], v[158:161], v[204:207], v[82:85]
	v_mfma_f32_16x16x32_bf16 v[82:85], v[154:157], v[200:203], v[82:85]
	s_barrier
; #define PG8_WAIT_V(n) asm volatile("s_waitcnt vmcnt(" #n ")" ::: "memory")
; #define PG8_WAIT_L(n) asm volatile("s_waitcnt lgkmcnt(" #n ")" ::: "memory")
;     __device__ __forceinline__ void operator()(const f32x4 (&acc)[2][2][4][2], const Unit& u, int wr, int wc, int fr, int fq) const {
;     ...
;         if (u.pm * BM < seq) {
; template <class Epi, class Sched, bool ALIGN_EPI = false, bool SP2 = false, bool ABLK = false>
; __device__ __forceinline__ void gemm_phase(PG8_LAS unsigned char* lds, const Gemm g, const Sched& S, const Epi& E) {
;     ...
;             PG8_WAIT_V(8); PG8_WAIT_L(0); PG8_BAR; PG8_MMA(0, 0, At, B0); PG8_MMA(0, 1, At, B1); PG8_BAR; PG8_SCHED;
;             PG8_LDA(At, 1, 1); PG8_STAGE(PG8_SB(1, 0), b3, voffB); PG8_STAGE(PG8_SB(1, 1), b3 + hstep, voffB); PG8_STAGE(PG8_SA(1, 0), a3, voffA);
;             PG8_WAIT_V(8); PG8_WAIT_L(0); PG8_BAR; PG8_MMA(1, 0, At, B0); PG8_MMA(1, 1, At, B1); PG8_BAR; PG8_SCHED;
;             } else {
;             PG8_LDB(B0, 0, 0); PG8_SCHED; PG8_LDA(At, 0, 0); PG8_STAGE(PG8_SA(1, 1), a1 + hstep, voffA);
;             PG8_WAIT_L(8); PG8_BAR; PG8_WAIT_L(0); PG8_MMA(0, 0, At, B0); PG8_BAR; PG8_SCHED;
;             PG8_LDB(B1, 0, 1); PG8_STAGE(PG8_SB(0, 0), b2, voffB);
;             PG8_BAR; PG8_WAIT_L(0); PG8_MMA(0, 1, At, B1); PG8_BAR;
;             PG8_LDA(At, 0, 1); PG8_STAGE(PG8_SA(0, 0), a2, voffA);
;             PG8_BAR; PG8_WAIT_L(0); PG8_MMA(1, 0, At, B0); PG8_BAR; PG8_SCHED;
;             PG8_STAGE(PG8_SB(0, 1), b2 + hstep, voffB);
;             PG8_WAIT_V(6); PG8_BAR; PG8_MMA(1, 1, At, B1); PG8_BAR;
;             PG8_LDB(B0, 1, 0); PG8_SCHED; PG8_LDA(At, 1, 0); PG8_STAGE(PG8_SA(0, 1), a2 + hstep, voffA);
;             PG8_WAIT_L(8); PG8_BAR; PG8_WAIT_L(0); PG8_MMA(0, 0, At, B0); PG8_BAR; PG8_SCHED;
;             PG8_LDB(B1, 1, 1); PG8_STAGE(PG8_SB(1, 0), b3, voffB);
;             PG8_BAR; PG8_WAIT_L(0); PG8_MMA(0, 1, At, B1); PG8_BAR;
;             PG8_LDA(At, 1, 1); PG8_STAGE(PG8_SA(1, 0), a3, voffA);
;             PG8_BAR; PG8_WAIT_L(0); PG8_MMA(1, 0, At, B0); PG8_BAR; PG8_SCHED;
;             PG8_STAGE(PG8_SB(1, 1), b3 + hstep, voffB);
;             PG8_WAIT_V(6); PG8_BAR; PG8_MMA(1, 1, At, B1); PG8_BAR;
;             }
;         }
;         if constexpr (ALIGN_EPI) { if (wr == 0) PG8_BAR; }
;         if constexpr (!Epi::AFTER_DRAIN) { E(acc, cur, wr, wc, fr, fq); S.done(cur); }
	s_setprio 2
	v_mfma_f32_16x16x32_bf16 v[98:101], v[154:157], v[192:195], v[98:101]
	v_mfma_f32_16x16x32_bf16 v[98:101], v[158:161], v[196:199], v[98:101]
	v_mfma_f32_16x16x32_bf16 v[114:117], v[158:161], v[188:191], v[114:117]
	v_mfma_f32_16x16x32_bf16 v[114:117], v[154:157], v[184:187], v[114:117]
	s_setprio 0
	s_add_i32 s53, s53, s69
	v_lshl_add_u64 v[218:219], v[170:171], 0, s[24:25]
	s_mov_b32 m0, s53
	ds_read_b128 v[184:187], v177 offset:49152
	ds_read_b128 v[188:191], v177 offset:50176
	ds_read_b128 v[192:195], v177 offset:51200
	ds_read_b128 v[196:199], v177 offset:52224
	ds_read_b128 v[200:203], v177 offset:53248
	ds_read_b128 v[204:207], v177 offset:54272
	ds_read_b128 v[208:211], v177 offset:55296
	ds_read_b128 v[212:215], v177 offset:56320
	global_load_lds_dwordx4 v[218:219], off sc1
	v_lshl_add_u64 v[218:219], v[170:171], 0, s[26:27]
	s_add_i32 m0, s53, 0x2000
	s_add_i32 s53, s64, s69
	global_load_lds_dwordx4 v[218:219], off sc1
	v_lshl_add_u64 v[218:219], v[170:171], 0, s[28:29]
	s_mov_b32 m0, s53
	v_lshl_add_u64 v[170:171], v[170:171], 0, s[30:31]
	global_load_lds_dwordx4 v[218:219], off sc1
	s_add_i32 m0, s53, 0x2000
	s_nop 0
	global_load_lds_dwordx4 v[170:171], off sc1
	v_lshl_add_u64 v[170:171], v[216:217], 0, s[24:25]
	s_mov_b32 m0, s75
	s_nop 0
	global_load_lds_dwordx4 v[170:171], off sc1
	v_lshl_add_u64 v[170:171], v[216:217], 0, s[26:27]
	s_mov_b32 m0, s76
	s_nop 0
	global_load_lds_dwordx4 v[170:171], off sc1
	s_waitcnt vmcnt(8)
	s_waitcnt lgkmcnt(0)
	s_barrier
	s_setprio 1
	s_waitcnt lgkmcnt(0)
	v_mfma_f32_16x16x32_bf16 v[62:65], v[130:133], v[184:187], v[62:65]
	v_mfma_f32_16x16x32_bf16 v[62:65], v[134:137], v[188:191], v[62:65]
	v_mfma_f32_16x16x32_bf16 v[46:49], v[134:137], v[196:199], v[46:49]
	v_mfma_f32_16x16x32_bf16 v[46:49], v[130:133], v[192:195], v[46:49]
	v_mfma_f32_16x16x32_bf16 v[30:33], v[130:133], v[200:203], v[30:33]
	v_mfma_f32_16x16x32_bf16 v[30:33], v[134:137], v[204:207], v[30:33]
	v_mfma_f32_16x16x32_bf16 v[14:17], v[134:137], v[212:215], v[14:17]
	v_mfma_f32_16x16x32_bf16 v[14:17], v[130:133], v[208:211], v[14:17]
	v_mfma_f32_16x16x32_bf16 v[10:13], v[138:141], v[208:211], v[10:13]
	v_mfma_f32_16x16x32_bf16 v[10:13], v[142:145], v[212:215], v[10:13]
	v_mfma_f32_16x16x32_bf16 v[26:29], v[142:145], v[204:207], v[26:29]
	v_mfma_f32_16x16x32_bf16 v[26:29], v[138:141], v[200:203], v[26:29]
	v_mfma_f32_16x16x32_bf16 v[42:45], v[138:141], v[192:195], v[42:45]
	v_mfma_f32_16x16x32_bf16 v[42:45], v[142:145], v[196:199], v[42:45]
	v_mfma_f32_16x16x32_bf16 v[58:61], v[142:145], v[188:191], v[58:61]
	v_mfma_f32_16x16x32_bf16 v[58:61], v[138:141], v[184:187], v[58:61]
	v_mfma_f32_16x16x32_bf16 v[54:57], v[146:149], v[184:187], v[54:57]
	v_mfma_f32_16x16x32_bf16 v[54:57], v[150:153], v[188:191], v[54:57]
	v_mfma_f32_16x16x32_bf16 v[38:41], v[150:153], v[196:199], v[38:41]
	v_mfma_f32_16x16x32_bf16 v[38:41], v[146:149], v[192:195], v[38:41]
	v_mfma_f32_16x16x32_bf16 v[22:25], v[146:149], v[200:203], v[22:25]
	v_mfma_f32_16x16x32_bf16 v[22:25], v[150:153], v[204:207], v[22:25]
	v_mfma_f32_16x16x32_bf16 v[6:9], v[150:153], v[212:215], v[6:9]
	v_mfma_f32_16x16x32_bf16 v[6:9], v[146:149], v[208:211], v[6:9]
	v_mfma_f32_16x16x32_bf16 v[2:5], v[154:157], v[208:211], v[2:5]
	v_mfma_f32_16x16x32_bf16 v[2:5], v[158:161], v[212:215], v[2:5]
	v_mfma_f32_16x16x32_bf16 v[18:21], v[158:161], v[204:207], v[18:21]
	v_mfma_f32_16x16x32_bf16 v[18:21], v[154:157], v[200:203], v[18:21]
	s_barrier
	s_setprio 2
	v_mfma_f32_16x16x32_bf16 v[34:37], v[154:157], v[192:195], v[34:37]
	v_mfma_f32_16x16x32_bf16 v[34:37], v[158:161], v[196:199], v[34:37]
	v_mfma_f32_16x16x32_bf16 v[50:53], v[158:161], v[188:191], v[50:53]
	v_mfma_f32_16x16x32_bf16 v[50:53], v[154:157], v[184:187], v[50:53]
	s_setprio 0
	s_add_u32 s62, s62, 0x1000
	s_addc_u32 s63, s63, 0
	s_add_u32 s11, s11, 0x1000
	s_addc_u32 s49, s49, 0
	s_cmp_ge_i32 s55, s89
	s_mov_b32 s53, s55
	s_cbranch_scc0 .LBB0_2399
	s_and_b64 vcc, exec, s[34:35]
	s_cbranch_vccnz .LBB0_2404
	s_lshl_b32 s11, s2, 8
	s_cmp_gt_i32 s2, 63
	s_mov_b64 s[62:63], -1
	s_cbranch_scc1 .LBB0_2405
